# GEMM main loops: LDS-DMA staging loads interleaved among the ds_read fragment reads of each load segment (reads first, DMA last, same epoch)
# speedup vs baseline: 1.0034x; 1.0034x over previous
.LBB1_93:
	s_ashr_i32 s19, s18, 31
	s_lshl_b64 s[20:21], s[18:19], 19
	s_add_u32 s20, s33, s20
	s_addc_u32 s21, s34, s21
	s_and_b64 s[22:23], s[0:1], exec
	s_cselect_b32 s5, s21, s27
	s_cselect_b32 s19, s20, s26
	s_ashr_i32 s17, s16, 31
	s_lshl_b64 s[22:23], s[16:17], 19
	s_add_u32 s22, s35, s22
	s_addc_u32 s23, s36, s23
	s_and_b64 s[30:31], s[0:1], exec
	s_cselect_b32 s17, s23, s29
	s_cselect_b32 s25, s22, s28
	s_add_u32 s26, s26, 0x40080
	s_addc_u32 s27, s27, 0
	s_add_u32 s52, s28, 0x100
	s_addc_u32 s53, s29, 0
	s_mov_b32 s54, -2
	ds_read_b128 v[148:151], v153
	ds_read_b128 v[156:159], v153 offset:1024
	ds_read_b128 v[160:163], v153 offset:2048
	ds_read_b128 v[164:167], v153 offset:3072
	ds_read_b128 v[168:171], v154
	ds_read_b128 v[172:175], v154 offset:1024
	ds_read_b128 v[176:179], v154 offset:2048
	ds_read_b128 v[180:183], v154 offset:3072
	s_add_u32 s28, s26, 0xfffc0080
	s_addc_u32 s29, s27, -1
	s_cmp_eq_u32 s54, 12
	s_cselect_b32 s31, s5, s29
	s_cselect_b32 s30, s19, s28
	s_cselect_b32 s29, s17, s53
	s_cselect_b32 s28, s25, s52
	v_lshl_add_u64 v[216:217], s[26:27], 0, v[140:141]
	s_add_i32 m0, s38, 0xc000
	s_nop 0
	global_load_lds_dwordx4 v[216:217], off
	ds_read_b128 v[184:187], v155
	ds_read_b128 v[188:191], v155 offset:1024
	ds_read_b128 v[192:195], v155 offset:2048
	ds_read_b128 v[196:199], v155 offset:3072
	ds_read_b128 v[200:203], v155 offset:4096
	ds_read_b128 v[204:207], v155 offset:5120
	ds_read_b128 v[208:211], v155 offset:6144
	ds_read_b128 v[212:215], v155 offset:7168
	v_lshl_add_u64 v[216:217], s[26:27], 0, v[142:143]
	s_add_i32 m0, s38, 0xe000
	s_nop 0
	global_load_lds_dwordx4 v[216:217], off
	s_waitcnt vmcnt(8)
	s_waitcnt lgkmcnt(0)
	s_barrier
	s_waitcnt lgkmcnt(0)
	v_mfma_f32_16x16x32_bf16 v[124:127], v[148:151], v[184:187], 0
	v_mfma_f32_16x16x32_bf16 v[120:123], v[160:163], v[184:187], 0
	v_mfma_f32_16x16x32_bf16 v[108:111], v[148:151], v[192:195], 0
	v_mfma_f32_16x16x32_bf16 v[104:107], v[160:163], v[192:195], 0
	v_mfma_f32_16x16x32_bf16 v[92:95], v[148:151], v[200:203], 0
	v_mfma_f32_16x16x32_bf16 v[88:91], v[160:163], v[200:203], 0
	v_mfma_f32_16x16x32_bf16 v[76:79], v[148:151], v[208:211], 0
	v_mfma_f32_16x16x32_bf16 v[72:75], v[160:163], v[208:211], 0
	v_mfma_f32_16x16x32_bf16 v[124:127], v[156:159], v[188:191], v[124:127]
	v_mfma_f32_16x16x32_bf16 v[120:123], v[164:167], v[188:191], v[120:123]
	v_mfma_f32_16x16x32_bf16 v[108:111], v[156:159], v[196:199], v[108:111]
	v_mfma_f32_16x16x32_bf16 v[104:107], v[164:167], v[196:199], v[104:107]
	v_mfma_f32_16x16x32_bf16 v[92:95], v[156:159], v[204:207], v[92:95]
	v_mfma_f32_16x16x32_bf16 v[88:91], v[164:167], v[204:207], v[88:91]
	v_mfma_f32_16x16x32_bf16 v[76:79], v[156:159], v[212:215], v[76:79]
	v_mfma_f32_16x16x32_bf16 v[72:75], v[164:167], v[212:215], v[72:75]
	v_mfma_f32_16x16x32_bf16 v[116:119], v[168:171], v[184:187], 0
	v_mfma_f32_16x16x32_bf16 v[112:115], v[176:179], v[184:187], 0
	v_mfma_f32_16x16x32_bf16 v[100:103], v[168:171], v[192:195], 0
	v_mfma_f32_16x16x32_bf16 v[96:99], v[176:179], v[192:195], 0
	v_mfma_f32_16x16x32_bf16 v[84:87], v[168:171], v[200:203], 0
	v_mfma_f32_16x16x32_bf16 v[80:83], v[176:179], v[200:203], 0
	v_mfma_f32_16x16x32_bf16 v[68:71], v[168:171], v[208:211], 0
	v_mfma_f32_16x16x32_bf16 v[64:67], v[176:179], v[208:211], 0
	v_mfma_f32_16x16x32_bf16 v[116:119], v[172:175], v[188:191], v[116:119]
	v_mfma_f32_16x16x32_bf16 v[112:115], v[180:183], v[188:191], v[112:115]
	v_mfma_f32_16x16x32_bf16 v[100:103], v[172:175], v[196:199], v[100:103]
	v_mfma_f32_16x16x32_bf16 v[96:99], v[180:183], v[196:199], v[96:99]
	v_mfma_f32_16x16x32_bf16 v[84:87], v[172:175], v[204:207], v[84:87]
	v_mfma_f32_16x16x32_bf16 v[80:83], v[180:183], v[204:207], v[80:83]
	v_mfma_f32_16x16x32_bf16 v[68:71], v[172:175], v[212:215], v[68:71]
	v_mfma_f32_16x16x32_bf16 v[64:67], v[180:183], v[212:215], v[64:67]
	s_barrier
	ds_read_b128 v[184:187], v155 offset:16384
	ds_read_b128 v[188:191], v155 offset:17408
	s_add_i32 s55, s48, s37
	v_lshl_add_u64 v[216:217], s[28:29], 0, v[130:131]
	s_mov_b32 m0, s55
	s_nop 0
	global_load_lds_dwordx4 v[216:217], off
	ds_read_b128 v[192:195], v155 offset:18432
	ds_read_b128 v[196:199], v155 offset:19456
	s_add_i32 m0, s55, 0x2000
	s_add_u32 s56, s28, 0x40000
	v_lshl_add_u64 v[218:219], s[28:29], 0, v[134:135]
	s_addc_u32 s57, s29, 0
	s_add_i32 s55, s49, s37
	global_load_lds_dwordx4 v[218:219], off
	ds_read_b128 v[200:203], v155 offset:20480
	v_lshl_add_u64 v[220:221], s[56:57], 0, v[130:131]
	s_mov_b32 m0, s55
	v_lshl_add_u64 v[222:223], s[30:31], 0, v[132:133]
	global_load_lds_dwordx4 v[220:221], off
	ds_read_b128 v[204:207], v155 offset:21504
	v_lshl_add_u64 v[220:221], s[56:57], 0, v[134:135]
	s_add_i32 m0, s55, 0x2000
	s_nop 0
	global_load_lds_dwordx4 v[220:221], off
	ds_read_b128 v[208:211], v155 offset:22528
	v_lshl_add_u64 v[220:221], s[30:31], 0, v[128:129]
	s_mov_b32 m0, s38
	s_nop 0
	global_load_lds_dwordx4 v[220:221], off
	ds_read_b128 v[212:215], v155 offset:23552
	s_mov_b32 m0, s39
	s_nop 0
	global_load_lds_dwordx4 v[222:223], off
	s_waitcnt vmcnt(8)
	s_waitcnt lgkmcnt(0)
	s_barrier
	s_waitcnt lgkmcnt(0)
	v_mfma_f32_16x16x32_bf16 v[60:63], v[148:151], v[184:187], 0
	v_mfma_f32_16x16x32_bf16 v[56:59], v[160:163], v[184:187], 0
	v_mfma_f32_16x16x32_bf16 v[44:47], v[148:151], v[192:195], 0
	v_mfma_f32_16x16x32_bf16 v[40:43], v[160:163], v[192:195], 0
	v_mfma_f32_16x16x32_bf16 v[28:31], v[148:151], v[200:203], 0
	v_mfma_f32_16x16x32_bf16 v[24:27], v[160:163], v[200:203], 0
	v_mfma_f32_16x16x32_bf16 v[12:15], v[148:151], v[208:211], 0
	v_mfma_f32_16x16x32_bf16 v[8:11], v[160:163], v[208:211], 0
	v_mfma_f32_16x16x32_bf16 v[60:63], v[156:159], v[188:191], v[60:63]
	v_mfma_f32_16x16x32_bf16 v[56:59], v[164:167], v[188:191], v[56:59]
	v_mfma_f32_16x16x32_bf16 v[44:47], v[156:159], v[196:199], v[44:47]
	v_mfma_f32_16x16x32_bf16 v[40:43], v[164:167], v[196:199], v[40:43]
	v_mfma_f32_16x16x32_bf16 v[28:31], v[156:159], v[204:207], v[28:31]
	v_mfma_f32_16x16x32_bf16 v[24:27], v[164:167], v[204:207], v[24:27]
	v_mfma_f32_16x16x32_bf16 v[12:15], v[156:159], v[212:215], v[12:15]
	v_mfma_f32_16x16x32_bf16 v[8:11], v[164:167], v[212:215], v[8:11]
	v_mfma_f32_16x16x32_bf16 v[52:55], v[168:171], v[184:187], 0
	v_mfma_f32_16x16x32_bf16 v[48:51], v[176:179], v[184:187], 0
	v_mfma_f32_16x16x32_bf16 v[36:39], v[168:171], v[192:195], 0
	v_mfma_f32_16x16x32_bf16 v[32:35], v[176:179], v[192:195], 0
	v_mfma_f32_16x16x32_bf16 v[20:23], v[168:171], v[200:203], 0
	v_mfma_f32_16x16x32_bf16 v[16:19], v[176:179], v[200:203], 0
	v_mfma_f32_16x16x32_bf16 v[4:7], v[168:171], v[208:211], 0
	v_mfma_f32_16x16x32_bf16 v[0:3], v[176:179], v[208:211], 0
	v_mfma_f32_16x16x32_bf16 v[52:55], v[172:175], v[188:191], v[52:55]
	v_mfma_f32_16x16x32_bf16 v[48:51], v[180:183], v[188:191], v[48:51]
	v_mfma_f32_16x16x32_bf16 v[36:39], v[172:175], v[196:199], v[36:39]
	v_mfma_f32_16x16x32_bf16 v[32:35], v[180:183], v[196:199], v[32:35]
	v_mfma_f32_16x16x32_bf16 v[20:23], v[172:175], v[204:207], v[20:23]
	v_mfma_f32_16x16x32_bf16 v[16:19], v[180:183], v[204:207], v[16:19]
	v_mfma_f32_16x16x32_bf16 v[4:7], v[172:175], v[212:215], v[4:7]
	v_mfma_f32_16x16x32_bf16 v[0:3], v[180:183], v[212:215], v[0:3]
	s_barrier
	s_add_i32 s56, 0, 0x1c000
	s_add_i32 s55, 0, 0x18000
	v_add_u32_e32 v164, s55, v152
	v_add_u32_e32 v180, s56, v152
	ds_read_b128 v[148:151], v164
	ds_read_b128 v[156:159], v164 offset:1024
	ds_read_b128 v[160:163], v164 offset:2048
	ds_read_b128 v[164:167], v164 offset:3072
	ds_read_b128 v[168:171], v180
	ds_read_b128 v[172:175], v180 offset:1024
	ds_read_b128 v[176:179], v180 offset:2048
	ds_read_b128 v[180:183], v180 offset:3072
	s_add_u32 s30, s30, 0x40000
	s_addc_u32 s31, s31, 0
	s_mov_b32 m0, s40
	v_lshl_add_u64 v[224:225], s[30:31], 0, v[128:129]
	global_load_lds_dwordx4 v[224:225], off
	ds_read_b128 v[184:187], v155 offset:32768
	ds_read_b128 v[188:191], v155 offset:33792
	ds_read_b128 v[192:195], v155 offset:34816
	ds_read_b128 v[196:199], v155 offset:35840
	ds_read_b128 v[200:203], v155 offset:36864
	ds_read_b128 v[204:207], v155 offset:37888
	ds_read_b128 v[208:211], v155 offset:38912
	ds_read_b128 v[212:215], v155 offset:39936
	v_lshl_add_u64 v[224:225], s[30:31], 0, v[132:133]
	s_mov_b32 m0, s41
	s_nop 0
	global_load_lds_dwordx4 v[224:225], off
	s_waitcnt vmcnt(8)
	s_waitcnt lgkmcnt(0)
	s_barrier
	s_waitcnt lgkmcnt(0)
	v_mfma_f32_16x16x32_bf16 v[124:127], v[148:151], v[184:187], v[124:127]
	v_mfma_f32_16x16x32_bf16 v[120:123], v[160:163], v[184:187], v[120:123]
	v_mfma_f32_16x16x32_bf16 v[108:111], v[148:151], v[192:195], v[108:111]
	v_mfma_f32_16x16x32_bf16 v[104:107], v[160:163], v[192:195], v[104:107]
	v_mfma_f32_16x16x32_bf16 v[92:95], v[148:151], v[200:203], v[92:95]
	v_mfma_f32_16x16x32_bf16 v[88:91], v[160:163], v[200:203], v[88:91]
	v_mfma_f32_16x16x32_bf16 v[76:79], v[148:151], v[208:211], v[76:79]
	v_mfma_f32_16x16x32_bf16 v[72:75], v[160:163], v[208:211], v[72:75]
	v_mfma_f32_16x16x32_bf16 v[124:127], v[156:159], v[188:191], v[124:127]
	v_mfma_f32_16x16x32_bf16 v[120:123], v[164:167], v[188:191], v[120:123]
	v_mfma_f32_16x16x32_bf16 v[108:111], v[156:159], v[196:199], v[108:111]
	v_mfma_f32_16x16x32_bf16 v[104:107], v[164:167], v[196:199], v[104:107]
	v_mfma_f32_16x16x32_bf16 v[92:95], v[156:159], v[204:207], v[92:95]
	v_mfma_f32_16x16x32_bf16 v[88:91], v[164:167], v[204:207], v[88:91]
	v_mfma_f32_16x16x32_bf16 v[76:79], v[156:159], v[212:215], v[76:79]
	v_mfma_f32_16x16x32_bf16 v[72:75], v[164:167], v[212:215], v[72:75]
	v_mfma_f32_16x16x32_bf16 v[116:119], v[168:171], v[184:187], v[116:119]
	v_mfma_f32_16x16x32_bf16 v[112:115], v[176:179], v[184:187], v[112:115]
	v_mfma_f32_16x16x32_bf16 v[100:103], v[168:171], v[192:195], v[100:103]
	v_mfma_f32_16x16x32_bf16 v[96:99], v[176:179], v[192:195], v[96:99]
	v_mfma_f32_16x16x32_bf16 v[84:87], v[168:171], v[200:203], v[84:87]
	v_mfma_f32_16x16x32_bf16 v[80:83], v[176:179], v[200:203], v[80:83]
	v_mfma_f32_16x16x32_bf16 v[68:71], v[168:171], v[208:211], v[68:71]
	v_mfma_f32_16x16x32_bf16 v[64:67], v[176:179], v[208:211], v[64:67]
	v_mfma_f32_16x16x32_bf16 v[116:119], v[172:175], v[188:191], v[116:119]
	v_mfma_f32_16x16x32_bf16 v[112:115], v[180:183], v[188:191], v[112:115]
	v_mfma_f32_16x16x32_bf16 v[100:103], v[172:175], v[196:199], v[100:103]
	v_mfma_f32_16x16x32_bf16 v[96:99], v[180:183], v[196:199], v[96:99]
	v_mfma_f32_16x16x32_bf16 v[84:87], v[172:175], v[204:207], v[84:87]
	v_mfma_f32_16x16x32_bf16 v[80:83], v[180:183], v[204:207], v[80:83]
	v_mfma_f32_16x16x32_bf16 v[68:71], v[172:175], v[212:215], v[68:71]
	v_mfma_f32_16x16x32_bf16 v[64:67], v[180:183], v[212:215], v[64:67]
	s_barrier
	ds_read_b128 v[184:187], v155 offset:49152
	ds_read_b128 v[188:191], v155 offset:50176
	s_add_i32 s30, s55, s37
	v_lshl_add_u64 v[216:217], v[216:217], 0, s[12:13]
	s_mov_b32 m0, s30
	s_nop 0
	global_load_lds_dwordx4 v[216:217], off
	ds_read_b128 v[192:195], v155 offset:51200
	ds_read_b128 v[196:199], v155 offset:52224
	s_add_i32 m0, s30, 0x2000
	s_add_u32 s28, s28, 0x40080
	v_lshl_add_u64 v[216:217], v[218:219], 0, s[12:13]
	s_addc_u32 s29, s29, 0
	s_add_i32 s30, s56, s37
	global_load_lds_dwordx4 v[216:217], off
	ds_read_b128 v[200:203], v155 offset:53248
	v_lshl_add_u64 v[216:217], s[28:29], 0, v[130:131]
	s_mov_b32 m0, s30
	s_nop 0
	global_load_lds_dwordx4 v[216:217], off
	ds_read_b128 v[204:207], v155 offset:54272
	v_lshl_add_u64 v[216:217], s[28:29], 0, v[134:135]
	s_add_i32 m0, s30, 0x2000
	s_nop 0
	global_load_lds_dwordx4 v[216:217], off
	ds_read_b128 v[208:211], v155 offset:55296
	v_lshl_add_u64 v[216:217], v[220:221], 0, s[12:13]
	s_mov_b32 m0, s43
	s_nop 0
	global_load_lds_dwordx4 v[216:217], off
	ds_read_b128 v[212:215], v155 offset:56320
	v_lshl_add_u64 v[216:217], v[222:223], 0, s[12:13]
	s_mov_b32 m0, s44
	s_nop 0
	global_load_lds_dwordx4 v[216:217], off
	s_waitcnt vmcnt(8)
	s_waitcnt lgkmcnt(0)
	s_barrier
	s_waitcnt lgkmcnt(0)
	v_mfma_f32_16x16x32_bf16 v[60:63], v[148:151], v[184:187], v[60:63]
	v_mfma_f32_16x16x32_bf16 v[56:59], v[160:163], v[184:187], v[56:59]
	v_mfma_f32_16x16x32_bf16 v[44:47], v[148:151], v[192:195], v[44:47]
	v_mfma_f32_16x16x32_bf16 v[40:43], v[160:163], v[192:195], v[40:43]
	v_mfma_f32_16x16x32_bf16 v[28:31], v[148:151], v[200:203], v[28:31]
	v_mfma_f32_16x16x32_bf16 v[24:27], v[160:163], v[200:203], v[24:27]
	v_mfma_f32_16x16x32_bf16 v[12:15], v[148:151], v[208:211], v[12:15]
	v_mfma_f32_16x16x32_bf16 v[8:11], v[160:163], v[208:211], v[8:11]
	v_mfma_f32_16x16x32_bf16 v[60:63], v[156:159], v[188:191], v[60:63]
	v_mfma_f32_16x16x32_bf16 v[56:59], v[164:167], v[188:191], v[56:59]
	v_mfma_f32_16x16x32_bf16 v[44:47], v[156:159], v[196:199], v[44:47]
	v_mfma_f32_16x16x32_bf16 v[40:43], v[164:167], v[196:199], v[40:43]
	v_mfma_f32_16x16x32_bf16 v[28:31], v[156:159], v[204:207], v[28:31]
	v_mfma_f32_16x16x32_bf16 v[24:27], v[164:167], v[204:207], v[24:27]
	v_mfma_f32_16x16x32_bf16 v[12:15], v[156:159], v[212:215], v[12:15]
	v_mfma_f32_16x16x32_bf16 v[8:11], v[164:167], v[212:215], v[8:11]
	v_mfma_f32_16x16x32_bf16 v[52:55], v[168:171], v[184:187], v[52:55]
	v_mfma_f32_16x16x32_bf16 v[48:51], v[176:179], v[184:187], v[48:51]
	v_mfma_f32_16x16x32_bf16 v[36:39], v[168:171], v[192:195], v[36:39]
	v_mfma_f32_16x16x32_bf16 v[32:35], v[176:179], v[192:195], v[32:35]
	v_mfma_f32_16x16x32_bf16 v[20:23], v[168:171], v[200:203], v[20:23]
	v_mfma_f32_16x16x32_bf16 v[16:19], v[176:179], v[200:203], v[16:19]
	v_mfma_f32_16x16x32_bf16 v[4:7], v[168:171], v[208:211], v[4:7]
	v_mfma_f32_16x16x32_bf16 v[0:3], v[176:179], v[208:211], v[0:3]
	v_mfma_f32_16x16x32_bf16 v[52:55], v[172:175], v[188:191], v[52:55]
	v_mfma_f32_16x16x32_bf16 v[48:51], v[180:183], v[188:191], v[48:51]
	v_mfma_f32_16x16x32_bf16 v[36:39], v[172:175], v[196:199], v[36:39]
	v_mfma_f32_16x16x32_bf16 v[32:35], v[180:183], v[196:199], v[32:35]
	v_mfma_f32_16x16x32_bf16 v[20:23], v[172:175], v[204:207], v[20:23]
	v_mfma_f32_16x16x32_bf16 v[16:19], v[180:183], v[204:207], v[16:19]
	v_mfma_f32_16x16x32_bf16 v[4:7], v[172:175], v[212:215], v[4:7]
	v_mfma_f32_16x16x32_bf16 v[0:3], v[180:183], v[212:215], v[0:3]
	s_barrier
	s_add_i32 s54, s54, 2
	s_add_u32 s26, s26, 0x100
	s_addc_u32 s27, s27, 0
	s_add_u32 s52, s52, 0x100
	s_addc_u32 s53, s53, 0
	s_cmp_gt_u32 s54, 13
.LBB1_94:
	ds_read_b128 v[148:151], v153
	ds_read_b128 v[156:159], v153 offset:1024
	ds_read_b128 v[160:163], v153 offset:2048
	ds_read_b128 v[164:167], v153 offset:3072
	ds_read_b128 v[168:171], v154
	ds_read_b128 v[172:175], v154 offset:1024
	ds_read_b128 v[176:179], v154 offset:2048
	ds_read_b128 v[180:183], v154 offset:3072
	s_add_u32 s28, s26, 0xfffc0080
	s_addc_u32 s29, s27, -1
	s_cmp_eq_u32 s54, 12
	s_cselect_b32 s31, s5, s29
	s_cselect_b32 s30, s19, s28
	s_cselect_b32 s29, s17, s53
	s_cselect_b32 s28, s25, s52
	v_lshl_add_u64 v[216:217], s[26:27], 0, v[140:141]
	s_add_i32 m0, s38, 0xc000
	s_nop 0
	global_load_lds_dwordx4 v[216:217], off
	ds_read_b128 v[184:187], v155
	ds_read_b128 v[188:191], v155 offset:1024
	ds_read_b128 v[192:195], v155 offset:2048
	ds_read_b128 v[196:199], v155 offset:3072
	ds_read_b128 v[200:203], v155 offset:4096
	ds_read_b128 v[204:207], v155 offset:5120
	ds_read_b128 v[208:211], v155 offset:6144
	ds_read_b128 v[212:215], v155 offset:7168
	v_lshl_add_u64 v[216:217], s[26:27], 0, v[142:143]
	s_add_i32 m0, s38, 0xe000
	s_nop 0
	global_load_lds_dwordx4 v[216:217], off
	s_waitcnt vmcnt(8)
	s_waitcnt lgkmcnt(0)
	s_barrier
	s_waitcnt lgkmcnt(0)
	v_mfma_f32_16x16x32_bf16 v[124:127], v[148:151], v[184:187], v[124:127]
	v_mfma_f32_16x16x32_bf16 v[120:123], v[160:163], v[184:187], v[120:123]
	v_mfma_f32_16x16x32_bf16 v[108:111], v[148:151], v[192:195], v[108:111]
	v_mfma_f32_16x16x32_bf16 v[104:107], v[160:163], v[192:195], v[104:107]
	v_mfma_f32_16x16x32_bf16 v[92:95], v[148:151], v[200:203], v[92:95]
	v_mfma_f32_16x16x32_bf16 v[88:91], v[160:163], v[200:203], v[88:91]
	v_mfma_f32_16x16x32_bf16 v[76:79], v[148:151], v[208:211], v[76:79]
	v_mfma_f32_16x16x32_bf16 v[72:75], v[160:163], v[208:211], v[72:75]
	v_mfma_f32_16x16x32_bf16 v[124:127], v[156:159], v[188:191], v[124:127]
	v_mfma_f32_16x16x32_bf16 v[120:123], v[164:167], v[188:191], v[120:123]
	v_mfma_f32_16x16x32_bf16 v[108:111], v[156:159], v[196:199], v[108:111]
	v_mfma_f32_16x16x32_bf16 v[104:107], v[164:167], v[196:199], v[104:107]
	v_mfma_f32_16x16x32_bf16 v[92:95], v[156:159], v[204:207], v[92:95]
	v_mfma_f32_16x16x32_bf16 v[88:91], v[164:167], v[204:207], v[88:91]
	v_mfma_f32_16x16x32_bf16 v[76:79], v[156:159], v[212:215], v[76:79]
	v_mfma_f32_16x16x32_bf16 v[72:75], v[164:167], v[212:215], v[72:75]
	v_mfma_f32_16x16x32_bf16 v[116:119], v[168:171], v[184:187], v[116:119]
	v_mfma_f32_16x16x32_bf16 v[112:115], v[176:179], v[184:187], v[112:115]
	v_mfma_f32_16x16x32_bf16 v[100:103], v[168:171], v[192:195], v[100:103]
	v_mfma_f32_16x16x32_bf16 v[96:99], v[176:179], v[192:195], v[96:99]
	v_mfma_f32_16x16x32_bf16 v[84:87], v[168:171], v[200:203], v[84:87]
	v_mfma_f32_16x16x32_bf16 v[80:83], v[176:179], v[200:203], v[80:83]
	v_mfma_f32_16x16x32_bf16 v[68:71], v[168:171], v[208:211], v[68:71]
	v_mfma_f32_16x16x32_bf16 v[64:67], v[176:179], v[208:211], v[64:67]
	v_mfma_f32_16x16x32_bf16 v[116:119], v[172:175], v[188:191], v[116:119]
	v_mfma_f32_16x16x32_bf16 v[112:115], v[180:183], v[188:191], v[112:115]
	v_mfma_f32_16x16x32_bf16 v[100:103], v[172:175], v[196:199], v[100:103]
	v_mfma_f32_16x16x32_bf16 v[96:99], v[180:183], v[196:199], v[96:99]
	v_mfma_f32_16x16x32_bf16 v[84:87], v[172:175], v[204:207], v[84:87]
	v_mfma_f32_16x16x32_bf16 v[80:83], v[180:183], v[204:207], v[80:83]
	v_mfma_f32_16x16x32_bf16 v[68:71], v[172:175], v[212:215], v[68:71]
	v_mfma_f32_16x16x32_bf16 v[64:67], v[180:183], v[212:215], v[64:67]
	s_barrier
	ds_read_b128 v[184:187], v155 offset:16384
	ds_read_b128 v[188:191], v155 offset:17408
	s_add_i32 s55, s48, s37
	v_lshl_add_u64 v[216:217], s[28:29], 0, v[130:131]
	s_mov_b32 m0, s55
	s_nop 0
	global_load_lds_dwordx4 v[216:217], off
	ds_read_b128 v[192:195], v155 offset:18432
	ds_read_b128 v[196:199], v155 offset:19456
	s_add_i32 m0, s55, 0x2000
	s_add_u32 s56, s28, 0x40000
	v_lshl_add_u64 v[218:219], s[28:29], 0, v[134:135]
	s_addc_u32 s57, s29, 0
	s_add_i32 s55, s49, s37
	global_load_lds_dwordx4 v[218:219], off
	ds_read_b128 v[200:203], v155 offset:20480
	v_lshl_add_u64 v[220:221], s[56:57], 0, v[130:131]
	s_mov_b32 m0, s55
	v_lshl_add_u64 v[222:223], s[30:31], 0, v[132:133]
	global_load_lds_dwordx4 v[220:221], off
	ds_read_b128 v[204:207], v155 offset:21504
	v_lshl_add_u64 v[220:221], s[56:57], 0, v[134:135]
	s_add_i32 m0, s55, 0x2000
	s_nop 0
	global_load_lds_dwordx4 v[220:221], off
	ds_read_b128 v[208:211], v155 offset:22528
	v_lshl_add_u64 v[220:221], s[30:31], 0, v[128:129]
	s_mov_b32 m0, s38
	s_nop 0
	global_load_lds_dwordx4 v[220:221], off
	ds_read_b128 v[212:215], v155 offset:23552
	s_mov_b32 m0, s39
	s_nop 0
	global_load_lds_dwordx4 v[222:223], off
	s_waitcnt vmcnt(8)
	s_waitcnt lgkmcnt(0)
	s_barrier
	s_waitcnt lgkmcnt(0)
	v_mfma_f32_16x16x32_bf16 v[60:63], v[148:151], v[184:187], v[60:63]
	v_mfma_f32_16x16x32_bf16 v[56:59], v[160:163], v[184:187], v[56:59]
	v_mfma_f32_16x16x32_bf16 v[44:47], v[148:151], v[192:195], v[44:47]
	v_mfma_f32_16x16x32_bf16 v[40:43], v[160:163], v[192:195], v[40:43]
	v_mfma_f32_16x16x32_bf16 v[28:31], v[148:151], v[200:203], v[28:31]
	v_mfma_f32_16x16x32_bf16 v[24:27], v[160:163], v[200:203], v[24:27]
	v_mfma_f32_16x16x32_bf16 v[12:15], v[148:151], v[208:211], v[12:15]
	v_mfma_f32_16x16x32_bf16 v[8:11], v[160:163], v[208:211], v[8:11]
	v_mfma_f32_16x16x32_bf16 v[60:63], v[156:159], v[188:191], v[60:63]
	v_mfma_f32_16x16x32_bf16 v[56:59], v[164:167], v[188:191], v[56:59]
	v_mfma_f32_16x16x32_bf16 v[44:47], v[156:159], v[196:199], v[44:47]
	v_mfma_f32_16x16x32_bf16 v[40:43], v[164:167], v[196:199], v[40:43]
	v_mfma_f32_16x16x32_bf16 v[28:31], v[156:159], v[204:207], v[28:31]
	v_mfma_f32_16x16x32_bf16 v[24:27], v[164:167], v[204:207], v[24:27]
	v_mfma_f32_16x16x32_bf16 v[12:15], v[156:159], v[212:215], v[12:15]
	v_mfma_f32_16x16x32_bf16 v[8:11], v[164:167], v[212:215], v[8:11]
	v_mfma_f32_16x16x32_bf16 v[52:55], v[168:171], v[184:187], v[52:55]
	v_mfma_f32_16x16x32_bf16 v[48:51], v[176:179], v[184:187], v[48:51]
	v_mfma_f32_16x16x32_bf16 v[36:39], v[168:171], v[192:195], v[36:39]
	v_mfma_f32_16x16x32_bf16 v[32:35], v[176:179], v[192:195], v[32:35]
	v_mfma_f32_16x16x32_bf16 v[20:23], v[168:171], v[200:203], v[20:23]
	v_mfma_f32_16x16x32_bf16 v[16:19], v[176:179], v[200:203], v[16:19]
	v_mfma_f32_16x16x32_bf16 v[4:7], v[168:171], v[208:211], v[4:7]
	v_mfma_f32_16x16x32_bf16 v[0:3], v[176:179], v[208:211], v[0:3]
	v_mfma_f32_16x16x32_bf16 v[52:55], v[172:175], v[188:191], v[52:55]
	v_mfma_f32_16x16x32_bf16 v[48:51], v[180:183], v[188:191], v[48:51]
	v_mfma_f32_16x16x32_bf16 v[36:39], v[172:175], v[196:199], v[36:39]
	v_mfma_f32_16x16x32_bf16 v[32:35], v[180:183], v[196:199], v[32:35]
	v_mfma_f32_16x16x32_bf16 v[20:23], v[172:175], v[204:207], v[20:23]
	v_mfma_f32_16x16x32_bf16 v[16:19], v[180:183], v[204:207], v[16:19]
	v_mfma_f32_16x16x32_bf16 v[4:7], v[172:175], v[212:215], v[4:7]
	v_mfma_f32_16x16x32_bf16 v[0:3], v[180:183], v[212:215], v[0:3]
	s_barrier
	s_add_i32 s56, 0, 0x1c000
	s_add_i32 s55, 0, 0x18000
	v_add_u32_e32 v164, s55, v152
	v_add_u32_e32 v180, s56, v152
	ds_read_b128 v[148:151], v164
	ds_read_b128 v[156:159], v164 offset:1024
	ds_read_b128 v[160:163], v164 offset:2048
	ds_read_b128 v[164:167], v164 offset:3072
	ds_read_b128 v[168:171], v180
	ds_read_b128 v[172:175], v180 offset:1024
	ds_read_b128 v[176:179], v180 offset:2048
	ds_read_b128 v[180:183], v180 offset:3072
	s_add_u32 s30, s30, 0x40000
	s_addc_u32 s31, s31, 0
	s_mov_b32 m0, s40
	v_lshl_add_u64 v[224:225], s[30:31], 0, v[128:129]
	global_load_lds_dwordx4 v[224:225], off
	ds_read_b128 v[184:187], v155 offset:32768
	ds_read_b128 v[188:191], v155 offset:33792
	ds_read_b128 v[192:195], v155 offset:34816
	ds_read_b128 v[196:199], v155 offset:35840
	ds_read_b128 v[200:203], v155 offset:36864
	ds_read_b128 v[204:207], v155 offset:37888
	ds_read_b128 v[208:211], v155 offset:38912
	ds_read_b128 v[212:215], v155 offset:39936
	v_lshl_add_u64 v[224:225], s[30:31], 0, v[132:133]
	s_mov_b32 m0, s41
	s_nop 0
	global_load_lds_dwordx4 v[224:225], off
	s_waitcnt vmcnt(8)
	s_waitcnt lgkmcnt(0)
	s_barrier
	s_waitcnt lgkmcnt(0)
	v_mfma_f32_16x16x32_bf16 v[124:127], v[148:151], v[184:187], v[124:127]
	v_mfma_f32_16x16x32_bf16 v[120:123], v[160:163], v[184:187], v[120:123]
	v_mfma_f32_16x16x32_bf16 v[108:111], v[148:151], v[192:195], v[108:111]
	v_mfma_f32_16x16x32_bf16 v[104:107], v[160:163], v[192:195], v[104:107]
	v_mfma_f32_16x16x32_bf16 v[92:95], v[148:151], v[200:203], v[92:95]
	v_mfma_f32_16x16x32_bf16 v[88:91], v[160:163], v[200:203], v[88:91]
	v_mfma_f32_16x16x32_bf16 v[76:79], v[148:151], v[208:211], v[76:79]
	v_mfma_f32_16x16x32_bf16 v[72:75], v[160:163], v[208:211], v[72:75]
	v_mfma_f32_16x16x32_bf16 v[124:127], v[156:159], v[188:191], v[124:127]
	v_mfma_f32_16x16x32_bf16 v[120:123], v[164:167], v[188:191], v[120:123]
	v_mfma_f32_16x16x32_bf16 v[108:111], v[156:159], v[196:199], v[108:111]
	v_mfma_f32_16x16x32_bf16 v[104:107], v[164:167], v[196:199], v[104:107]
	v_mfma_f32_16x16x32_bf16 v[92:95], v[156:159], v[204:207], v[92:95]
	v_mfma_f32_16x16x32_bf16 v[88:91], v[164:167], v[204:207], v[88:91]
	v_mfma_f32_16x16x32_bf16 v[76:79], v[156:159], v[212:215], v[76:79]
	v_mfma_f32_16x16x32_bf16 v[72:75], v[164:167], v[212:215], v[72:75]
	v_mfma_f32_16x16x32_bf16 v[116:119], v[168:171], v[184:187], v[116:119]
	v_mfma_f32_16x16x32_bf16 v[112:115], v[176:179], v[184:187], v[112:115]
	v_mfma_f32_16x16x32_bf16 v[100:103], v[168:171], v[192:195], v[100:103]
	v_mfma_f32_16x16x32_bf16 v[96:99], v[176:179], v[192:195], v[96:99]
	v_mfma_f32_16x16x32_bf16 v[84:87], v[168:171], v[200:203], v[84:87]
	v_mfma_f32_16x16x32_bf16 v[80:83], v[176:179], v[200:203], v[80:83]
	v_mfma_f32_16x16x32_bf16 v[68:71], v[168:171], v[208:211], v[68:71]
	v_mfma_f32_16x16x32_bf16 v[64:67], v[176:179], v[208:211], v[64:67]
	v_mfma_f32_16x16x32_bf16 v[116:119], v[172:175], v[188:191], v[116:119]
	v_mfma_f32_16x16x32_bf16 v[112:115], v[180:183], v[188:191], v[112:115]
	v_mfma_f32_16x16x32_bf16 v[100:103], v[172:175], v[196:199], v[100:103]
	v_mfma_f32_16x16x32_bf16 v[96:99], v[180:183], v[196:199], v[96:99]
	v_mfma_f32_16x16x32_bf16 v[84:87], v[172:175], v[204:207], v[84:87]
	v_mfma_f32_16x16x32_bf16 v[80:83], v[180:183], v[204:207], v[80:83]
	v_mfma_f32_16x16x32_bf16 v[68:71], v[172:175], v[212:215], v[68:71]
	v_mfma_f32_16x16x32_bf16 v[64:67], v[180:183], v[212:215], v[64:67]
	s_barrier
	ds_read_b128 v[184:187], v155 offset:49152
	ds_read_b128 v[188:191], v155 offset:50176
	s_add_i32 s30, s55, s37
	v_lshl_add_u64 v[216:217], v[216:217], 0, s[12:13]
	s_mov_b32 m0, s30
	s_nop 0
	global_load_lds_dwordx4 v[216:217], off
	ds_read_b128 v[192:195], v155 offset:51200
	ds_read_b128 v[196:199], v155 offset:52224
	s_add_i32 m0, s30, 0x2000
	s_add_u32 s28, s28, 0x40080
	v_lshl_add_u64 v[216:217], v[218:219], 0, s[12:13]
	s_addc_u32 s29, s29, 0
	s_add_i32 s30, s56, s37
	global_load_lds_dwordx4 v[216:217], off
	ds_read_b128 v[200:203], v155 offset:53248
	v_lshl_add_u64 v[216:217], s[28:29], 0, v[130:131]
	s_mov_b32 m0, s30
	s_nop 0
	global_load_lds_dwordx4 v[216:217], off
	ds_read_b128 v[204:207], v155 offset:54272
	v_lshl_add_u64 v[216:217], s[28:29], 0, v[134:135]
	s_add_i32 m0, s30, 0x2000
	s_nop 0
	global_load_lds_dwordx4 v[216:217], off
	ds_read_b128 v[208:211], v155 offset:55296
	v_lshl_add_u64 v[216:217], v[220:221], 0, s[12:13]
	s_mov_b32 m0, s43
	s_nop 0
	global_load_lds_dwordx4 v[216:217], off
	ds_read_b128 v[212:215], v155 offset:56320
	v_lshl_add_u64 v[216:217], v[222:223], 0, s[12:13]
	s_mov_b32 m0, s44
	s_nop 0
	global_load_lds_dwordx4 v[216:217], off
	s_waitcnt vmcnt(8)
	s_waitcnt lgkmcnt(0)
	s_barrier
	s_waitcnt lgkmcnt(0)
	v_mfma_f32_16x16x32_bf16 v[60:63], v[148:151], v[184:187], v[60:63]
	v_mfma_f32_16x16x32_bf16 v[56:59], v[160:163], v[184:187], v[56:59]
	v_mfma_f32_16x16x32_bf16 v[44:47], v[148:151], v[192:195], v[44:47]
	v_mfma_f32_16x16x32_bf16 v[40:43], v[160:163], v[192:195], v[40:43]
	v_mfma_f32_16x16x32_bf16 v[28:31], v[148:151], v[200:203], v[28:31]
	v_mfma_f32_16x16x32_bf16 v[24:27], v[160:163], v[200:203], v[24:27]
	v_mfma_f32_16x16x32_bf16 v[12:15], v[148:151], v[208:211], v[12:15]
	v_mfma_f32_16x16x32_bf16 v[8:11], v[160:163], v[208:211], v[8:11]
	v_mfma_f32_16x16x32_bf16 v[60:63], v[156:159], v[188:191], v[60:63]
	v_mfma_f32_16x16x32_bf16 v[56:59], v[164:167], v[188:191], v[56:59]
	v_mfma_f32_16x16x32_bf16 v[44:47], v[156:159], v[196:199], v[44:47]
	v_mfma_f32_16x16x32_bf16 v[40:43], v[164:167], v[196:199], v[40:43]
	v_mfma_f32_16x16x32_bf16 v[28:31], v[156:159], v[204:207], v[28:31]
	v_mfma_f32_16x16x32_bf16 v[24:27], v[164:167], v[204:207], v[24:27]
	v_mfma_f32_16x16x32_bf16 v[12:15], v[156:159], v[212:215], v[12:15]
	v_mfma_f32_16x16x32_bf16 v[8:11], v[164:167], v[212:215], v[8:11]
	v_mfma_f32_16x16x32_bf16 v[52:55], v[168:171], v[184:187], v[52:55]
	v_mfma_f32_16x16x32_bf16 v[48:51], v[176:179], v[184:187], v[48:51]
	v_mfma_f32_16x16x32_bf16 v[36:39], v[168:171], v[192:195], v[36:39]
	v_mfma_f32_16x16x32_bf16 v[32:35], v[176:179], v[192:195], v[32:35]
	v_mfma_f32_16x16x32_bf16 v[20:23], v[168:171], v[200:203], v[20:23]
	v_mfma_f32_16x16x32_bf16 v[16:19], v[176:179], v[200:203], v[16:19]
	v_mfma_f32_16x16x32_bf16 v[4:7], v[168:171], v[208:211], v[4:7]
	v_mfma_f32_16x16x32_bf16 v[0:3], v[176:179], v[208:211], v[0:3]
	v_mfma_f32_16x16x32_bf16 v[52:55], v[172:175], v[188:191], v[52:55]
	v_mfma_f32_16x16x32_bf16 v[48:51], v[180:183], v[188:191], v[48:51]
	v_mfma_f32_16x16x32_bf16 v[36:39], v[172:175], v[196:199], v[36:39]
	v_mfma_f32_16x16x32_bf16 v[32:35], v[180:183], v[196:199], v[32:35]
	v_mfma_f32_16x16x32_bf16 v[20:23], v[172:175], v[204:207], v[20:23]
	v_mfma_f32_16x16x32_bf16 v[16:19], v[180:183], v[204:207], v[16:19]
	v_mfma_f32_16x16x32_bf16 v[4:7], v[172:175], v[212:215], v[4:7]
	v_mfma_f32_16x16x32_bf16 v[0:3], v[180:183], v[212:215], v[0:3]
	s_barrier
	s_add_i32 s54, s54, 2
	s_add_u32 s26, s26, 0x100
	s_addc_u32 s27, s27, 0
	s_add_u32 s52, s52, 0x100
	s_addc_u32 s53, s53, 0
	s_cmp_gt_u32 s54, 13
	s_cbranch_scc0 .LBB1_94
	s_and_b64 vcc, exec, s[14:15]
	s_cbranch_vccz .LBB1_97
	s_barrier

.LBB3_19:
	s_ashr_i32 s17, s16, 31
	s_lshl_b64 s[18:19], s[16:17], 19
	s_add_u32 s18, s33, s18
	v_cmp_lt_i64_e64 s[4:5], s[4:5], v[142:143]
	s_addc_u32 s19, s34, s19
	s_and_b64 s[20:21], s[4:5], exec
	s_cselect_b32 s17, s19, s25
	s_cselect_b32 s53, s18, s24
	s_ashr_i32 s15, s14, 31
	s_lshl_b64 s[20:21], s[14:15], 19
	s_add_u32 s20, s6, s20
	s_addc_u32 s21, s7, s21
	s_and_b64 s[28:29], s[4:5], exec
	s_cselect_b32 s15, s21, s27
	s_cselect_b32 s54, s20, s26
	s_add_u32 s24, s24, 0x40080
	s_addc_u32 s25, s25, 0
	s_add_u32 s55, s26, 0x100
	s_addc_u32 s56, s27, 0
	s_mov_b32 s57, -2
	ds_read_b128 v[152:155], v149
	ds_read_b128 v[156:159], v149 offset:1024
	ds_read_b128 v[160:163], v149 offset:2048
	ds_read_b128 v[164:167], v149 offset:3072
	ds_read_b128 v[168:171], v150
	ds_read_b128 v[172:175], v150 offset:1024
	ds_read_b128 v[176:179], v150 offset:2048
	ds_read_b128 v[180:183], v150 offset:3072
	s_add_u32 s26, s24, 0xfffc0080
	s_addc_u32 s27, s25, -1
	s_cmp_eq_u32 s57, 12
	s_cselect_b32 s29, s17, s27
	s_cselect_b32 s28, s53, s26
	s_cselect_b32 s27, s15, s56
	s_cselect_b32 s26, s54, s55
	v_lshl_add_u64 v[146:147], s[24:25], 0, v[138:139]
	s_add_i32 m0, s23, 0xc000
	s_nop 0
	global_load_lds_dwordx4 v[146:147], off
	ds_read_b128 v[184:187], v151
	ds_read_b128 v[188:191], v151 offset:1024
	ds_read_b128 v[192:195], v151 offset:2048
	ds_read_b128 v[196:199], v151 offset:3072
	ds_read_b128 v[200:203], v151 offset:4096
	ds_read_b128 v[204:207], v151 offset:5120
	ds_read_b128 v[208:211], v151 offset:6144
	ds_read_b128 v[212:215], v151 offset:7168
	v_lshl_add_u64 v[146:147], s[24:25], 0, v[140:141]
	s_add_i32 m0, s23, 0xe000
	s_nop 0
	global_load_lds_dwordx4 v[146:147], off
	s_waitcnt vmcnt(8)
	s_waitcnt lgkmcnt(0)
	s_barrier
	s_waitcnt lgkmcnt(0)
	v_mfma_f32_16x16x32_bf16 v[124:127], v[152:155], v[184:187], 0
	v_mfma_f32_16x16x32_bf16 v[120:123], v[160:163], v[184:187], 0
	v_mfma_f32_16x16x32_bf16 v[116:119], v[152:155], v[192:195], 0
	v_mfma_f32_16x16x32_bf16 v[108:111], v[160:163], v[192:195], 0
	v_mfma_f32_16x16x32_bf16 v[100:103], v[152:155], v[200:203], 0
	v_mfma_f32_16x16x32_bf16 v[92:95], v[160:163], v[200:203], 0
	v_mfma_f32_16x16x32_bf16 v[84:87], v[152:155], v[208:211], 0
	v_mfma_f32_16x16x32_bf16 v[76:79], v[160:163], v[208:211], 0
	v_mfma_f32_16x16x32_bf16 v[124:127], v[156:159], v[188:191], v[124:127]
	v_mfma_f32_16x16x32_bf16 v[120:123], v[164:167], v[188:191], v[120:123]
	v_mfma_f32_16x16x32_bf16 v[116:119], v[156:159], v[196:199], v[116:119]
	v_mfma_f32_16x16x32_bf16 v[108:111], v[164:167], v[196:199], v[108:111]
	v_mfma_f32_16x16x32_bf16 v[100:103], v[156:159], v[204:207], v[100:103]
	v_mfma_f32_16x16x32_bf16 v[92:95], v[164:167], v[204:207], v[92:95]
	v_mfma_f32_16x16x32_bf16 v[84:87], v[156:159], v[212:215], v[84:87]
	v_mfma_f32_16x16x32_bf16 v[76:79], v[164:167], v[212:215], v[76:79]
	v_mfma_f32_16x16x32_bf16 v[112:115], v[168:171], v[184:187], 0
	v_mfma_f32_16x16x32_bf16 v[104:107], v[176:179], v[184:187], 0
	v_mfma_f32_16x16x32_bf16 v[96:99], v[168:171], v[192:195], 0
	v_mfma_f32_16x16x32_bf16 v[88:91], v[176:179], v[192:195], 0
	v_mfma_f32_16x16x32_bf16 v[80:83], v[168:171], v[200:203], 0
	v_mfma_f32_16x16x32_bf16 v[72:75], v[176:179], v[200:203], 0
	v_mfma_f32_16x16x32_bf16 v[68:71], v[168:171], v[208:211], 0
	v_mfma_f32_16x16x32_bf16 v[64:67], v[176:179], v[208:211], 0
	v_mfma_f32_16x16x32_bf16 v[112:115], v[172:175], v[188:191], v[112:115]
	v_mfma_f32_16x16x32_bf16 v[104:107], v[180:183], v[188:191], v[104:107]
	v_mfma_f32_16x16x32_bf16 v[96:99], v[172:175], v[196:199], v[96:99]
	v_mfma_f32_16x16x32_bf16 v[88:91], v[180:183], v[196:199], v[88:91]
	v_mfma_f32_16x16x32_bf16 v[80:83], v[172:175], v[204:207], v[80:83]
	v_mfma_f32_16x16x32_bf16 v[72:75], v[180:183], v[204:207], v[72:75]
	v_mfma_f32_16x16x32_bf16 v[68:71], v[172:175], v[212:215], v[68:71]
	v_mfma_f32_16x16x32_bf16 v[64:67], v[180:183], v[212:215], v[64:67]
	s_barrier
	ds_read_b128 v[184:187], v151 offset:16384
	ds_read_b128 v[188:191], v151 offset:17408
	s_add_i32 s58, s45, s31
	v_lshl_add_u64 v[146:147], s[26:27], 0, v[130:131]
	s_mov_b32 m0, s58
	s_nop 0
	global_load_lds_dwordx4 v[146:147], off
	ds_read_b128 v[192:195], v151 offset:18432
	ds_read_b128 v[196:199], v151 offset:19456
	s_add_i32 m0, s58, 0x2000
	s_add_u32 s58, s26, 0x40000
	v_lshl_add_u64 v[216:217], s[26:27], 0, v[134:135]
	s_addc_u32 s59, s27, 0
	s_add_i32 s60, s46, s31
	global_load_lds_dwordx4 v[216:217], off
	ds_read_b128 v[200:203], v151 offset:20480
	v_lshl_add_u64 v[218:219], s[58:59], 0, v[130:131]
	s_mov_b32 m0, s60
	v_lshl_add_u64 v[220:221], s[28:29], 0, v[132:133]
	global_load_lds_dwordx4 v[218:219], off
	ds_read_b128 v[204:207], v151 offset:21504
	v_lshl_add_u64 v[218:219], s[58:59], 0, v[134:135]
	s_add_i32 m0, s60, 0x2000
	s_nop 0
	global_load_lds_dwordx4 v[218:219], off
	ds_read_b128 v[208:211], v151 offset:22528
	v_lshl_add_u64 v[218:219], s[28:29], 0, v[128:129]
	s_mov_b32 m0, s23
	s_nop 0
	global_load_lds_dwordx4 v[218:219], off
	ds_read_b128 v[212:215], v151 offset:23552
	s_mov_b32 m0, s35
	s_nop 0
	global_load_lds_dwordx4 v[220:221], off
	s_waitcnt vmcnt(8)
	s_waitcnt lgkmcnt(0)
	s_barrier
	s_waitcnt lgkmcnt(0)
	v_mfma_f32_16x16x32_bf16 v[60:63], v[152:155], v[184:187], 0
	v_mfma_f32_16x16x32_bf16 v[56:59], v[160:163], v[184:187], 0
	v_mfma_f32_16x16x32_bf16 v[52:55], v[152:155], v[192:195], 0
	v_mfma_f32_16x16x32_bf16 v[44:47], v[160:163], v[192:195], 0
	v_mfma_f32_16x16x32_bf16 v[36:39], v[152:155], v[200:203], 0
	v_mfma_f32_16x16x32_bf16 v[28:31], v[160:163], v[200:203], 0
	v_mfma_f32_16x16x32_bf16 v[20:23], v[152:155], v[208:211], 0
	v_mfma_f32_16x16x32_bf16 v[12:15], v[160:163], v[208:211], 0
	v_mfma_f32_16x16x32_bf16 v[60:63], v[156:159], v[188:191], v[60:63]
	v_mfma_f32_16x16x32_bf16 v[56:59], v[164:167], v[188:191], v[56:59]
	v_mfma_f32_16x16x32_bf16 v[52:55], v[156:159], v[196:199], v[52:55]
	v_mfma_f32_16x16x32_bf16 v[44:47], v[164:167], v[196:199], v[44:47]
	v_mfma_f32_16x16x32_bf16 v[36:39], v[156:159], v[204:207], v[36:39]
	v_mfma_f32_16x16x32_bf16 v[28:31], v[164:167], v[204:207], v[28:31]
	v_mfma_f32_16x16x32_bf16 v[20:23], v[156:159], v[212:215], v[20:23]
	v_mfma_f32_16x16x32_bf16 v[12:15], v[164:167], v[212:215], v[12:15]
	v_mfma_f32_16x16x32_bf16 v[48:51], v[168:171], v[184:187], 0
	v_mfma_f32_16x16x32_bf16 v[40:43], v[176:179], v[184:187], 0
	v_mfma_f32_16x16x32_bf16 v[32:35], v[168:171], v[192:195], 0
	v_mfma_f32_16x16x32_bf16 v[24:27], v[176:179], v[192:195], 0
	v_mfma_f32_16x16x32_bf16 v[16:19], v[168:171], v[200:203], 0
	v_mfma_f32_16x16x32_bf16 v[8:11], v[176:179], v[200:203], 0
	v_mfma_f32_16x16x32_bf16 v[4:7], v[168:171], v[208:211], 0
	v_mfma_f32_16x16x32_bf16 v[0:3], v[176:179], v[208:211], 0
	v_mfma_f32_16x16x32_bf16 v[48:51], v[172:175], v[188:191], v[48:51]
	v_mfma_f32_16x16x32_bf16 v[40:43], v[180:183], v[188:191], v[40:43]
	v_mfma_f32_16x16x32_bf16 v[32:35], v[172:175], v[196:199], v[32:35]
	v_mfma_f32_16x16x32_bf16 v[24:27], v[180:183], v[196:199], v[24:27]
	v_mfma_f32_16x16x32_bf16 v[16:19], v[172:175], v[204:207], v[16:19]
	v_mfma_f32_16x16x32_bf16 v[8:11], v[180:183], v[204:207], v[8:11]
	v_mfma_f32_16x16x32_bf16 v[4:7], v[172:175], v[212:215], v[4:7]
	v_mfma_f32_16x16x32_bf16 v[0:3], v[180:183], v[212:215], v[0:3]
	s_barrier
	s_add_i32 s59, 0, 0x1c000
	s_add_i32 s58, 0, 0x18000
	v_add_u32_e32 v164, s58, v148
	v_add_u32_e32 v180, s59, v148
	ds_read_b128 v[152:155], v164
	ds_read_b128 v[156:159], v164 offset:1024
	ds_read_b128 v[160:163], v164 offset:2048
	ds_read_b128 v[164:167], v164 offset:3072
	ds_read_b128 v[168:171], v180
	ds_read_b128 v[172:175], v180 offset:1024
	ds_read_b128 v[176:179], v180 offset:2048
	ds_read_b128 v[180:183], v180 offset:3072
	s_add_u32 s28, s28, 0x40000
	s_addc_u32 s29, s29, 0
	s_mov_b32 m0, s36
	v_lshl_add_u64 v[222:223], s[28:29], 0, v[128:129]
	global_load_lds_dwordx4 v[222:223], off
	ds_read_b128 v[184:187], v151 offset:32768
	ds_read_b128 v[188:191], v151 offset:33792
	ds_read_b128 v[192:195], v151 offset:34816
	ds_read_b128 v[196:199], v151 offset:35840
	ds_read_b128 v[200:203], v151 offset:36864
	ds_read_b128 v[204:207], v151 offset:37888
	ds_read_b128 v[208:211], v151 offset:38912
	ds_read_b128 v[212:215], v151 offset:39936
	v_lshl_add_u64 v[222:223], s[28:29], 0, v[132:133]
	s_mov_b32 m0, s37
	s_nop 0
	global_load_lds_dwordx4 v[222:223], off
	s_waitcnt vmcnt(8)
	s_waitcnt lgkmcnt(0)
	s_barrier
	s_waitcnt lgkmcnt(0)
	v_mfma_f32_16x16x32_bf16 v[124:127], v[152:155], v[184:187], v[124:127]
	v_mfma_f32_16x16x32_bf16 v[120:123], v[160:163], v[184:187], v[120:123]
	v_mfma_f32_16x16x32_bf16 v[116:119], v[152:155], v[192:195], v[116:119]
	v_mfma_f32_16x16x32_bf16 v[108:111], v[160:163], v[192:195], v[108:111]
	v_mfma_f32_16x16x32_bf16 v[100:103], v[152:155], v[200:203], v[100:103]
	v_mfma_f32_16x16x32_bf16 v[92:95], v[160:163], v[200:203], v[92:95]
	v_mfma_f32_16x16x32_bf16 v[84:87], v[152:155], v[208:211], v[84:87]
	v_mfma_f32_16x16x32_bf16 v[76:79], v[160:163], v[208:211], v[76:79]
	v_mfma_f32_16x16x32_bf16 v[124:127], v[156:159], v[188:191], v[124:127]
	v_mfma_f32_16x16x32_bf16 v[120:123], v[164:167], v[188:191], v[120:123]
	v_mfma_f32_16x16x32_bf16 v[116:119], v[156:159], v[196:199], v[116:119]
	v_mfma_f32_16x16x32_bf16 v[108:111], v[164:167], v[196:199], v[108:111]
	v_mfma_f32_16x16x32_bf16 v[100:103], v[156:159], v[204:207], v[100:103]
	v_mfma_f32_16x16x32_bf16 v[92:95], v[164:167], v[204:207], v[92:95]
	v_mfma_f32_16x16x32_bf16 v[84:87], v[156:159], v[212:215], v[84:87]
	v_mfma_f32_16x16x32_bf16 v[76:79], v[164:167], v[212:215], v[76:79]
	v_mfma_f32_16x16x32_bf16 v[112:115], v[168:171], v[184:187], v[112:115]
	v_mfma_f32_16x16x32_bf16 v[104:107], v[176:179], v[184:187], v[104:107]
	v_mfma_f32_16x16x32_bf16 v[96:99], v[168:171], v[192:195], v[96:99]
	v_mfma_f32_16x16x32_bf16 v[88:91], v[176:179], v[192:195], v[88:91]
	v_mfma_f32_16x16x32_bf16 v[80:83], v[168:171], v[200:203], v[80:83]
	v_mfma_f32_16x16x32_bf16 v[72:75], v[176:179], v[200:203], v[72:75]
	v_mfma_f32_16x16x32_bf16 v[68:71], v[168:171], v[208:211], v[68:71]
	v_mfma_f32_16x16x32_bf16 v[64:67], v[176:179], v[208:211], v[64:67]
	v_mfma_f32_16x16x32_bf16 v[112:115], v[172:175], v[188:191], v[112:115]
	v_mfma_f32_16x16x32_bf16 v[104:107], v[180:183], v[188:191], v[104:107]
	v_mfma_f32_16x16x32_bf16 v[96:99], v[172:175], v[196:199], v[96:99]
	v_mfma_f32_16x16x32_bf16 v[88:91], v[180:183], v[196:199], v[88:91]
	v_mfma_f32_16x16x32_bf16 v[80:83], v[172:175], v[204:207], v[80:83]
	v_mfma_f32_16x16x32_bf16 v[72:75], v[180:183], v[204:207], v[72:75]
	v_mfma_f32_16x16x32_bf16 v[68:71], v[172:175], v[212:215], v[68:71]
	v_mfma_f32_16x16x32_bf16 v[64:67], v[180:183], v[212:215], v[64:67]
	s_barrier
	ds_read_b128 v[184:187], v151 offset:49152
	ds_read_b128 v[188:191], v151 offset:50176
	s_add_i32 s28, s58, s31
	v_lshl_add_u64 v[146:147], v[146:147], 0, s[12:13]
	s_mov_b32 m0, s28
	s_nop 0
	global_load_lds_dwordx4 v[146:147], off
	ds_read_b128 v[192:195], v151 offset:51200
	ds_read_b128 v[196:199], v151 offset:52224
	s_add_i32 m0, s28, 0x2000
	s_add_u32 s26, s26, 0x40080
	v_lshl_add_u64 v[146:147], v[216:217], 0, s[12:13]
	s_addc_u32 s27, s27, 0
	s_add_i32 s28, s59, s31
	global_load_lds_dwordx4 v[146:147], off
	ds_read_b128 v[200:203], v151 offset:53248
	v_lshl_add_u64 v[146:147], s[26:27], 0, v[130:131]
	s_mov_b32 m0, s28
	s_nop 0
	global_load_lds_dwordx4 v[146:147], off
	ds_read_b128 v[204:207], v151 offset:54272
	v_lshl_add_u64 v[146:147], s[26:27], 0, v[134:135]
	s_add_i32 m0, s28, 0x2000
	s_nop 0
	global_load_lds_dwordx4 v[146:147], off
	ds_read_b128 v[208:211], v151 offset:55296
	v_lshl_add_u64 v[146:147], v[218:219], 0, s[12:13]
	s_mov_b32 m0, s40
	s_nop 0
	global_load_lds_dwordx4 v[146:147], off
	ds_read_b128 v[212:215], v151 offset:56320
	v_lshl_add_u64 v[146:147], v[220:221], 0, s[12:13]
	s_mov_b32 m0, s41
	s_nop 0
	global_load_lds_dwordx4 v[146:147], off
	s_waitcnt vmcnt(8)
	s_waitcnt lgkmcnt(0)
	s_barrier
	s_waitcnt lgkmcnt(0)
	v_mfma_f32_16x16x32_bf16 v[60:63], v[152:155], v[184:187], v[60:63]
	v_mfma_f32_16x16x32_bf16 v[56:59], v[160:163], v[184:187], v[56:59]
	v_mfma_f32_16x16x32_bf16 v[52:55], v[152:155], v[192:195], v[52:55]
	v_mfma_f32_16x16x32_bf16 v[44:47], v[160:163], v[192:195], v[44:47]
	v_mfma_f32_16x16x32_bf16 v[36:39], v[152:155], v[200:203], v[36:39]
	v_mfma_f32_16x16x32_bf16 v[28:31], v[160:163], v[200:203], v[28:31]
	v_mfma_f32_16x16x32_bf16 v[20:23], v[152:155], v[208:211], v[20:23]
	v_mfma_f32_16x16x32_bf16 v[12:15], v[160:163], v[208:211], v[12:15]
	v_mfma_f32_16x16x32_bf16 v[60:63], v[156:159], v[188:191], v[60:63]
	v_mfma_f32_16x16x32_bf16 v[56:59], v[164:167], v[188:191], v[56:59]
	v_mfma_f32_16x16x32_bf16 v[52:55], v[156:159], v[196:199], v[52:55]
	v_mfma_f32_16x16x32_bf16 v[44:47], v[164:167], v[196:199], v[44:47]
	v_mfma_f32_16x16x32_bf16 v[36:39], v[156:159], v[204:207], v[36:39]
	v_mfma_f32_16x16x32_bf16 v[28:31], v[164:167], v[204:207], v[28:31]
	v_mfma_f32_16x16x32_bf16 v[20:23], v[156:159], v[212:215], v[20:23]
	v_mfma_f32_16x16x32_bf16 v[12:15], v[164:167], v[212:215], v[12:15]
	v_mfma_f32_16x16x32_bf16 v[48:51], v[168:171], v[184:187], v[48:51]
	v_mfma_f32_16x16x32_bf16 v[40:43], v[176:179], v[184:187], v[40:43]
	v_mfma_f32_16x16x32_bf16 v[32:35], v[168:171], v[192:195], v[32:35]
	v_mfma_f32_16x16x32_bf16 v[24:27], v[176:179], v[192:195], v[24:27]
	v_mfma_f32_16x16x32_bf16 v[16:19], v[168:171], v[200:203], v[16:19]
	v_mfma_f32_16x16x32_bf16 v[8:11], v[176:179], v[200:203], v[8:11]
	v_mfma_f32_16x16x32_bf16 v[4:7], v[168:171], v[208:211], v[4:7]
	v_mfma_f32_16x16x32_bf16 v[0:3], v[176:179], v[208:211], v[0:3]
	v_mfma_f32_16x16x32_bf16 v[48:51], v[172:175], v[188:191], v[48:51]
	v_mfma_f32_16x16x32_bf16 v[40:43], v[180:183], v[188:191], v[40:43]
	v_mfma_f32_16x16x32_bf16 v[32:35], v[172:175], v[196:199], v[32:35]
	v_mfma_f32_16x16x32_bf16 v[24:27], v[180:183], v[196:199], v[24:27]
	v_mfma_f32_16x16x32_bf16 v[16:19], v[172:175], v[204:207], v[16:19]
	v_mfma_f32_16x16x32_bf16 v[8:11], v[180:183], v[204:207], v[8:11]
	v_mfma_f32_16x16x32_bf16 v[4:7], v[172:175], v[212:215], v[4:7]
	v_mfma_f32_16x16x32_bf16 v[0:3], v[180:183], v[212:215], v[0:3]
	s_barrier
	s_add_i32 s57, s57, 2
	s_add_u32 s24, s24, 0x100
	s_addc_u32 s25, s25, 0
	s_add_u32 s55, s55, 0x100
	s_addc_u32 s56, s56, 0
	s_cmp_gt_u32 s57, 13
.LBB3_20:
	ds_read_b128 v[152:155], v149
	ds_read_b128 v[156:159], v149 offset:1024
	ds_read_b128 v[160:163], v149 offset:2048
	ds_read_b128 v[164:167], v149 offset:3072
	ds_read_b128 v[168:171], v150
	ds_read_b128 v[172:175], v150 offset:1024
	ds_read_b128 v[176:179], v150 offset:2048
	ds_read_b128 v[180:183], v150 offset:3072
	s_add_u32 s26, s24, 0xfffc0080
	s_addc_u32 s27, s25, -1
	s_cmp_eq_u32 s57, 12
	s_cselect_b32 s29, s17, s27
	s_cselect_b32 s28, s53, s26
	s_cselect_b32 s27, s15, s56
	s_cselect_b32 s26, s54, s55
	v_lshl_add_u64 v[146:147], s[24:25], 0, v[138:139]
	s_add_i32 m0, s23, 0xc000
	s_nop 0
	global_load_lds_dwordx4 v[146:147], off
	ds_read_b128 v[184:187], v151
	ds_read_b128 v[188:191], v151 offset:1024
	ds_read_b128 v[192:195], v151 offset:2048
	ds_read_b128 v[196:199], v151 offset:3072
	ds_read_b128 v[200:203], v151 offset:4096
	ds_read_b128 v[204:207], v151 offset:5120
	ds_read_b128 v[208:211], v151 offset:6144
	ds_read_b128 v[212:215], v151 offset:7168
	v_lshl_add_u64 v[146:147], s[24:25], 0, v[140:141]
	s_add_i32 m0, s23, 0xe000
	s_nop 0
	global_load_lds_dwordx4 v[146:147], off
	s_waitcnt vmcnt(8)
	s_waitcnt lgkmcnt(0)
	s_barrier
	s_waitcnt lgkmcnt(0)
	v_mfma_f32_16x16x32_bf16 v[124:127], v[152:155], v[184:187], v[124:127]
	v_mfma_f32_16x16x32_bf16 v[120:123], v[160:163], v[184:187], v[120:123]
	v_mfma_f32_16x16x32_bf16 v[116:119], v[152:155], v[192:195], v[116:119]
	v_mfma_f32_16x16x32_bf16 v[108:111], v[160:163], v[192:195], v[108:111]
	v_mfma_f32_16x16x32_bf16 v[100:103], v[152:155], v[200:203], v[100:103]
	v_mfma_f32_16x16x32_bf16 v[92:95], v[160:163], v[200:203], v[92:95]
	v_mfma_f32_16x16x32_bf16 v[84:87], v[152:155], v[208:211], v[84:87]
	v_mfma_f32_16x16x32_bf16 v[76:79], v[160:163], v[208:211], v[76:79]
	v_mfma_f32_16x16x32_bf16 v[124:127], v[156:159], v[188:191], v[124:127]
	v_mfma_f32_16x16x32_bf16 v[120:123], v[164:167], v[188:191], v[120:123]
	v_mfma_f32_16x16x32_bf16 v[116:119], v[156:159], v[196:199], v[116:119]
	v_mfma_f32_16x16x32_bf16 v[108:111], v[164:167], v[196:199], v[108:111]
	v_mfma_f32_16x16x32_bf16 v[100:103], v[156:159], v[204:207], v[100:103]
	v_mfma_f32_16x16x32_bf16 v[92:95], v[164:167], v[204:207], v[92:95]
	v_mfma_f32_16x16x32_bf16 v[84:87], v[156:159], v[212:215], v[84:87]
	v_mfma_f32_16x16x32_bf16 v[76:79], v[164:167], v[212:215], v[76:79]
	v_mfma_f32_16x16x32_bf16 v[112:115], v[168:171], v[184:187], v[112:115]
	v_mfma_f32_16x16x32_bf16 v[104:107], v[176:179], v[184:187], v[104:107]
	v_mfma_f32_16x16x32_bf16 v[96:99], v[168:171], v[192:195], v[96:99]
	v_mfma_f32_16x16x32_bf16 v[88:91], v[176:179], v[192:195], v[88:91]
	v_mfma_f32_16x16x32_bf16 v[80:83], v[168:171], v[200:203], v[80:83]
	v_mfma_f32_16x16x32_bf16 v[72:75], v[176:179], v[200:203], v[72:75]
	v_mfma_f32_16x16x32_bf16 v[68:71], v[168:171], v[208:211], v[68:71]
	v_mfma_f32_16x16x32_bf16 v[64:67], v[176:179], v[208:211], v[64:67]
	v_mfma_f32_16x16x32_bf16 v[112:115], v[172:175], v[188:191], v[112:115]
	v_mfma_f32_16x16x32_bf16 v[104:107], v[180:183], v[188:191], v[104:107]
	v_mfma_f32_16x16x32_bf16 v[96:99], v[172:175], v[196:199], v[96:99]
	v_mfma_f32_16x16x32_bf16 v[88:91], v[180:183], v[196:199], v[88:91]
	v_mfma_f32_16x16x32_bf16 v[80:83], v[172:175], v[204:207], v[80:83]
	v_mfma_f32_16x16x32_bf16 v[72:75], v[180:183], v[204:207], v[72:75]
	v_mfma_f32_16x16x32_bf16 v[68:71], v[172:175], v[212:215], v[68:71]
	v_mfma_f32_16x16x32_bf16 v[64:67], v[180:183], v[212:215], v[64:67]
	s_barrier
	ds_read_b128 v[184:187], v151 offset:16384
	ds_read_b128 v[188:191], v151 offset:17408
	s_add_i32 s58, s45, s31
	v_lshl_add_u64 v[146:147], s[26:27], 0, v[130:131]
	s_mov_b32 m0, s58
	s_nop 0
	global_load_lds_dwordx4 v[146:147], off
	ds_read_b128 v[192:195], v151 offset:18432
	ds_read_b128 v[196:199], v151 offset:19456
	s_add_i32 m0, s58, 0x2000
	s_add_u32 s58, s26, 0x40000
	v_lshl_add_u64 v[216:217], s[26:27], 0, v[134:135]
	s_addc_u32 s59, s27, 0
	s_add_i32 s60, s46, s31
	global_load_lds_dwordx4 v[216:217], off
	ds_read_b128 v[200:203], v151 offset:20480
	v_lshl_add_u64 v[218:219], s[58:59], 0, v[130:131]
	s_mov_b32 m0, s60
	v_lshl_add_u64 v[220:221], s[28:29], 0, v[132:133]
	global_load_lds_dwordx4 v[218:219], off
	ds_read_b128 v[204:207], v151 offset:21504
	v_lshl_add_u64 v[218:219], s[58:59], 0, v[134:135]
	s_add_i32 m0, s60, 0x2000
	s_nop 0
	global_load_lds_dwordx4 v[218:219], off
	ds_read_b128 v[208:211], v151 offset:22528
	v_lshl_add_u64 v[218:219], s[28:29], 0, v[128:129]
	s_mov_b32 m0, s23
	s_nop 0
	global_load_lds_dwordx4 v[218:219], off
	ds_read_b128 v[212:215], v151 offset:23552
	s_mov_b32 m0, s35
	s_nop 0
	global_load_lds_dwordx4 v[220:221], off
	s_waitcnt vmcnt(8)
	s_waitcnt lgkmcnt(0)
	s_barrier
	s_waitcnt lgkmcnt(0)
	v_mfma_f32_16x16x32_bf16 v[60:63], v[152:155], v[184:187], v[60:63]
	v_mfma_f32_16x16x32_bf16 v[56:59], v[160:163], v[184:187], v[56:59]
	v_mfma_f32_16x16x32_bf16 v[52:55], v[152:155], v[192:195], v[52:55]
	v_mfma_f32_16x16x32_bf16 v[44:47], v[160:163], v[192:195], v[44:47]
	v_mfma_f32_16x16x32_bf16 v[36:39], v[152:155], v[200:203], v[36:39]
	v_mfma_f32_16x16x32_bf16 v[28:31], v[160:163], v[200:203], v[28:31]
	v_mfma_f32_16x16x32_bf16 v[20:23], v[152:155], v[208:211], v[20:23]
	v_mfma_f32_16x16x32_bf16 v[12:15], v[160:163], v[208:211], v[12:15]
	v_mfma_f32_16x16x32_bf16 v[60:63], v[156:159], v[188:191], v[60:63]
	v_mfma_f32_16x16x32_bf16 v[56:59], v[164:167], v[188:191], v[56:59]
	v_mfma_f32_16x16x32_bf16 v[52:55], v[156:159], v[196:199], v[52:55]
	v_mfma_f32_16x16x32_bf16 v[44:47], v[164:167], v[196:199], v[44:47]
	v_mfma_f32_16x16x32_bf16 v[36:39], v[156:159], v[204:207], v[36:39]
	v_mfma_f32_16x16x32_bf16 v[28:31], v[164:167], v[204:207], v[28:31]
	v_mfma_f32_16x16x32_bf16 v[20:23], v[156:159], v[212:215], v[20:23]
	v_mfma_f32_16x16x32_bf16 v[12:15], v[164:167], v[212:215], v[12:15]
	v_mfma_f32_16x16x32_bf16 v[48:51], v[168:171], v[184:187], v[48:51]
	v_mfma_f32_16x16x32_bf16 v[40:43], v[176:179], v[184:187], v[40:43]
	v_mfma_f32_16x16x32_bf16 v[32:35], v[168:171], v[192:195], v[32:35]
	v_mfma_f32_16x16x32_bf16 v[24:27], v[176:179], v[192:195], v[24:27]
	v_mfma_f32_16x16x32_bf16 v[16:19], v[168:171], v[200:203], v[16:19]
	v_mfma_f32_16x16x32_bf16 v[8:11], v[176:179], v[200:203], v[8:11]
	v_mfma_f32_16x16x32_bf16 v[4:7], v[168:171], v[208:211], v[4:7]
	v_mfma_f32_16x16x32_bf16 v[0:3], v[176:179], v[208:211], v[0:3]
	v_mfma_f32_16x16x32_bf16 v[48:51], v[172:175], v[188:191], v[48:51]
	v_mfma_f32_16x16x32_bf16 v[40:43], v[180:183], v[188:191], v[40:43]
	v_mfma_f32_16x16x32_bf16 v[32:35], v[172:175], v[196:199], v[32:35]
	v_mfma_f32_16x16x32_bf16 v[24:27], v[180:183], v[196:199], v[24:27]
	v_mfma_f32_16x16x32_bf16 v[16:19], v[172:175], v[204:207], v[16:19]
	v_mfma_f32_16x16x32_bf16 v[8:11], v[180:183], v[204:207], v[8:11]
	v_mfma_f32_16x16x32_bf16 v[4:7], v[172:175], v[212:215], v[4:7]
	v_mfma_f32_16x16x32_bf16 v[0:3], v[180:183], v[212:215], v[0:3]
	s_barrier
	s_add_i32 s59, 0, 0x1c000
	s_add_i32 s58, 0, 0x18000
	v_add_u32_e32 v164, s58, v148
	v_add_u32_e32 v180, s59, v148
	ds_read_b128 v[152:155], v164
	ds_read_b128 v[156:159], v164 offset:1024
	ds_read_b128 v[160:163], v164 offset:2048
	ds_read_b128 v[164:167], v164 offset:3072
	ds_read_b128 v[168:171], v180
	ds_read_b128 v[172:175], v180 offset:1024
	ds_read_b128 v[176:179], v180 offset:2048
	ds_read_b128 v[180:183], v180 offset:3072
	s_add_u32 s28, s28, 0x40000
	s_addc_u32 s29, s29, 0
	s_mov_b32 m0, s36
	v_lshl_add_u64 v[222:223], s[28:29], 0, v[128:129]
	global_load_lds_dwordx4 v[222:223], off
	ds_read_b128 v[184:187], v151 offset:32768
	ds_read_b128 v[188:191], v151 offset:33792
	ds_read_b128 v[192:195], v151 offset:34816
	ds_read_b128 v[196:199], v151 offset:35840
	ds_read_b128 v[200:203], v151 offset:36864
	ds_read_b128 v[204:207], v151 offset:37888
	ds_read_b128 v[208:211], v151 offset:38912
	ds_read_b128 v[212:215], v151 offset:39936
	v_lshl_add_u64 v[222:223], s[28:29], 0, v[132:133]
	s_mov_b32 m0, s37
	s_nop 0
	global_load_lds_dwordx4 v[222:223], off
	s_waitcnt vmcnt(8)
	s_waitcnt lgkmcnt(0)
	s_barrier
	s_waitcnt lgkmcnt(0)
	v_mfma_f32_16x16x32_bf16 v[124:127], v[152:155], v[184:187], v[124:127]
	v_mfma_f32_16x16x32_bf16 v[120:123], v[160:163], v[184:187], v[120:123]
	v_mfma_f32_16x16x32_bf16 v[116:119], v[152:155], v[192:195], v[116:119]
	v_mfma_f32_16x16x32_bf16 v[108:111], v[160:163], v[192:195], v[108:111]
	v_mfma_f32_16x16x32_bf16 v[100:103], v[152:155], v[200:203], v[100:103]
	v_mfma_f32_16x16x32_bf16 v[92:95], v[160:163], v[200:203], v[92:95]
	v_mfma_f32_16x16x32_bf16 v[84:87], v[152:155], v[208:211], v[84:87]
	v_mfma_f32_16x16x32_bf16 v[76:79], v[160:163], v[208:211], v[76:79]
	v_mfma_f32_16x16x32_bf16 v[124:127], v[156:159], v[188:191], v[124:127]
	v_mfma_f32_16x16x32_bf16 v[120:123], v[164:167], v[188:191], v[120:123]
	v_mfma_f32_16x16x32_bf16 v[116:119], v[156:159], v[196:199], v[116:119]
	v_mfma_f32_16x16x32_bf16 v[108:111], v[164:167], v[196:199], v[108:111]
	v_mfma_f32_16x16x32_bf16 v[100:103], v[156:159], v[204:207], v[100:103]
	v_mfma_f32_16x16x32_bf16 v[92:95], v[164:167], v[204:207], v[92:95]
	v_mfma_f32_16x16x32_bf16 v[84:87], v[156:159], v[212:215], v[84:87]
	v_mfma_f32_16x16x32_bf16 v[76:79], v[164:167], v[212:215], v[76:79]
	v_mfma_f32_16x16x32_bf16 v[112:115], v[168:171], v[184:187], v[112:115]
	v_mfma_f32_16x16x32_bf16 v[104:107], v[176:179], v[184:187], v[104:107]
	v_mfma_f32_16x16x32_bf16 v[96:99], v[168:171], v[192:195], v[96:99]
	v_mfma_f32_16x16x32_bf16 v[88:91], v[176:179], v[192:195], v[88:91]
	v_mfma_f32_16x16x32_bf16 v[80:83], v[168:171], v[200:203], v[80:83]
	v_mfma_f32_16x16x32_bf16 v[72:75], v[176:179], v[200:203], v[72:75]
	v_mfma_f32_16x16x32_bf16 v[68:71], v[168:171], v[208:211], v[68:71]
	v_mfma_f32_16x16x32_bf16 v[64:67], v[176:179], v[208:211], v[64:67]
	v_mfma_f32_16x16x32_bf16 v[112:115], v[172:175], v[188:191], v[112:115]
	v_mfma_f32_16x16x32_bf16 v[104:107], v[180:183], v[188:191], v[104:107]
	v_mfma_f32_16x16x32_bf16 v[96:99], v[172:175], v[196:199], v[96:99]
	v_mfma_f32_16x16x32_bf16 v[88:91], v[180:183], v[196:199], v[88:91]
	v_mfma_f32_16x16x32_bf16 v[80:83], v[172:175], v[204:207], v[80:83]
	v_mfma_f32_16x16x32_bf16 v[72:75], v[180:183], v[204:207], v[72:75]
	v_mfma_f32_16x16x32_bf16 v[68:71], v[172:175], v[212:215], v[68:71]
	v_mfma_f32_16x16x32_bf16 v[64:67], v[180:183], v[212:215], v[64:67]
	s_barrier
	ds_read_b128 v[184:187], v151 offset:49152
	ds_read_b128 v[188:191], v151 offset:50176
	s_add_i32 s28, s58, s31
	v_lshl_add_u64 v[146:147], v[146:147], 0, s[12:13]
	s_mov_b32 m0, s28
	s_nop 0
	global_load_lds_dwordx4 v[146:147], off
	ds_read_b128 v[192:195], v151 offset:51200
	ds_read_b128 v[196:199], v151 offset:52224
	s_add_i32 m0, s28, 0x2000
	s_add_u32 s26, s26, 0x40080
	v_lshl_add_u64 v[146:147], v[216:217], 0, s[12:13]
	s_addc_u32 s27, s27, 0
	s_add_i32 s28, s59, s31
	global_load_lds_dwordx4 v[146:147], off
	ds_read_b128 v[200:203], v151 offset:53248
	v_lshl_add_u64 v[146:147], s[26:27], 0, v[130:131]
	s_mov_b32 m0, s28
	s_nop 0
	global_load_lds_dwordx4 v[146:147], off
	ds_read_b128 v[204:207], v151 offset:54272
	v_lshl_add_u64 v[146:147], s[26:27], 0, v[134:135]
	s_add_i32 m0, s28, 0x2000
	s_nop 0
	global_load_lds_dwordx4 v[146:147], off
	ds_read_b128 v[208:211], v151 offset:55296
	v_lshl_add_u64 v[146:147], v[218:219], 0, s[12:13]
	s_mov_b32 m0, s40
	s_nop 0
	global_load_lds_dwordx4 v[146:147], off
	ds_read_b128 v[212:215], v151 offset:56320
	v_lshl_add_u64 v[146:147], v[220:221], 0, s[12:13]
	s_mov_b32 m0, s41
	s_nop 0
	global_load_lds_dwordx4 v[146:147], off
	s_waitcnt vmcnt(8)
	s_waitcnt lgkmcnt(0)
	s_barrier
	s_waitcnt lgkmcnt(0)
	v_mfma_f32_16x16x32_bf16 v[60:63], v[152:155], v[184:187], v[60:63]
	v_mfma_f32_16x16x32_bf16 v[56:59], v[160:163], v[184:187], v[56:59]
	v_mfma_f32_16x16x32_bf16 v[52:55], v[152:155], v[192:195], v[52:55]
	v_mfma_f32_16x16x32_bf16 v[44:47], v[160:163], v[192:195], v[44:47]
	v_mfma_f32_16x16x32_bf16 v[36:39], v[152:155], v[200:203], v[36:39]
	v_mfma_f32_16x16x32_bf16 v[28:31], v[160:163], v[200:203], v[28:31]
	v_mfma_f32_16x16x32_bf16 v[20:23], v[152:155], v[208:211], v[20:23]
	v_mfma_f32_16x16x32_bf16 v[12:15], v[160:163], v[208:211], v[12:15]
	v_mfma_f32_16x16x32_bf16 v[60:63], v[156:159], v[188:191], v[60:63]
	v_mfma_f32_16x16x32_bf16 v[56:59], v[164:167], v[188:191], v[56:59]
	v_mfma_f32_16x16x32_bf16 v[52:55], v[156:159], v[196:199], v[52:55]
	v_mfma_f32_16x16x32_bf16 v[44:47], v[164:167], v[196:199], v[44:47]
	v_mfma_f32_16x16x32_bf16 v[36:39], v[156:159], v[204:207], v[36:39]
	v_mfma_f32_16x16x32_bf16 v[28:31], v[164:167], v[204:207], v[28:31]
	v_mfma_f32_16x16x32_bf16 v[20:23], v[156:159], v[212:215], v[20:23]
	v_mfma_f32_16x16x32_bf16 v[12:15], v[164:167], v[212:215], v[12:15]
	v_mfma_f32_16x16x32_bf16 v[48:51], v[168:171], v[184:187], v[48:51]
	v_mfma_f32_16x16x32_bf16 v[40:43], v[176:179], v[184:187], v[40:43]
	v_mfma_f32_16x16x32_bf16 v[32:35], v[168:171], v[192:195], v[32:35]
	v_mfma_f32_16x16x32_bf16 v[24:27], v[176:179], v[192:195], v[24:27]
	v_mfma_f32_16x16x32_bf16 v[16:19], v[168:171], v[200:203], v[16:19]
	v_mfma_f32_16x16x32_bf16 v[8:11], v[176:179], v[200:203], v[8:11]
	v_mfma_f32_16x16x32_bf16 v[4:7], v[168:171], v[208:211], v[4:7]
	v_mfma_f32_16x16x32_bf16 v[0:3], v[176:179], v[208:211], v[0:3]
	v_mfma_f32_16x16x32_bf16 v[48:51], v[172:175], v[188:191], v[48:51]
	v_mfma_f32_16x16x32_bf16 v[40:43], v[180:183], v[188:191], v[40:43]
	v_mfma_f32_16x16x32_bf16 v[32:35], v[172:175], v[196:199], v[32:35]
	v_mfma_f32_16x16x32_bf16 v[24:27], v[180:183], v[196:199], v[24:27]
	v_mfma_f32_16x16x32_bf16 v[16:19], v[172:175], v[204:207], v[16:19]
	v_mfma_f32_16x16x32_bf16 v[8:11], v[180:183], v[204:207], v[8:11]
	v_mfma_f32_16x16x32_bf16 v[4:7], v[172:175], v[212:215], v[4:7]
	v_mfma_f32_16x16x32_bf16 v[0:3], v[180:183], v[212:215], v[0:3]
	s_barrier
	s_add_i32 s57, s57, 2
	s_add_u32 s24, s24, 0x100
	s_addc_u32 s25, s25, 0
	s_add_u32 s55, s55, 0x100
	s_addc_u32 s56, s56, 0
	s_cmp_gt_u32 s57, 13
	s_cbranch_scc0 .LBB3_20
	s_mov_b64 vcc, s[0:1]
	s_cbranch_vccz .LBB3_23
	s_barrier

.LBB5_8:
	s_ashr_i32 s15, s14, 31
	s_lshl_b64 s[16:17], s[14:15], 19
	s_add_u32 s16, s28, s16
	v_cmp_lt_i64_e64 s[4:5], s[4:5], v[142:143]
	s_addc_u32 s17, s29, s17
	s_and_b64 s[18:19], s[4:5], exec
	s_cselect_b32 s15, s17, s23
	s_cselect_b32 s54, s16, s22
	s_ashr_i32 s13, s12, 31
	s_lshl_b64 s[18:19], s[12:13], 19
	s_add_u32 s18, s30, s18
	s_addc_u32 s19, s31, s19
	s_and_b64 s[26:27], s[4:5], exec
	s_cselect_b32 s13, s19, s25
	s_cselect_b32 s55, s18, s24
	s_add_u32 s22, s22, 0x40080
	s_addc_u32 s23, s23, 0
	s_add_u32 s56, s24, 0x100
	s_addc_u32 s57, s25, 0
	s_mov_b32 s58, -2
	ds_read_b128 v[152:155], v149
	ds_read_b128 v[156:159], v149 offset:1024
	ds_read_b128 v[160:163], v149 offset:2048
	ds_read_b128 v[164:167], v149 offset:3072
	ds_read_b128 v[168:171], v150
	ds_read_b128 v[172:175], v150 offset:1024
	ds_read_b128 v[176:179], v150 offset:2048
	ds_read_b128 v[180:183], v150 offset:3072
	s_add_u32 s24, s22, 0xfffc0080
	s_addc_u32 s25, s23, -1
	s_cmp_eq_u32 s58, 12
	s_cselect_b32 s27, s15, s25
	s_cselect_b32 s26, s54, s24
	s_cselect_b32 s25, s13, s57
	s_cselect_b32 s24, s55, s56
	v_lshl_add_u64 v[146:147], s[22:23], 0, v[138:139]
	s_add_i32 m0, s21, 0xc000
	s_nop 0
	global_load_lds_dwordx4 v[146:147], off
	ds_read_b128 v[184:187], v151
	ds_read_b128 v[188:191], v151 offset:1024
	ds_read_b128 v[192:195], v151 offset:2048
	ds_read_b128 v[196:199], v151 offset:3072
	ds_read_b128 v[200:203], v151 offset:4096
	ds_read_b128 v[204:207], v151 offset:5120
	ds_read_b128 v[208:211], v151 offset:6144
	ds_read_b128 v[212:215], v151 offset:7168
	v_lshl_add_u64 v[146:147], s[22:23], 0, v[140:141]
	s_add_i32 m0, s21, 0xe000
	s_nop 0
	global_load_lds_dwordx4 v[146:147], off
	s_waitcnt vmcnt(8)
	s_waitcnt lgkmcnt(0)
	s_barrier
	s_waitcnt lgkmcnt(0)
	v_mfma_f32_16x16x32_bf16 v[124:127], v[152:155], v[184:187], 0
	v_mfma_f32_16x16x32_bf16 v[120:123], v[160:163], v[184:187], 0
	v_mfma_f32_16x16x32_bf16 v[108:111], v[152:155], v[192:195], 0
	v_mfma_f32_16x16x32_bf16 v[104:107], v[160:163], v[192:195], 0
	v_mfma_f32_16x16x32_bf16 v[92:95], v[152:155], v[200:203], 0
	v_mfma_f32_16x16x32_bf16 v[88:91], v[160:163], v[200:203], 0
	v_mfma_f32_16x16x32_bf16 v[76:79], v[152:155], v[208:211], 0
	v_mfma_f32_16x16x32_bf16 v[72:75], v[160:163], v[208:211], 0
	v_mfma_f32_16x16x32_bf16 v[124:127], v[156:159], v[188:191], v[124:127]
	v_mfma_f32_16x16x32_bf16 v[120:123], v[164:167], v[188:191], v[120:123]
	v_mfma_f32_16x16x32_bf16 v[108:111], v[156:159], v[196:199], v[108:111]
	v_mfma_f32_16x16x32_bf16 v[104:107], v[164:167], v[196:199], v[104:107]
	v_mfma_f32_16x16x32_bf16 v[92:95], v[156:159], v[204:207], v[92:95]
	v_mfma_f32_16x16x32_bf16 v[88:91], v[164:167], v[204:207], v[88:91]
	v_mfma_f32_16x16x32_bf16 v[76:79], v[156:159], v[212:215], v[76:79]
	v_mfma_f32_16x16x32_bf16 v[72:75], v[164:167], v[212:215], v[72:75]
	v_mfma_f32_16x16x32_bf16 v[116:119], v[168:171], v[184:187], 0
	v_mfma_f32_16x16x32_bf16 v[112:115], v[176:179], v[184:187], 0
	v_mfma_f32_16x16x32_bf16 v[100:103], v[168:171], v[192:195], 0
	v_mfma_f32_16x16x32_bf16 v[96:99], v[176:179], v[192:195], 0
	v_mfma_f32_16x16x32_bf16 v[84:87], v[168:171], v[200:203], 0
	v_mfma_f32_16x16x32_bf16 v[80:83], v[176:179], v[200:203], 0
	v_mfma_f32_16x16x32_bf16 v[68:71], v[168:171], v[208:211], 0
	v_mfma_f32_16x16x32_bf16 v[64:67], v[176:179], v[208:211], 0
	v_mfma_f32_16x16x32_bf16 v[116:119], v[172:175], v[188:191], v[116:119]
	v_mfma_f32_16x16x32_bf16 v[112:115], v[180:183], v[188:191], v[112:115]
	v_mfma_f32_16x16x32_bf16 v[100:103], v[172:175], v[196:199], v[100:103]
	v_mfma_f32_16x16x32_bf16 v[96:99], v[180:183], v[196:199], v[96:99]
	v_mfma_f32_16x16x32_bf16 v[84:87], v[172:175], v[204:207], v[84:87]
	v_mfma_f32_16x16x32_bf16 v[80:83], v[180:183], v[204:207], v[80:83]
	v_mfma_f32_16x16x32_bf16 v[68:71], v[172:175], v[212:215], v[68:71]
	v_mfma_f32_16x16x32_bf16 v[64:67], v[180:183], v[212:215], v[64:67]
	s_barrier
	ds_read_b128 v[184:187], v151 offset:16384
	ds_read_b128 v[188:191], v151 offset:17408
	s_add_i32 s59, s43, s33
	v_lshl_add_u64 v[146:147], s[24:25], 0, v[132:133]
	s_mov_b32 m0, s59
	s_nop 0
	global_load_lds_dwordx4 v[146:147], off
	ds_read_b128 v[192:195], v151 offset:18432
	ds_read_b128 v[196:199], v151 offset:19456
	s_add_i32 m0, s59, 0x2000
	s_add_u32 s60, s24, 0x40000
	v_lshl_add_u64 v[216:217], s[24:25], 0, v[128:129]
	s_addc_u32 s61, s25, 0
	s_add_i32 s59, s44, s33
	global_load_lds_dwordx4 v[216:217], off
	ds_read_b128 v[200:203], v151 offset:20480
	v_lshl_add_u64 v[218:219], s[60:61], 0, v[132:133]
	s_mov_b32 m0, s59
	v_lshl_add_u64 v[220:221], s[26:27], 0, v[130:131]
	global_load_lds_dwordx4 v[218:219], off
	ds_read_b128 v[204:207], v151 offset:21504
	v_lshl_add_u64 v[218:219], s[60:61], 0, v[128:129]
	s_add_i32 m0, s59, 0x2000
	s_nop 0
	global_load_lds_dwordx4 v[218:219], off
	ds_read_b128 v[208:211], v151 offset:22528
	v_lshl_add_u64 v[218:219], s[26:27], 0, v[134:135]
	s_mov_b32 m0, s21
	s_nop 0
	global_load_lds_dwordx4 v[218:219], off
	ds_read_b128 v[212:215], v151 offset:23552
	s_mov_b32 m0, s36
	s_nop 0
	global_load_lds_dwordx4 v[220:221], off
	s_waitcnt vmcnt(8)
	s_waitcnt lgkmcnt(0)
	s_barrier
	s_waitcnt lgkmcnt(0)
	v_mfma_f32_16x16x32_bf16 v[60:63], v[152:155], v[184:187], 0
	v_mfma_f32_16x16x32_bf16 v[56:59], v[160:163], v[184:187], 0
	v_mfma_f32_16x16x32_bf16 v[44:47], v[152:155], v[192:195], 0
	v_mfma_f32_16x16x32_bf16 v[40:43], v[160:163], v[192:195], 0
	v_mfma_f32_16x16x32_bf16 v[28:31], v[152:155], v[200:203], 0
	v_mfma_f32_16x16x32_bf16 v[24:27], v[160:163], v[200:203], 0
	v_mfma_f32_16x16x32_bf16 v[12:15], v[152:155], v[208:211], 0
	v_mfma_f32_16x16x32_bf16 v[8:11], v[160:163], v[208:211], 0
	v_mfma_f32_16x16x32_bf16 v[60:63], v[156:159], v[188:191], v[60:63]
	v_mfma_f32_16x16x32_bf16 v[56:59], v[164:167], v[188:191], v[56:59]
	v_mfma_f32_16x16x32_bf16 v[44:47], v[156:159], v[196:199], v[44:47]
	v_mfma_f32_16x16x32_bf16 v[40:43], v[164:167], v[196:199], v[40:43]
	v_mfma_f32_16x16x32_bf16 v[28:31], v[156:159], v[204:207], v[28:31]
	v_mfma_f32_16x16x32_bf16 v[24:27], v[164:167], v[204:207], v[24:27]
	v_mfma_f32_16x16x32_bf16 v[12:15], v[156:159], v[212:215], v[12:15]
	v_mfma_f32_16x16x32_bf16 v[8:11], v[164:167], v[212:215], v[8:11]
	v_mfma_f32_16x16x32_bf16 v[52:55], v[168:171], v[184:187], 0
	v_mfma_f32_16x16x32_bf16 v[48:51], v[176:179], v[184:187], 0
	v_mfma_f32_16x16x32_bf16 v[36:39], v[168:171], v[192:195], 0
	v_mfma_f32_16x16x32_bf16 v[32:35], v[176:179], v[192:195], 0
	v_mfma_f32_16x16x32_bf16 v[20:23], v[168:171], v[200:203], 0
	v_mfma_f32_16x16x32_bf16 v[16:19], v[176:179], v[200:203], 0
	v_mfma_f32_16x16x32_bf16 v[4:7], v[168:171], v[208:211], 0
	v_mfma_f32_16x16x32_bf16 v[0:3], v[176:179], v[208:211], 0
	v_mfma_f32_16x16x32_bf16 v[52:55], v[172:175], v[188:191], v[52:55]
	v_mfma_f32_16x16x32_bf16 v[48:51], v[180:183], v[188:191], v[48:51]
	v_mfma_f32_16x16x32_bf16 v[36:39], v[172:175], v[196:199], v[36:39]
	v_mfma_f32_16x16x32_bf16 v[32:35], v[180:183], v[196:199], v[32:35]
	v_mfma_f32_16x16x32_bf16 v[20:23], v[172:175], v[204:207], v[20:23]
	v_mfma_f32_16x16x32_bf16 v[16:19], v[180:183], v[204:207], v[16:19]
	v_mfma_f32_16x16x32_bf16 v[4:7], v[172:175], v[212:215], v[4:7]
	v_mfma_f32_16x16x32_bf16 v[0:3], v[180:183], v[212:215], v[0:3]
	s_barrier
	s_add_i32 s60, 0, 0x1c000
	s_add_i32 s59, 0, 0x18000
	v_add_u32_e32 v164, s59, v148
	v_add_u32_e32 v180, s60, v148
	ds_read_b128 v[152:155], v164
	ds_read_b128 v[156:159], v164 offset:1024
	ds_read_b128 v[160:163], v164 offset:2048
	ds_read_b128 v[164:167], v164 offset:3072
	ds_read_b128 v[168:171], v180
	ds_read_b128 v[172:175], v180 offset:1024
	ds_read_b128 v[176:179], v180 offset:2048
	ds_read_b128 v[180:183], v180 offset:3072
	s_add_u32 s26, s26, 0x40000
	s_addc_u32 s27, s27, 0
	s_mov_b32 m0, s37
	v_lshl_add_u64 v[222:223], s[26:27], 0, v[134:135]
	global_load_lds_dwordx4 v[222:223], off
	ds_read_b128 v[184:187], v151 offset:32768
	ds_read_b128 v[188:191], v151 offset:33792
	ds_read_b128 v[192:195], v151 offset:34816
	ds_read_b128 v[196:199], v151 offset:35840
	ds_read_b128 v[200:203], v151 offset:36864
	ds_read_b128 v[204:207], v151 offset:37888
	ds_read_b128 v[208:211], v151 offset:38912
	ds_read_b128 v[212:215], v151 offset:39936
	v_lshl_add_u64 v[222:223], s[26:27], 0, v[130:131]
	s_mov_b32 m0, s38
	s_nop 0
	global_load_lds_dwordx4 v[222:223], off
	s_waitcnt vmcnt(8)
	s_waitcnt lgkmcnt(0)
	s_barrier
	s_waitcnt lgkmcnt(0)
	v_mfma_f32_16x16x32_bf16 v[124:127], v[152:155], v[184:187], v[124:127]
	v_mfma_f32_16x16x32_bf16 v[120:123], v[160:163], v[184:187], v[120:123]
	v_mfma_f32_16x16x32_bf16 v[108:111], v[152:155], v[192:195], v[108:111]
	v_mfma_f32_16x16x32_bf16 v[104:107], v[160:163], v[192:195], v[104:107]
	v_mfma_f32_16x16x32_bf16 v[92:95], v[152:155], v[200:203], v[92:95]
	v_mfma_f32_16x16x32_bf16 v[88:91], v[160:163], v[200:203], v[88:91]
	v_mfma_f32_16x16x32_bf16 v[76:79], v[152:155], v[208:211], v[76:79]
	v_mfma_f32_16x16x32_bf16 v[72:75], v[160:163], v[208:211], v[72:75]
	v_mfma_f32_16x16x32_bf16 v[124:127], v[156:159], v[188:191], v[124:127]
	v_mfma_f32_16x16x32_bf16 v[120:123], v[164:167], v[188:191], v[120:123]
	v_mfma_f32_16x16x32_bf16 v[108:111], v[156:159], v[196:199], v[108:111]
	v_mfma_f32_16x16x32_bf16 v[104:107], v[164:167], v[196:199], v[104:107]
	v_mfma_f32_16x16x32_bf16 v[92:95], v[156:159], v[204:207], v[92:95]
	v_mfma_f32_16x16x32_bf16 v[88:91], v[164:167], v[204:207], v[88:91]
	v_mfma_f32_16x16x32_bf16 v[76:79], v[156:159], v[212:215], v[76:79]
	v_mfma_f32_16x16x32_bf16 v[72:75], v[164:167], v[212:215], v[72:75]
	v_mfma_f32_16x16x32_bf16 v[116:119], v[168:171], v[184:187], v[116:119]
	v_mfma_f32_16x16x32_bf16 v[112:115], v[176:179], v[184:187], v[112:115]
	v_mfma_f32_16x16x32_bf16 v[100:103], v[168:171], v[192:195], v[100:103]
	v_mfma_f32_16x16x32_bf16 v[96:99], v[176:179], v[192:195], v[96:99]
	v_mfma_f32_16x16x32_bf16 v[84:87], v[168:171], v[200:203], v[84:87]
	v_mfma_f32_16x16x32_bf16 v[80:83], v[176:179], v[200:203], v[80:83]
	v_mfma_f32_16x16x32_bf16 v[68:71], v[168:171], v[208:211], v[68:71]
	v_mfma_f32_16x16x32_bf16 v[64:67], v[176:179], v[208:211], v[64:67]
	v_mfma_f32_16x16x32_bf16 v[116:119], v[172:175], v[188:191], v[116:119]
	v_mfma_f32_16x16x32_bf16 v[112:115], v[180:183], v[188:191], v[112:115]
	v_mfma_f32_16x16x32_bf16 v[100:103], v[172:175], v[196:199], v[100:103]
	v_mfma_f32_16x16x32_bf16 v[96:99], v[180:183], v[196:199], v[96:99]
	v_mfma_f32_16x16x32_bf16 v[84:87], v[172:175], v[204:207], v[84:87]
	v_mfma_f32_16x16x32_bf16 v[80:83], v[180:183], v[204:207], v[80:83]
	v_mfma_f32_16x16x32_bf16 v[68:71], v[172:175], v[212:215], v[68:71]
	v_mfma_f32_16x16x32_bf16 v[64:67], v[180:183], v[212:215], v[64:67]
	s_barrier
	ds_read_b128 v[184:187], v151 offset:49152
	ds_read_b128 v[188:191], v151 offset:50176
	s_add_i32 s26, s59, s33
	v_lshl_add_u64 v[146:147], v[146:147], 0, s[10:11]
	s_mov_b32 m0, s26
	s_nop 0
	global_load_lds_dwordx4 v[146:147], off
	ds_read_b128 v[192:195], v151 offset:51200
	ds_read_b128 v[196:199], v151 offset:52224
	s_add_i32 m0, s26, 0x2000
	s_add_u32 s24, s24, 0x40080
	v_lshl_add_u64 v[146:147], v[216:217], 0, s[10:11]
	s_addc_u32 s25, s25, 0
	s_add_i32 s26, s60, s33
	global_load_lds_dwordx4 v[146:147], off
	ds_read_b128 v[200:203], v151 offset:53248
	v_lshl_add_u64 v[146:147], s[24:25], 0, v[132:133]
	s_mov_b32 m0, s26
	s_nop 0
	global_load_lds_dwordx4 v[146:147], off
	ds_read_b128 v[204:207], v151 offset:54272
	v_lshl_add_u64 v[146:147], s[24:25], 0, v[128:129]
	s_add_i32 m0, s26, 0x2000
	s_nop 0
	global_load_lds_dwordx4 v[146:147], off
	ds_read_b128 v[208:211], v151 offset:55296
	v_lshl_add_u64 v[146:147], v[218:219], 0, s[10:11]
	s_mov_b32 m0, s40
	s_nop 0
	global_load_lds_dwordx4 v[146:147], off
	ds_read_b128 v[212:215], v151 offset:56320
	v_lshl_add_u64 v[146:147], v[220:221], 0, s[10:11]
	s_mov_b32 m0, s41
	s_nop 0
	global_load_lds_dwordx4 v[146:147], off
	s_waitcnt vmcnt(8)
	s_waitcnt lgkmcnt(0)
	s_barrier
	s_waitcnt lgkmcnt(0)
	v_mfma_f32_16x16x32_bf16 v[60:63], v[152:155], v[184:187], v[60:63]
	v_mfma_f32_16x16x32_bf16 v[56:59], v[160:163], v[184:187], v[56:59]
	v_mfma_f32_16x16x32_bf16 v[44:47], v[152:155], v[192:195], v[44:47]
	v_mfma_f32_16x16x32_bf16 v[40:43], v[160:163], v[192:195], v[40:43]
	v_mfma_f32_16x16x32_bf16 v[28:31], v[152:155], v[200:203], v[28:31]
	v_mfma_f32_16x16x32_bf16 v[24:27], v[160:163], v[200:203], v[24:27]
	v_mfma_f32_16x16x32_bf16 v[12:15], v[152:155], v[208:211], v[12:15]
	v_mfma_f32_16x16x32_bf16 v[8:11], v[160:163], v[208:211], v[8:11]
	v_mfma_f32_16x16x32_bf16 v[60:63], v[156:159], v[188:191], v[60:63]
	v_mfma_f32_16x16x32_bf16 v[56:59], v[164:167], v[188:191], v[56:59]
	v_mfma_f32_16x16x32_bf16 v[44:47], v[156:159], v[196:199], v[44:47]
	v_mfma_f32_16x16x32_bf16 v[40:43], v[164:167], v[196:199], v[40:43]
	v_mfma_f32_16x16x32_bf16 v[28:31], v[156:159], v[204:207], v[28:31]
	v_mfma_f32_16x16x32_bf16 v[24:27], v[164:167], v[204:207], v[24:27]
	v_mfma_f32_16x16x32_bf16 v[12:15], v[156:159], v[212:215], v[12:15]
	v_mfma_f32_16x16x32_bf16 v[8:11], v[164:167], v[212:215], v[8:11]
	v_mfma_f32_16x16x32_bf16 v[52:55], v[168:171], v[184:187], v[52:55]
	v_mfma_f32_16x16x32_bf16 v[48:51], v[176:179], v[184:187], v[48:51]
	v_mfma_f32_16x16x32_bf16 v[36:39], v[168:171], v[192:195], v[36:39]
	v_mfma_f32_16x16x32_bf16 v[32:35], v[176:179], v[192:195], v[32:35]
	v_mfma_f32_16x16x32_bf16 v[20:23], v[168:171], v[200:203], v[20:23]
	v_mfma_f32_16x16x32_bf16 v[16:19], v[176:179], v[200:203], v[16:19]
	v_mfma_f32_16x16x32_bf16 v[4:7], v[168:171], v[208:211], v[4:7]
	v_mfma_f32_16x16x32_bf16 v[0:3], v[176:179], v[208:211], v[0:3]
	v_mfma_f32_16x16x32_bf16 v[52:55], v[172:175], v[188:191], v[52:55]
	v_mfma_f32_16x16x32_bf16 v[48:51], v[180:183], v[188:191], v[48:51]
	v_mfma_f32_16x16x32_bf16 v[36:39], v[172:175], v[196:199], v[36:39]
	v_mfma_f32_16x16x32_bf16 v[32:35], v[180:183], v[196:199], v[32:35]
	v_mfma_f32_16x16x32_bf16 v[20:23], v[172:175], v[204:207], v[20:23]
	v_mfma_f32_16x16x32_bf16 v[16:19], v[180:183], v[204:207], v[16:19]
	v_mfma_f32_16x16x32_bf16 v[4:7], v[172:175], v[212:215], v[4:7]
	v_mfma_f32_16x16x32_bf16 v[0:3], v[180:183], v[212:215], v[0:3]
	s_barrier
	s_add_i32 s58, s58, 2
	s_add_u32 s22, s22, 0x100
	s_addc_u32 s23, s23, 0
	s_add_u32 s56, s56, 0x100
	s_addc_u32 s57, s57, 0
	s_cmp_gt_u32 s58, 13
.LBB5_9:
	ds_read_b128 v[152:155], v149
	ds_read_b128 v[156:159], v149 offset:1024
	ds_read_b128 v[160:163], v149 offset:2048
	ds_read_b128 v[164:167], v149 offset:3072
	ds_read_b128 v[168:171], v150
	ds_read_b128 v[172:175], v150 offset:1024
	ds_read_b128 v[176:179], v150 offset:2048
	ds_read_b128 v[180:183], v150 offset:3072
	s_add_u32 s24, s22, 0xfffc0080
	s_addc_u32 s25, s23, -1
	s_cmp_eq_u32 s58, 12
	s_cselect_b32 s27, s15, s25
	s_cselect_b32 s26, s54, s24
	s_cselect_b32 s25, s13, s57
	s_cselect_b32 s24, s55, s56
	v_lshl_add_u64 v[146:147], s[22:23], 0, v[138:139]
	s_add_i32 m0, s21, 0xc000
	s_nop 0
	global_load_lds_dwordx4 v[146:147], off
	ds_read_b128 v[184:187], v151
	ds_read_b128 v[188:191], v151 offset:1024
	ds_read_b128 v[192:195], v151 offset:2048
	ds_read_b128 v[196:199], v151 offset:3072
	ds_read_b128 v[200:203], v151 offset:4096
	ds_read_b128 v[204:207], v151 offset:5120
	ds_read_b128 v[208:211], v151 offset:6144
	ds_read_b128 v[212:215], v151 offset:7168
	v_lshl_add_u64 v[146:147], s[22:23], 0, v[140:141]
	s_add_i32 m0, s21, 0xe000
	s_nop 0
	global_load_lds_dwordx4 v[146:147], off
	s_waitcnt vmcnt(8)
	s_waitcnt lgkmcnt(0)
	s_barrier
	s_waitcnt lgkmcnt(0)
	v_mfma_f32_16x16x32_bf16 v[124:127], v[152:155], v[184:187], v[124:127]
	v_mfma_f32_16x16x32_bf16 v[120:123], v[160:163], v[184:187], v[120:123]
	v_mfma_f32_16x16x32_bf16 v[108:111], v[152:155], v[192:195], v[108:111]
	v_mfma_f32_16x16x32_bf16 v[104:107], v[160:163], v[192:195], v[104:107]
	v_mfma_f32_16x16x32_bf16 v[92:95], v[152:155], v[200:203], v[92:95]
	v_mfma_f32_16x16x32_bf16 v[88:91], v[160:163], v[200:203], v[88:91]
	v_mfma_f32_16x16x32_bf16 v[76:79], v[152:155], v[208:211], v[76:79]
	v_mfma_f32_16x16x32_bf16 v[72:75], v[160:163], v[208:211], v[72:75]
	v_mfma_f32_16x16x32_bf16 v[124:127], v[156:159], v[188:191], v[124:127]
	v_mfma_f32_16x16x32_bf16 v[120:123], v[164:167], v[188:191], v[120:123]
	v_mfma_f32_16x16x32_bf16 v[108:111], v[156:159], v[196:199], v[108:111]
	v_mfma_f32_16x16x32_bf16 v[104:107], v[164:167], v[196:199], v[104:107]
	v_mfma_f32_16x16x32_bf16 v[92:95], v[156:159], v[204:207], v[92:95]
	v_mfma_f32_16x16x32_bf16 v[88:91], v[164:167], v[204:207], v[88:91]
	v_mfma_f32_16x16x32_bf16 v[76:79], v[156:159], v[212:215], v[76:79]
	v_mfma_f32_16x16x32_bf16 v[72:75], v[164:167], v[212:215], v[72:75]
	v_mfma_f32_16x16x32_bf16 v[116:119], v[168:171], v[184:187], v[116:119]
	v_mfma_f32_16x16x32_bf16 v[112:115], v[176:179], v[184:187], v[112:115]
	v_mfma_f32_16x16x32_bf16 v[100:103], v[168:171], v[192:195], v[100:103]
	v_mfma_f32_16x16x32_bf16 v[96:99], v[176:179], v[192:195], v[96:99]
	v_mfma_f32_16x16x32_bf16 v[84:87], v[168:171], v[200:203], v[84:87]
	v_mfma_f32_16x16x32_bf16 v[80:83], v[176:179], v[200:203], v[80:83]
	v_mfma_f32_16x16x32_bf16 v[68:71], v[168:171], v[208:211], v[68:71]
	v_mfma_f32_16x16x32_bf16 v[64:67], v[176:179], v[208:211], v[64:67]
	v_mfma_f32_16x16x32_bf16 v[116:119], v[172:175], v[188:191], v[116:119]
	v_mfma_f32_16x16x32_bf16 v[112:115], v[180:183], v[188:191], v[112:115]
	v_mfma_f32_16x16x32_bf16 v[100:103], v[172:175], v[196:199], v[100:103]
	v_mfma_f32_16x16x32_bf16 v[96:99], v[180:183], v[196:199], v[96:99]
	v_mfma_f32_16x16x32_bf16 v[84:87], v[172:175], v[204:207], v[84:87]
	v_mfma_f32_16x16x32_bf16 v[80:83], v[180:183], v[204:207], v[80:83]
	v_mfma_f32_16x16x32_bf16 v[68:71], v[172:175], v[212:215], v[68:71]
	v_mfma_f32_16x16x32_bf16 v[64:67], v[180:183], v[212:215], v[64:67]
	s_barrier
	ds_read_b128 v[184:187], v151 offset:16384
	ds_read_b128 v[188:191], v151 offset:17408
	s_add_i32 s59, s43, s33
	v_lshl_add_u64 v[146:147], s[24:25], 0, v[132:133]
	s_mov_b32 m0, s59
	s_nop 0
	global_load_lds_dwordx4 v[146:147], off
	ds_read_b128 v[192:195], v151 offset:18432
	ds_read_b128 v[196:199], v151 offset:19456
	s_add_i32 m0, s59, 0x2000
	s_add_u32 s60, s24, 0x40000
	v_lshl_add_u64 v[216:217], s[24:25], 0, v[128:129]
	s_addc_u32 s61, s25, 0
	s_add_i32 s59, s44, s33
	global_load_lds_dwordx4 v[216:217], off
	ds_read_b128 v[200:203], v151 offset:20480
	v_lshl_add_u64 v[218:219], s[60:61], 0, v[132:133]
	s_mov_b32 m0, s59
	v_lshl_add_u64 v[220:221], s[26:27], 0, v[130:131]
	global_load_lds_dwordx4 v[218:219], off
	ds_read_b128 v[204:207], v151 offset:21504
	v_lshl_add_u64 v[218:219], s[60:61], 0, v[128:129]
	s_add_i32 m0, s59, 0x2000
	s_nop 0
	global_load_lds_dwordx4 v[218:219], off
	ds_read_b128 v[208:211], v151 offset:22528
	v_lshl_add_u64 v[218:219], s[26:27], 0, v[134:135]
	s_mov_b32 m0, s21
	s_nop 0
	global_load_lds_dwordx4 v[218:219], off
	ds_read_b128 v[212:215], v151 offset:23552
	s_mov_b32 m0, s36
	s_nop 0
	global_load_lds_dwordx4 v[220:221], off
	s_waitcnt vmcnt(8)
	s_waitcnt lgkmcnt(0)
	s_barrier
	s_waitcnt lgkmcnt(0)
	v_mfma_f32_16x16x32_bf16 v[60:63], v[152:155], v[184:187], v[60:63]
	v_mfma_f32_16x16x32_bf16 v[56:59], v[160:163], v[184:187], v[56:59]
	v_mfma_f32_16x16x32_bf16 v[44:47], v[152:155], v[192:195], v[44:47]
	v_mfma_f32_16x16x32_bf16 v[40:43], v[160:163], v[192:195], v[40:43]
	v_mfma_f32_16x16x32_bf16 v[28:31], v[152:155], v[200:203], v[28:31]
	v_mfma_f32_16x16x32_bf16 v[24:27], v[160:163], v[200:203], v[24:27]
	v_mfma_f32_16x16x32_bf16 v[12:15], v[152:155], v[208:211], v[12:15]
	v_mfma_f32_16x16x32_bf16 v[8:11], v[160:163], v[208:211], v[8:11]
	v_mfma_f32_16x16x32_bf16 v[60:63], v[156:159], v[188:191], v[60:63]
	v_mfma_f32_16x16x32_bf16 v[56:59], v[164:167], v[188:191], v[56:59]
	v_mfma_f32_16x16x32_bf16 v[44:47], v[156:159], v[196:199], v[44:47]
	v_mfma_f32_16x16x32_bf16 v[40:43], v[164:167], v[196:199], v[40:43]
	v_mfma_f32_16x16x32_bf16 v[28:31], v[156:159], v[204:207], v[28:31]
	v_mfma_f32_16x16x32_bf16 v[24:27], v[164:167], v[204:207], v[24:27]
	v_mfma_f32_16x16x32_bf16 v[12:15], v[156:159], v[212:215], v[12:15]
	v_mfma_f32_16x16x32_bf16 v[8:11], v[164:167], v[212:215], v[8:11]
	v_mfma_f32_16x16x32_bf16 v[52:55], v[168:171], v[184:187], v[52:55]
	v_mfma_f32_16x16x32_bf16 v[48:51], v[176:179], v[184:187], v[48:51]
	v_mfma_f32_16x16x32_bf16 v[36:39], v[168:171], v[192:195], v[36:39]
	v_mfma_f32_16x16x32_bf16 v[32:35], v[176:179], v[192:195], v[32:35]
	v_mfma_f32_16x16x32_bf16 v[20:23], v[168:171], v[200:203], v[20:23]
	v_mfma_f32_16x16x32_bf16 v[16:19], v[176:179], v[200:203], v[16:19]
	v_mfma_f32_16x16x32_bf16 v[4:7], v[168:171], v[208:211], v[4:7]
	v_mfma_f32_16x16x32_bf16 v[0:3], v[176:179], v[208:211], v[0:3]
	v_mfma_f32_16x16x32_bf16 v[52:55], v[172:175], v[188:191], v[52:55]
	v_mfma_f32_16x16x32_bf16 v[48:51], v[180:183], v[188:191], v[48:51]
	v_mfma_f32_16x16x32_bf16 v[36:39], v[172:175], v[196:199], v[36:39]
	v_mfma_f32_16x16x32_bf16 v[32:35], v[180:183], v[196:199], v[32:35]
	v_mfma_f32_16x16x32_bf16 v[20:23], v[172:175], v[204:207], v[20:23]
	v_mfma_f32_16x16x32_bf16 v[16:19], v[180:183], v[204:207], v[16:19]
	v_mfma_f32_16x16x32_bf16 v[4:7], v[172:175], v[212:215], v[4:7]
	v_mfma_f32_16x16x32_bf16 v[0:3], v[180:183], v[212:215], v[0:3]
	s_barrier
	s_add_i32 s60, 0, 0x1c000
	s_add_i32 s59, 0, 0x18000
	v_add_u32_e32 v164, s59, v148
	v_add_u32_e32 v180, s60, v148
	ds_read_b128 v[152:155], v164
	ds_read_b128 v[156:159], v164 offset:1024
	ds_read_b128 v[160:163], v164 offset:2048
	ds_read_b128 v[164:167], v164 offset:3072
	ds_read_b128 v[168:171], v180
	ds_read_b128 v[172:175], v180 offset:1024
	ds_read_b128 v[176:179], v180 offset:2048
	ds_read_b128 v[180:183], v180 offset:3072
	s_add_u32 s26, s26, 0x40000
	s_addc_u32 s27, s27, 0
	s_mov_b32 m0, s37
	v_lshl_add_u64 v[222:223], s[26:27], 0, v[134:135]
	global_load_lds_dwordx4 v[222:223], off
	ds_read_b128 v[184:187], v151 offset:32768
	ds_read_b128 v[188:191], v151 offset:33792
	ds_read_b128 v[192:195], v151 offset:34816
	ds_read_b128 v[196:199], v151 offset:35840
	ds_read_b128 v[200:203], v151 offset:36864
	ds_read_b128 v[204:207], v151 offset:37888
	ds_read_b128 v[208:211], v151 offset:38912
	ds_read_b128 v[212:215], v151 offset:39936
	v_lshl_add_u64 v[222:223], s[26:27], 0, v[130:131]
	s_mov_b32 m0, s38
	s_nop 0
	global_load_lds_dwordx4 v[222:223], off
	s_waitcnt vmcnt(8)
	s_waitcnt lgkmcnt(0)
	s_barrier
	s_waitcnt lgkmcnt(0)
	v_mfma_f32_16x16x32_bf16 v[124:127], v[152:155], v[184:187], v[124:127]
	v_mfma_f32_16x16x32_bf16 v[120:123], v[160:163], v[184:187], v[120:123]
	v_mfma_f32_16x16x32_bf16 v[108:111], v[152:155], v[192:195], v[108:111]
	v_mfma_f32_16x16x32_bf16 v[104:107], v[160:163], v[192:195], v[104:107]
	v_mfma_f32_16x16x32_bf16 v[92:95], v[152:155], v[200:203], v[92:95]
	v_mfma_f32_16x16x32_bf16 v[88:91], v[160:163], v[200:203], v[88:91]
	v_mfma_f32_16x16x32_bf16 v[76:79], v[152:155], v[208:211], v[76:79]
	v_mfma_f32_16x16x32_bf16 v[72:75], v[160:163], v[208:211], v[72:75]
	v_mfma_f32_16x16x32_bf16 v[124:127], v[156:159], v[188:191], v[124:127]
	v_mfma_f32_16x16x32_bf16 v[120:123], v[164:167], v[188:191], v[120:123]
	v_mfma_f32_16x16x32_bf16 v[108:111], v[156:159], v[196:199], v[108:111]
	v_mfma_f32_16x16x32_bf16 v[104:107], v[164:167], v[196:199], v[104:107]
	v_mfma_f32_16x16x32_bf16 v[92:95], v[156:159], v[204:207], v[92:95]
	v_mfma_f32_16x16x32_bf16 v[88:91], v[164:167], v[204:207], v[88:91]
	v_mfma_f32_16x16x32_bf16 v[76:79], v[156:159], v[212:215], v[76:79]
	v_mfma_f32_16x16x32_bf16 v[72:75], v[164:167], v[212:215], v[72:75]
	v_mfma_f32_16x16x32_bf16 v[116:119], v[168:171], v[184:187], v[116:119]
	v_mfma_f32_16x16x32_bf16 v[112:115], v[176:179], v[184:187], v[112:115]
	v_mfma_f32_16x16x32_bf16 v[100:103], v[168:171], v[192:195], v[100:103]
	v_mfma_f32_16x16x32_bf16 v[96:99], v[176:179], v[192:195], v[96:99]
	v_mfma_f32_16x16x32_bf16 v[84:87], v[168:171], v[200:203], v[84:87]
	v_mfma_f32_16x16x32_bf16 v[80:83], v[176:179], v[200:203], v[80:83]
	v_mfma_f32_16x16x32_bf16 v[68:71], v[168:171], v[208:211], v[68:71]
	v_mfma_f32_16x16x32_bf16 v[64:67], v[176:179], v[208:211], v[64:67]
	v_mfma_f32_16x16x32_bf16 v[116:119], v[172:175], v[188:191], v[116:119]
	v_mfma_f32_16x16x32_bf16 v[112:115], v[180:183], v[188:191], v[112:115]
	v_mfma_f32_16x16x32_bf16 v[100:103], v[172:175], v[196:199], v[100:103]
	v_mfma_f32_16x16x32_bf16 v[96:99], v[180:183], v[196:199], v[96:99]
	v_mfma_f32_16x16x32_bf16 v[84:87], v[172:175], v[204:207], v[84:87]
	v_mfma_f32_16x16x32_bf16 v[80:83], v[180:183], v[204:207], v[80:83]
	v_mfma_f32_16x16x32_bf16 v[68:71], v[172:175], v[212:215], v[68:71]
	v_mfma_f32_16x16x32_bf16 v[64:67], v[180:183], v[212:215], v[64:67]
	s_barrier
	ds_read_b128 v[184:187], v151 offset:49152
	ds_read_b128 v[188:191], v151 offset:50176
	s_add_i32 s26, s59, s33
	v_lshl_add_u64 v[146:147], v[146:147], 0, s[10:11]
	s_mov_b32 m0, s26
	s_nop 0
	global_load_lds_dwordx4 v[146:147], off
	ds_read_b128 v[192:195], v151 offset:51200
	ds_read_b128 v[196:199], v151 offset:52224
	s_add_i32 m0, s26, 0x2000
	s_add_u32 s24, s24, 0x40080
	v_lshl_add_u64 v[146:147], v[216:217], 0, s[10:11]
	s_addc_u32 s25, s25, 0
	s_add_i32 s26, s60, s33
	global_load_lds_dwordx4 v[146:147], off
	ds_read_b128 v[200:203], v151 offset:53248
	v_lshl_add_u64 v[146:147], s[24:25], 0, v[132:133]
	s_mov_b32 m0, s26
	s_nop 0
	global_load_lds_dwordx4 v[146:147], off
	ds_read_b128 v[204:207], v151 offset:54272
	v_lshl_add_u64 v[146:147], s[24:25], 0, v[128:129]
	s_add_i32 m0, s26, 0x2000
	s_nop 0
	global_load_lds_dwordx4 v[146:147], off
	ds_read_b128 v[208:211], v151 offset:55296
	v_lshl_add_u64 v[146:147], v[218:219], 0, s[10:11]
	s_mov_b32 m0, s40
	s_nop 0
	global_load_lds_dwordx4 v[146:147], off
	ds_read_b128 v[212:215], v151 offset:56320
	v_lshl_add_u64 v[146:147], v[220:221], 0, s[10:11]
	s_mov_b32 m0, s41
	s_nop 0
	global_load_lds_dwordx4 v[146:147], off
	s_waitcnt vmcnt(8)
	s_waitcnt lgkmcnt(0)
	s_barrier
	s_waitcnt lgkmcnt(0)
	v_mfma_f32_16x16x32_bf16 v[60:63], v[152:155], v[184:187], v[60:63]
	v_mfma_f32_16x16x32_bf16 v[56:59], v[160:163], v[184:187], v[56:59]
	v_mfma_f32_16x16x32_bf16 v[44:47], v[152:155], v[192:195], v[44:47]
	v_mfma_f32_16x16x32_bf16 v[40:43], v[160:163], v[192:195], v[40:43]
	v_mfma_f32_16x16x32_bf16 v[28:31], v[152:155], v[200:203], v[28:31]
	v_mfma_f32_16x16x32_bf16 v[24:27], v[160:163], v[200:203], v[24:27]
	v_mfma_f32_16x16x32_bf16 v[12:15], v[152:155], v[208:211], v[12:15]
	v_mfma_f32_16x16x32_bf16 v[8:11], v[160:163], v[208:211], v[8:11]
	v_mfma_f32_16x16x32_bf16 v[60:63], v[156:159], v[188:191], v[60:63]
	v_mfma_f32_16x16x32_bf16 v[56:59], v[164:167], v[188:191], v[56:59]
	v_mfma_f32_16x16x32_bf16 v[44:47], v[156:159], v[196:199], v[44:47]
	v_mfma_f32_16x16x32_bf16 v[40:43], v[164:167], v[196:199], v[40:43]
	v_mfma_f32_16x16x32_bf16 v[28:31], v[156:159], v[204:207], v[28:31]
	v_mfma_f32_16x16x32_bf16 v[24:27], v[164:167], v[204:207], v[24:27]
	v_mfma_f32_16x16x32_bf16 v[12:15], v[156:159], v[212:215], v[12:15]
	v_mfma_f32_16x16x32_bf16 v[8:11], v[164:167], v[212:215], v[8:11]
	v_mfma_f32_16x16x32_bf16 v[52:55], v[168:171], v[184:187], v[52:55]
	v_mfma_f32_16x16x32_bf16 v[48:51], v[176:179], v[184:187], v[48:51]
	v_mfma_f32_16x16x32_bf16 v[36:39], v[168:171], v[192:195], v[36:39]
	v_mfma_f32_16x16x32_bf16 v[32:35], v[176:179], v[192:195], v[32:35]
	v_mfma_f32_16x16x32_bf16 v[20:23], v[168:171], v[200:203], v[20:23]
	v_mfma_f32_16x16x32_bf16 v[16:19], v[176:179], v[200:203], v[16:19]
	v_mfma_f32_16x16x32_bf16 v[4:7], v[168:171], v[208:211], v[4:7]
	v_mfma_f32_16x16x32_bf16 v[0:3], v[176:179], v[208:211], v[0:3]
	v_mfma_f32_16x16x32_bf16 v[52:55], v[172:175], v[188:191], v[52:55]
	v_mfma_f32_16x16x32_bf16 v[48:51], v[180:183], v[188:191], v[48:51]
	v_mfma_f32_16x16x32_bf16 v[36:39], v[172:175], v[196:199], v[36:39]
	v_mfma_f32_16x16x32_bf16 v[32:35], v[180:183], v[196:199], v[32:35]
	v_mfma_f32_16x16x32_bf16 v[20:23], v[172:175], v[204:207], v[20:23]
	v_mfma_f32_16x16x32_bf16 v[16:19], v[180:183], v[204:207], v[16:19]
	v_mfma_f32_16x16x32_bf16 v[4:7], v[172:175], v[212:215], v[4:7]
	v_mfma_f32_16x16x32_bf16 v[0:3], v[180:183], v[212:215], v[0:3]
	s_barrier
	s_add_i32 s58, s58, 2
	s_add_u32 s22, s22, 0x100
	s_addc_u32 s23, s23, 0
	s_add_u32 s56, s56, 0x100
	s_addc_u32 s57, s57, 0
	s_cmp_gt_u32 s58, 13
	s_cbranch_scc0 .LBB5_9
	s_mov_b64 vcc, s[0:1]
	s_cbranch_vccz .LBB5_12
	s_barrier

.LBB6_19:
	s_ashr_i32 s17, s16, 31
	s_lshl_b64 s[18:19], s[16:17], 21
	s_add_u32 s18, s33, s18
	v_cmp_lt_i64_e64 s[4:5], s[4:5], v[142:143]
	s_addc_u32 s19, s34, s19
	s_and_b64 s[20:21], s[4:5], exec
	s_cselect_b32 s17, s19, s25
	s_cselect_b32 s53, s18, s24
	s_ashr_i32 s15, s14, 31
	s_lshl_b64 s[20:21], s[14:15], 21
	s_add_u32 s20, s6, s20
	s_addc_u32 s21, s7, s21
	s_and_b64 s[28:29], s[4:5], exec
	s_cselect_b32 s15, s21, s27
	s_cselect_b32 s54, s20, s26
	s_add_u32 s24, s24, 0x100080
	s_addc_u32 s25, s25, 0
	s_add_u32 s55, s26, 0x100
	s_addc_u32 s56, s27, 0
	s_mov_b32 s57, -2
	ds_read_b128 v[152:155], v149
	ds_read_b128 v[156:159], v149 offset:1024
	ds_read_b128 v[160:163], v149 offset:2048
	ds_read_b128 v[164:167], v149 offset:3072
	ds_read_b128 v[168:171], v150
	ds_read_b128 v[172:175], v150 offset:1024
	ds_read_b128 v[176:179], v150 offset:2048
	ds_read_b128 v[180:183], v150 offset:3072
	s_add_u32 s26, s24, 0xfff00080
	s_addc_u32 s27, s25, -1
	s_cmp_eq_u32 s57, 60
	s_cselect_b32 s29, s17, s27
	s_cselect_b32 s28, s53, s26
	s_cselect_b32 s27, s15, s56
	s_cselect_b32 s26, s54, s55
	v_lshl_add_u64 v[146:147], s[24:25], 0, v[138:139]
	s_add_i32 m0, s23, 0xc000
	s_nop 0
	global_load_lds_dwordx4 v[146:147], off
	ds_read_b128 v[184:187], v151
	ds_read_b128 v[188:191], v151 offset:1024
	ds_read_b128 v[192:195], v151 offset:2048
	ds_read_b128 v[196:199], v151 offset:3072
	ds_read_b128 v[200:203], v151 offset:4096
	ds_read_b128 v[204:207], v151 offset:5120
	ds_read_b128 v[208:211], v151 offset:6144
	ds_read_b128 v[212:215], v151 offset:7168
	v_lshl_add_u64 v[146:147], s[24:25], 0, v[140:141]
	s_add_i32 m0, s23, 0xe000
	s_nop 0
	global_load_lds_dwordx4 v[146:147], off
	s_waitcnt vmcnt(8)
	s_waitcnt lgkmcnt(0)
	s_barrier
	s_waitcnt lgkmcnt(0)
	v_mfma_f32_16x16x32_bf16 v[124:127], v[152:155], v[184:187], 0
	v_mfma_f32_16x16x32_bf16 v[120:123], v[160:163], v[184:187], 0
	v_mfma_f32_16x16x32_bf16 v[116:119], v[152:155], v[192:195], 0
	v_mfma_f32_16x16x32_bf16 v[108:111], v[160:163], v[192:195], 0
	v_mfma_f32_16x16x32_bf16 v[100:103], v[152:155], v[200:203], 0
	v_mfma_f32_16x16x32_bf16 v[92:95], v[160:163], v[200:203], 0
	v_mfma_f32_16x16x32_bf16 v[84:87], v[152:155], v[208:211], 0
	v_mfma_f32_16x16x32_bf16 v[76:79], v[160:163], v[208:211], 0
	v_mfma_f32_16x16x32_bf16 v[124:127], v[156:159], v[188:191], v[124:127]
	v_mfma_f32_16x16x32_bf16 v[120:123], v[164:167], v[188:191], v[120:123]
	v_mfma_f32_16x16x32_bf16 v[116:119], v[156:159], v[196:199], v[116:119]
	v_mfma_f32_16x16x32_bf16 v[108:111], v[164:167], v[196:199], v[108:111]
	v_mfma_f32_16x16x32_bf16 v[100:103], v[156:159], v[204:207], v[100:103]
	v_mfma_f32_16x16x32_bf16 v[92:95], v[164:167], v[204:207], v[92:95]
	v_mfma_f32_16x16x32_bf16 v[84:87], v[156:159], v[212:215], v[84:87]
	v_mfma_f32_16x16x32_bf16 v[76:79], v[164:167], v[212:215], v[76:79]
	v_mfma_f32_16x16x32_bf16 v[112:115], v[168:171], v[184:187], 0
	v_mfma_f32_16x16x32_bf16 v[104:107], v[176:179], v[184:187], 0
	v_mfma_f32_16x16x32_bf16 v[96:99], v[168:171], v[192:195], 0
	v_mfma_f32_16x16x32_bf16 v[88:91], v[176:179], v[192:195], 0
	v_mfma_f32_16x16x32_bf16 v[80:83], v[168:171], v[200:203], 0
	v_mfma_f32_16x16x32_bf16 v[72:75], v[176:179], v[200:203], 0
	v_mfma_f32_16x16x32_bf16 v[68:71], v[168:171], v[208:211], 0
	v_mfma_f32_16x16x32_bf16 v[64:67], v[176:179], v[208:211], 0
	v_mfma_f32_16x16x32_bf16 v[112:115], v[172:175], v[188:191], v[112:115]
	v_mfma_f32_16x16x32_bf16 v[104:107], v[180:183], v[188:191], v[104:107]
	v_mfma_f32_16x16x32_bf16 v[96:99], v[172:175], v[196:199], v[96:99]
	v_mfma_f32_16x16x32_bf16 v[88:91], v[180:183], v[196:199], v[88:91]
	v_mfma_f32_16x16x32_bf16 v[80:83], v[172:175], v[204:207], v[80:83]
	v_mfma_f32_16x16x32_bf16 v[72:75], v[180:183], v[204:207], v[72:75]
	v_mfma_f32_16x16x32_bf16 v[68:71], v[172:175], v[212:215], v[68:71]
	v_mfma_f32_16x16x32_bf16 v[64:67], v[180:183], v[212:215], v[64:67]
	s_barrier
	ds_read_b128 v[184:187], v151 offset:16384
	ds_read_b128 v[188:191], v151 offset:17408
	s_add_i32 s58, s45, s31
	v_lshl_add_u64 v[146:147], s[26:27], 0, v[130:131]
	s_mov_b32 m0, s58
	s_nop 0
	global_load_lds_dwordx4 v[146:147], off
	ds_read_b128 v[192:195], v151 offset:18432
	ds_read_b128 v[196:199], v151 offset:19456
	s_add_i32 m0, s58, 0x2000
	s_add_u32 s58, s26, 0x100000
	v_lshl_add_u64 v[216:217], s[26:27], 0, v[134:135]
	s_addc_u32 s59, s27, 0
	s_add_i32 s60, s46, s31
	global_load_lds_dwordx4 v[216:217], off
	ds_read_b128 v[200:203], v151 offset:20480
	v_lshl_add_u64 v[218:219], s[58:59], 0, v[130:131]
	s_mov_b32 m0, s60
	v_lshl_add_u64 v[220:221], s[28:29], 0, v[132:133]
	global_load_lds_dwordx4 v[218:219], off
	ds_read_b128 v[204:207], v151 offset:21504
	v_lshl_add_u64 v[218:219], s[58:59], 0, v[134:135]
	s_add_i32 m0, s60, 0x2000
	s_nop 0
	global_load_lds_dwordx4 v[218:219], off
	ds_read_b128 v[208:211], v151 offset:22528
	v_lshl_add_u64 v[218:219], s[28:29], 0, v[128:129]
	s_mov_b32 m0, s23
	s_nop 0
	global_load_lds_dwordx4 v[218:219], off
	ds_read_b128 v[212:215], v151 offset:23552
	s_mov_b32 m0, s35
	s_nop 0
	global_load_lds_dwordx4 v[220:221], off
	s_waitcnt vmcnt(8)
	s_waitcnt lgkmcnt(0)
	s_barrier
	s_waitcnt lgkmcnt(0)
	v_mfma_f32_16x16x32_bf16 v[60:63], v[152:155], v[184:187], 0
	v_mfma_f32_16x16x32_bf16 v[56:59], v[160:163], v[184:187], 0
	v_mfma_f32_16x16x32_bf16 v[52:55], v[152:155], v[192:195], 0
	v_mfma_f32_16x16x32_bf16 v[44:47], v[160:163], v[192:195], 0
	v_mfma_f32_16x16x32_bf16 v[36:39], v[152:155], v[200:203], 0
	v_mfma_f32_16x16x32_bf16 v[28:31], v[160:163], v[200:203], 0
	v_mfma_f32_16x16x32_bf16 v[20:23], v[152:155], v[208:211], 0
	v_mfma_f32_16x16x32_bf16 v[12:15], v[160:163], v[208:211], 0
	v_mfma_f32_16x16x32_bf16 v[60:63], v[156:159], v[188:191], v[60:63]
	v_mfma_f32_16x16x32_bf16 v[56:59], v[164:167], v[188:191], v[56:59]
	v_mfma_f32_16x16x32_bf16 v[52:55], v[156:159], v[196:199], v[52:55]
	v_mfma_f32_16x16x32_bf16 v[44:47], v[164:167], v[196:199], v[44:47]
	v_mfma_f32_16x16x32_bf16 v[36:39], v[156:159], v[204:207], v[36:39]
	v_mfma_f32_16x16x32_bf16 v[28:31], v[164:167], v[204:207], v[28:31]
	v_mfma_f32_16x16x32_bf16 v[20:23], v[156:159], v[212:215], v[20:23]
	v_mfma_f32_16x16x32_bf16 v[12:15], v[164:167], v[212:215], v[12:15]
	v_mfma_f32_16x16x32_bf16 v[48:51], v[168:171], v[184:187], 0
	v_mfma_f32_16x16x32_bf16 v[40:43], v[176:179], v[184:187], 0
	v_mfma_f32_16x16x32_bf16 v[32:35], v[168:171], v[192:195], 0
	v_mfma_f32_16x16x32_bf16 v[24:27], v[176:179], v[192:195], 0
	v_mfma_f32_16x16x32_bf16 v[16:19], v[168:171], v[200:203], 0
	v_mfma_f32_16x16x32_bf16 v[8:11], v[176:179], v[200:203], 0
	v_mfma_f32_16x16x32_bf16 v[4:7], v[168:171], v[208:211], 0
	v_mfma_f32_16x16x32_bf16 v[0:3], v[176:179], v[208:211], 0
	v_mfma_f32_16x16x32_bf16 v[48:51], v[172:175], v[188:191], v[48:51]
	v_mfma_f32_16x16x32_bf16 v[40:43], v[180:183], v[188:191], v[40:43]
	v_mfma_f32_16x16x32_bf16 v[32:35], v[172:175], v[196:199], v[32:35]
	v_mfma_f32_16x16x32_bf16 v[24:27], v[180:183], v[196:199], v[24:27]
	v_mfma_f32_16x16x32_bf16 v[16:19], v[172:175], v[204:207], v[16:19]
	v_mfma_f32_16x16x32_bf16 v[8:11], v[180:183], v[204:207], v[8:11]
	v_mfma_f32_16x16x32_bf16 v[4:7], v[172:175], v[212:215], v[4:7]
	v_mfma_f32_16x16x32_bf16 v[0:3], v[180:183], v[212:215], v[0:3]
	s_barrier
	s_add_i32 s59, 0, 0x1c000
	s_add_i32 s58, 0, 0x18000
	v_add_u32_e32 v164, s58, v148
	v_add_u32_e32 v180, s59, v148
	ds_read_b128 v[152:155], v164
	ds_read_b128 v[156:159], v164 offset:1024
	ds_read_b128 v[160:163], v164 offset:2048
	ds_read_b128 v[164:167], v164 offset:3072
	ds_read_b128 v[168:171], v180
	ds_read_b128 v[172:175], v180 offset:1024
	ds_read_b128 v[176:179], v180 offset:2048
	ds_read_b128 v[180:183], v180 offset:3072
	s_add_u32 s28, s28, 0x100000
	s_addc_u32 s29, s29, 0
	s_mov_b32 m0, s36
	v_lshl_add_u64 v[222:223], s[28:29], 0, v[128:129]
	global_load_lds_dwordx4 v[222:223], off
	ds_read_b128 v[184:187], v151 offset:32768
	ds_read_b128 v[188:191], v151 offset:33792
	ds_read_b128 v[192:195], v151 offset:34816
	ds_read_b128 v[196:199], v151 offset:35840
	ds_read_b128 v[200:203], v151 offset:36864
	ds_read_b128 v[204:207], v151 offset:37888
	ds_read_b128 v[208:211], v151 offset:38912
	ds_read_b128 v[212:215], v151 offset:39936
	v_lshl_add_u64 v[222:223], s[28:29], 0, v[132:133]
	s_mov_b32 m0, s37
	s_nop 0
	global_load_lds_dwordx4 v[222:223], off
	s_waitcnt vmcnt(8)
	s_waitcnt lgkmcnt(0)
	s_barrier
	s_waitcnt lgkmcnt(0)
	v_mfma_f32_16x16x32_bf16 v[124:127], v[152:155], v[184:187], v[124:127]
	v_mfma_f32_16x16x32_bf16 v[120:123], v[160:163], v[184:187], v[120:123]
	v_mfma_f32_16x16x32_bf16 v[116:119], v[152:155], v[192:195], v[116:119]
	v_mfma_f32_16x16x32_bf16 v[108:111], v[160:163], v[192:195], v[108:111]
	v_mfma_f32_16x16x32_bf16 v[100:103], v[152:155], v[200:203], v[100:103]
	v_mfma_f32_16x16x32_bf16 v[92:95], v[160:163], v[200:203], v[92:95]
	v_mfma_f32_16x16x32_bf16 v[84:87], v[152:155], v[208:211], v[84:87]
	v_mfma_f32_16x16x32_bf16 v[76:79], v[160:163], v[208:211], v[76:79]
	v_mfma_f32_16x16x32_bf16 v[124:127], v[156:159], v[188:191], v[124:127]
	v_mfma_f32_16x16x32_bf16 v[120:123], v[164:167], v[188:191], v[120:123]
	v_mfma_f32_16x16x32_bf16 v[116:119], v[156:159], v[196:199], v[116:119]
	v_mfma_f32_16x16x32_bf16 v[108:111], v[164:167], v[196:199], v[108:111]
	v_mfma_f32_16x16x32_bf16 v[100:103], v[156:159], v[204:207], v[100:103]
	v_mfma_f32_16x16x32_bf16 v[92:95], v[164:167], v[204:207], v[92:95]
	v_mfma_f32_16x16x32_bf16 v[84:87], v[156:159], v[212:215], v[84:87]
	v_mfma_f32_16x16x32_bf16 v[76:79], v[164:167], v[212:215], v[76:79]
	v_mfma_f32_16x16x32_bf16 v[112:115], v[168:171], v[184:187], v[112:115]
	v_mfma_f32_16x16x32_bf16 v[104:107], v[176:179], v[184:187], v[104:107]
	v_mfma_f32_16x16x32_bf16 v[96:99], v[168:171], v[192:195], v[96:99]
	v_mfma_f32_16x16x32_bf16 v[88:91], v[176:179], v[192:195], v[88:91]
	v_mfma_f32_16x16x32_bf16 v[80:83], v[168:171], v[200:203], v[80:83]
	v_mfma_f32_16x16x32_bf16 v[72:75], v[176:179], v[200:203], v[72:75]
	v_mfma_f32_16x16x32_bf16 v[68:71], v[168:171], v[208:211], v[68:71]
	v_mfma_f32_16x16x32_bf16 v[64:67], v[176:179], v[208:211], v[64:67]
	v_mfma_f32_16x16x32_bf16 v[112:115], v[172:175], v[188:191], v[112:115]
	v_mfma_f32_16x16x32_bf16 v[104:107], v[180:183], v[188:191], v[104:107]
	v_mfma_f32_16x16x32_bf16 v[96:99], v[172:175], v[196:199], v[96:99]
	v_mfma_f32_16x16x32_bf16 v[88:91], v[180:183], v[196:199], v[88:91]
	v_mfma_f32_16x16x32_bf16 v[80:83], v[172:175], v[204:207], v[80:83]
	v_mfma_f32_16x16x32_bf16 v[72:75], v[180:183], v[204:207], v[72:75]
	v_mfma_f32_16x16x32_bf16 v[68:71], v[172:175], v[212:215], v[68:71]
	v_mfma_f32_16x16x32_bf16 v[64:67], v[180:183], v[212:215], v[64:67]
	s_barrier
	ds_read_b128 v[184:187], v151 offset:49152
	ds_read_b128 v[188:191], v151 offset:50176
	s_add_i32 s28, s58, s31
	v_lshl_add_u64 v[146:147], v[146:147], 0, s[12:13]
	s_mov_b32 m0, s28
	s_nop 0
	global_load_lds_dwordx4 v[146:147], off
	ds_read_b128 v[192:195], v151 offset:51200
	ds_read_b128 v[196:199], v151 offset:52224
	s_add_i32 m0, s28, 0x2000
	s_add_u32 s26, s26, 0x100080
	v_lshl_add_u64 v[146:147], v[216:217], 0, s[12:13]
	s_addc_u32 s27, s27, 0
	s_add_i32 s28, s59, s31
	global_load_lds_dwordx4 v[146:147], off
	ds_read_b128 v[200:203], v151 offset:53248
	v_lshl_add_u64 v[146:147], s[26:27], 0, v[130:131]
	s_mov_b32 m0, s28
	s_nop 0
	global_load_lds_dwordx4 v[146:147], off
	ds_read_b128 v[204:207], v151 offset:54272
	v_lshl_add_u64 v[146:147], s[26:27], 0, v[134:135]
	s_add_i32 m0, s28, 0x2000
	s_nop 0
	global_load_lds_dwordx4 v[146:147], off
	ds_read_b128 v[208:211], v151 offset:55296
	v_lshl_add_u64 v[146:147], v[218:219], 0, s[12:13]
	s_mov_b32 m0, s40
	s_nop 0
	global_load_lds_dwordx4 v[146:147], off
	ds_read_b128 v[212:215], v151 offset:56320
	v_lshl_add_u64 v[146:147], v[220:221], 0, s[12:13]
	s_mov_b32 m0, s41
	s_nop 0
	global_load_lds_dwordx4 v[146:147], off
	s_waitcnt vmcnt(8)
	s_waitcnt lgkmcnt(0)
	s_barrier
	s_waitcnt lgkmcnt(0)
	v_mfma_f32_16x16x32_bf16 v[60:63], v[152:155], v[184:187], v[60:63]
	v_mfma_f32_16x16x32_bf16 v[56:59], v[160:163], v[184:187], v[56:59]
	v_mfma_f32_16x16x32_bf16 v[52:55], v[152:155], v[192:195], v[52:55]
	v_mfma_f32_16x16x32_bf16 v[44:47], v[160:163], v[192:195], v[44:47]
	v_mfma_f32_16x16x32_bf16 v[36:39], v[152:155], v[200:203], v[36:39]
	v_mfma_f32_16x16x32_bf16 v[28:31], v[160:163], v[200:203], v[28:31]
	v_mfma_f32_16x16x32_bf16 v[20:23], v[152:155], v[208:211], v[20:23]
	v_mfma_f32_16x16x32_bf16 v[12:15], v[160:163], v[208:211], v[12:15]
	v_mfma_f32_16x16x32_bf16 v[60:63], v[156:159], v[188:191], v[60:63]
	v_mfma_f32_16x16x32_bf16 v[56:59], v[164:167], v[188:191], v[56:59]
	v_mfma_f32_16x16x32_bf16 v[52:55], v[156:159], v[196:199], v[52:55]
	v_mfma_f32_16x16x32_bf16 v[44:47], v[164:167], v[196:199], v[44:47]
	v_mfma_f32_16x16x32_bf16 v[36:39], v[156:159], v[204:207], v[36:39]
	v_mfma_f32_16x16x32_bf16 v[28:31], v[164:167], v[204:207], v[28:31]
	v_mfma_f32_16x16x32_bf16 v[20:23], v[156:159], v[212:215], v[20:23]
	v_mfma_f32_16x16x32_bf16 v[12:15], v[164:167], v[212:215], v[12:15]
	v_mfma_f32_16x16x32_bf16 v[48:51], v[168:171], v[184:187], v[48:51]
	v_mfma_f32_16x16x32_bf16 v[40:43], v[176:179], v[184:187], v[40:43]
	v_mfma_f32_16x16x32_bf16 v[32:35], v[168:171], v[192:195], v[32:35]
	v_mfma_f32_16x16x32_bf16 v[24:27], v[176:179], v[192:195], v[24:27]
	v_mfma_f32_16x16x32_bf16 v[16:19], v[168:171], v[200:203], v[16:19]
	v_mfma_f32_16x16x32_bf16 v[8:11], v[176:179], v[200:203], v[8:11]
	v_mfma_f32_16x16x32_bf16 v[4:7], v[168:171], v[208:211], v[4:7]
	v_mfma_f32_16x16x32_bf16 v[0:3], v[176:179], v[208:211], v[0:3]
	v_mfma_f32_16x16x32_bf16 v[48:51], v[172:175], v[188:191], v[48:51]
	v_mfma_f32_16x16x32_bf16 v[40:43], v[180:183], v[188:191], v[40:43]
	v_mfma_f32_16x16x32_bf16 v[32:35], v[172:175], v[196:199], v[32:35]
	v_mfma_f32_16x16x32_bf16 v[24:27], v[180:183], v[196:199], v[24:27]
	v_mfma_f32_16x16x32_bf16 v[16:19], v[172:175], v[204:207], v[16:19]
	v_mfma_f32_16x16x32_bf16 v[8:11], v[180:183], v[204:207], v[8:11]
	v_mfma_f32_16x16x32_bf16 v[4:7], v[172:175], v[212:215], v[4:7]
	v_mfma_f32_16x16x32_bf16 v[0:3], v[180:183], v[212:215], v[0:3]
	s_barrier
	s_add_i32 s57, s57, 2
	s_add_u32 s24, s24, 0x100
	s_addc_u32 s25, s25, 0
	s_add_u32 s55, s55, 0x100
	s_addc_u32 s56, s56, 0
	s_cmp_gt_u32 s57, 61
.LBB6_20:
	ds_read_b128 v[152:155], v149
	ds_read_b128 v[156:159], v149 offset:1024
	ds_read_b128 v[160:163], v149 offset:2048
	ds_read_b128 v[164:167], v149 offset:3072
	ds_read_b128 v[168:171], v150
	ds_read_b128 v[172:175], v150 offset:1024
	ds_read_b128 v[176:179], v150 offset:2048
	ds_read_b128 v[180:183], v150 offset:3072
	s_add_u32 s26, s24, 0xfff00080
	s_addc_u32 s27, s25, -1
	s_cmp_eq_u32 s57, 60
	s_cselect_b32 s29, s17, s27
	s_cselect_b32 s28, s53, s26
	s_cselect_b32 s27, s15, s56
	s_cselect_b32 s26, s54, s55
	v_lshl_add_u64 v[146:147], s[24:25], 0, v[138:139]
	s_add_i32 m0, s23, 0xc000
	s_nop 0
	global_load_lds_dwordx4 v[146:147], off
	ds_read_b128 v[184:187], v151
	ds_read_b128 v[188:191], v151 offset:1024
	ds_read_b128 v[192:195], v151 offset:2048
	ds_read_b128 v[196:199], v151 offset:3072
	ds_read_b128 v[200:203], v151 offset:4096
	ds_read_b128 v[204:207], v151 offset:5120
	ds_read_b128 v[208:211], v151 offset:6144
	ds_read_b128 v[212:215], v151 offset:7168
	v_lshl_add_u64 v[146:147], s[24:25], 0, v[140:141]
	s_add_i32 m0, s23, 0xe000
	s_nop 0
	global_load_lds_dwordx4 v[146:147], off
	s_waitcnt vmcnt(8)
	s_waitcnt lgkmcnt(0)
	s_barrier
	s_waitcnt lgkmcnt(0)
	v_mfma_f32_16x16x32_bf16 v[124:127], v[152:155], v[184:187], v[124:127]
	v_mfma_f32_16x16x32_bf16 v[120:123], v[160:163], v[184:187], v[120:123]
	v_mfma_f32_16x16x32_bf16 v[116:119], v[152:155], v[192:195], v[116:119]
	v_mfma_f32_16x16x32_bf16 v[108:111], v[160:163], v[192:195], v[108:111]
	v_mfma_f32_16x16x32_bf16 v[100:103], v[152:155], v[200:203], v[100:103]
	v_mfma_f32_16x16x32_bf16 v[92:95], v[160:163], v[200:203], v[92:95]
	v_mfma_f32_16x16x32_bf16 v[84:87], v[152:155], v[208:211], v[84:87]
	v_mfma_f32_16x16x32_bf16 v[76:79], v[160:163], v[208:211], v[76:79]
	v_mfma_f32_16x16x32_bf16 v[124:127], v[156:159], v[188:191], v[124:127]
	v_mfma_f32_16x16x32_bf16 v[120:123], v[164:167], v[188:191], v[120:123]
	v_mfma_f32_16x16x32_bf16 v[116:119], v[156:159], v[196:199], v[116:119]
	v_mfma_f32_16x16x32_bf16 v[108:111], v[164:167], v[196:199], v[108:111]
	v_mfma_f32_16x16x32_bf16 v[100:103], v[156:159], v[204:207], v[100:103]
	v_mfma_f32_16x16x32_bf16 v[92:95], v[164:167], v[204:207], v[92:95]
	v_mfma_f32_16x16x32_bf16 v[84:87], v[156:159], v[212:215], v[84:87]
	v_mfma_f32_16x16x32_bf16 v[76:79], v[164:167], v[212:215], v[76:79]
	v_mfma_f32_16x16x32_bf16 v[112:115], v[168:171], v[184:187], v[112:115]
	v_mfma_f32_16x16x32_bf16 v[104:107], v[176:179], v[184:187], v[104:107]
	v_mfma_f32_16x16x32_bf16 v[96:99], v[168:171], v[192:195], v[96:99]
	v_mfma_f32_16x16x32_bf16 v[88:91], v[176:179], v[192:195], v[88:91]
	v_mfma_f32_16x16x32_bf16 v[80:83], v[168:171], v[200:203], v[80:83]
	v_mfma_f32_16x16x32_bf16 v[72:75], v[176:179], v[200:203], v[72:75]
	v_mfma_f32_16x16x32_bf16 v[68:71], v[168:171], v[208:211], v[68:71]
	v_mfma_f32_16x16x32_bf16 v[64:67], v[176:179], v[208:211], v[64:67]
	v_mfma_f32_16x16x32_bf16 v[112:115], v[172:175], v[188:191], v[112:115]
	v_mfma_f32_16x16x32_bf16 v[104:107], v[180:183], v[188:191], v[104:107]
	v_mfma_f32_16x16x32_bf16 v[96:99], v[172:175], v[196:199], v[96:99]
	v_mfma_f32_16x16x32_bf16 v[88:91], v[180:183], v[196:199], v[88:91]
	v_mfma_f32_16x16x32_bf16 v[80:83], v[172:175], v[204:207], v[80:83]
	v_mfma_f32_16x16x32_bf16 v[72:75], v[180:183], v[204:207], v[72:75]
	v_mfma_f32_16x16x32_bf16 v[68:71], v[172:175], v[212:215], v[68:71]
	v_mfma_f32_16x16x32_bf16 v[64:67], v[180:183], v[212:215], v[64:67]
	s_barrier
	ds_read_b128 v[184:187], v151 offset:16384
	ds_read_b128 v[188:191], v151 offset:17408
	s_add_i32 s58, s45, s31
	v_lshl_add_u64 v[146:147], s[26:27], 0, v[130:131]
	s_mov_b32 m0, s58
	s_nop 0
	global_load_lds_dwordx4 v[146:147], off
	ds_read_b128 v[192:195], v151 offset:18432
	ds_read_b128 v[196:199], v151 offset:19456
	s_add_i32 m0, s58, 0x2000
	s_add_u32 s58, s26, 0x100000
	v_lshl_add_u64 v[216:217], s[26:27], 0, v[134:135]
	s_addc_u32 s59, s27, 0
	s_add_i32 s60, s46, s31
	global_load_lds_dwordx4 v[216:217], off
	ds_read_b128 v[200:203], v151 offset:20480
	v_lshl_add_u64 v[218:219], s[58:59], 0, v[130:131]
	s_mov_b32 m0, s60
	v_lshl_add_u64 v[220:221], s[28:29], 0, v[132:133]
	global_load_lds_dwordx4 v[218:219], off
	ds_read_b128 v[204:207], v151 offset:21504
	v_lshl_add_u64 v[218:219], s[58:59], 0, v[134:135]
	s_add_i32 m0, s60, 0x2000
	s_nop 0
	global_load_lds_dwordx4 v[218:219], off
	ds_read_b128 v[208:211], v151 offset:22528
	v_lshl_add_u64 v[218:219], s[28:29], 0, v[128:129]
	s_mov_b32 m0, s23
	s_nop 0
	global_load_lds_dwordx4 v[218:219], off
	ds_read_b128 v[212:215], v151 offset:23552
	s_mov_b32 m0, s35
	s_nop 0
	global_load_lds_dwordx4 v[220:221], off
	s_waitcnt vmcnt(8)
	s_waitcnt lgkmcnt(0)
	s_barrier
	s_waitcnt lgkmcnt(0)
	v_mfma_f32_16x16x32_bf16 v[60:63], v[152:155], v[184:187], v[60:63]
	v_mfma_f32_16x16x32_bf16 v[56:59], v[160:163], v[184:187], v[56:59]
	v_mfma_f32_16x16x32_bf16 v[52:55], v[152:155], v[192:195], v[52:55]
	v_mfma_f32_16x16x32_bf16 v[44:47], v[160:163], v[192:195], v[44:47]
	v_mfma_f32_16x16x32_bf16 v[36:39], v[152:155], v[200:203], v[36:39]
	v_mfma_f32_16x16x32_bf16 v[28:31], v[160:163], v[200:203], v[28:31]
	v_mfma_f32_16x16x32_bf16 v[20:23], v[152:155], v[208:211], v[20:23]
	v_mfma_f32_16x16x32_bf16 v[12:15], v[160:163], v[208:211], v[12:15]
	v_mfma_f32_16x16x32_bf16 v[60:63], v[156:159], v[188:191], v[60:63]
	v_mfma_f32_16x16x32_bf16 v[56:59], v[164:167], v[188:191], v[56:59]
	v_mfma_f32_16x16x32_bf16 v[52:55], v[156:159], v[196:199], v[52:55]
	v_mfma_f32_16x16x32_bf16 v[44:47], v[164:167], v[196:199], v[44:47]
	v_mfma_f32_16x16x32_bf16 v[36:39], v[156:159], v[204:207], v[36:39]
	v_mfma_f32_16x16x32_bf16 v[28:31], v[164:167], v[204:207], v[28:31]
	v_mfma_f32_16x16x32_bf16 v[20:23], v[156:159], v[212:215], v[20:23]
	v_mfma_f32_16x16x32_bf16 v[12:15], v[164:167], v[212:215], v[12:15]
	v_mfma_f32_16x16x32_bf16 v[48:51], v[168:171], v[184:187], v[48:51]
	v_mfma_f32_16x16x32_bf16 v[40:43], v[176:179], v[184:187], v[40:43]
	v_mfma_f32_16x16x32_bf16 v[32:35], v[168:171], v[192:195], v[32:35]
	v_mfma_f32_16x16x32_bf16 v[24:27], v[176:179], v[192:195], v[24:27]
	v_mfma_f32_16x16x32_bf16 v[16:19], v[168:171], v[200:203], v[16:19]
	v_mfma_f32_16x16x32_bf16 v[8:11], v[176:179], v[200:203], v[8:11]
	v_mfma_f32_16x16x32_bf16 v[4:7], v[168:171], v[208:211], v[4:7]
	v_mfma_f32_16x16x32_bf16 v[0:3], v[176:179], v[208:211], v[0:3]
	v_mfma_f32_16x16x32_bf16 v[48:51], v[172:175], v[188:191], v[48:51]
	v_mfma_f32_16x16x32_bf16 v[40:43], v[180:183], v[188:191], v[40:43]
	v_mfma_f32_16x16x32_bf16 v[32:35], v[172:175], v[196:199], v[32:35]
	v_mfma_f32_16x16x32_bf16 v[24:27], v[180:183], v[196:199], v[24:27]
	v_mfma_f32_16x16x32_bf16 v[16:19], v[172:175], v[204:207], v[16:19]
	v_mfma_f32_16x16x32_bf16 v[8:11], v[180:183], v[204:207], v[8:11]
	v_mfma_f32_16x16x32_bf16 v[4:7], v[172:175], v[212:215], v[4:7]
	v_mfma_f32_16x16x32_bf16 v[0:3], v[180:183], v[212:215], v[0:3]
	s_barrier
	s_add_i32 s59, 0, 0x1c000
	s_add_i32 s58, 0, 0x18000
	v_add_u32_e32 v164, s58, v148
	v_add_u32_e32 v180, s59, v148
	ds_read_b128 v[152:155], v164
	ds_read_b128 v[156:159], v164 offset:1024
	ds_read_b128 v[160:163], v164 offset:2048
	ds_read_b128 v[164:167], v164 offset:3072
	ds_read_b128 v[168:171], v180
	ds_read_b128 v[172:175], v180 offset:1024
	ds_read_b128 v[176:179], v180 offset:2048
	ds_read_b128 v[180:183], v180 offset:3072
	s_add_u32 s28, s28, 0x100000
	s_addc_u32 s29, s29, 0
	s_mov_b32 m0, s36
	v_lshl_add_u64 v[222:223], s[28:29], 0, v[128:129]
	global_load_lds_dwordx4 v[222:223], off
	ds_read_b128 v[184:187], v151 offset:32768
	ds_read_b128 v[188:191], v151 offset:33792
	ds_read_b128 v[192:195], v151 offset:34816
	ds_read_b128 v[196:199], v151 offset:35840
	ds_read_b128 v[200:203], v151 offset:36864
	ds_read_b128 v[204:207], v151 offset:37888
	ds_read_b128 v[208:211], v151 offset:38912
	ds_read_b128 v[212:215], v151 offset:39936
	v_lshl_add_u64 v[222:223], s[28:29], 0, v[132:133]
	s_mov_b32 m0, s37
	s_nop 0
	global_load_lds_dwordx4 v[222:223], off
	s_waitcnt vmcnt(8)
	s_waitcnt lgkmcnt(0)
	s_barrier
	s_waitcnt lgkmcnt(0)
	v_mfma_f32_16x16x32_bf16 v[124:127], v[152:155], v[184:187], v[124:127]
	v_mfma_f32_16x16x32_bf16 v[120:123], v[160:163], v[184:187], v[120:123]
	v_mfma_f32_16x16x32_bf16 v[116:119], v[152:155], v[192:195], v[116:119]
	v_mfma_f32_16x16x32_bf16 v[108:111], v[160:163], v[192:195], v[108:111]
	v_mfma_f32_16x16x32_bf16 v[100:103], v[152:155], v[200:203], v[100:103]
	v_mfma_f32_16x16x32_bf16 v[92:95], v[160:163], v[200:203], v[92:95]
	v_mfma_f32_16x16x32_bf16 v[84:87], v[152:155], v[208:211], v[84:87]
	v_mfma_f32_16x16x32_bf16 v[76:79], v[160:163], v[208:211], v[76:79]
	v_mfma_f32_16x16x32_bf16 v[124:127], v[156:159], v[188:191], v[124:127]
	v_mfma_f32_16x16x32_bf16 v[120:123], v[164:167], v[188:191], v[120:123]
	v_mfma_f32_16x16x32_bf16 v[116:119], v[156:159], v[196:199], v[116:119]
	v_mfma_f32_16x16x32_bf16 v[108:111], v[164:167], v[196:199], v[108:111]
	v_mfma_f32_16x16x32_bf16 v[100:103], v[156:159], v[204:207], v[100:103]
	v_mfma_f32_16x16x32_bf16 v[92:95], v[164:167], v[204:207], v[92:95]
	v_mfma_f32_16x16x32_bf16 v[84:87], v[156:159], v[212:215], v[84:87]
	v_mfma_f32_16x16x32_bf16 v[76:79], v[164:167], v[212:215], v[76:79]
	v_mfma_f32_16x16x32_bf16 v[112:115], v[168:171], v[184:187], v[112:115]
	v_mfma_f32_16x16x32_bf16 v[104:107], v[176:179], v[184:187], v[104:107]
	v_mfma_f32_16x16x32_bf16 v[96:99], v[168:171], v[192:195], v[96:99]
	v_mfma_f32_16x16x32_bf16 v[88:91], v[176:179], v[192:195], v[88:91]
	v_mfma_f32_16x16x32_bf16 v[80:83], v[168:171], v[200:203], v[80:83]
	v_mfma_f32_16x16x32_bf16 v[72:75], v[176:179], v[200:203], v[72:75]
	v_mfma_f32_16x16x32_bf16 v[68:71], v[168:171], v[208:211], v[68:71]
	v_mfma_f32_16x16x32_bf16 v[64:67], v[176:179], v[208:211], v[64:67]
	v_mfma_f32_16x16x32_bf16 v[112:115], v[172:175], v[188:191], v[112:115]
	v_mfma_f32_16x16x32_bf16 v[104:107], v[180:183], v[188:191], v[104:107]
	v_mfma_f32_16x16x32_bf16 v[96:99], v[172:175], v[196:199], v[96:99]
	v_mfma_f32_16x16x32_bf16 v[88:91], v[180:183], v[196:199], v[88:91]
	v_mfma_f32_16x16x32_bf16 v[80:83], v[172:175], v[204:207], v[80:83]
	v_mfma_f32_16x16x32_bf16 v[72:75], v[180:183], v[204:207], v[72:75]
	v_mfma_f32_16x16x32_bf16 v[68:71], v[172:175], v[212:215], v[68:71]
	v_mfma_f32_16x16x32_bf16 v[64:67], v[180:183], v[212:215], v[64:67]
	s_barrier
	ds_read_b128 v[184:187], v151 offset:49152
	ds_read_b128 v[188:191], v151 offset:50176
	s_add_i32 s28, s58, s31
	v_lshl_add_u64 v[146:147], v[146:147], 0, s[12:13]
	s_mov_b32 m0, s28
	s_nop 0
	global_load_lds_dwordx4 v[146:147], off
	ds_read_b128 v[192:195], v151 offset:51200
	ds_read_b128 v[196:199], v151 offset:52224
	s_add_i32 m0, s28, 0x2000
	s_add_u32 s26, s26, 0x100080
	v_lshl_add_u64 v[146:147], v[216:217], 0, s[12:13]
	s_addc_u32 s27, s27, 0
	s_add_i32 s28, s59, s31
	global_load_lds_dwordx4 v[146:147], off
	ds_read_b128 v[200:203], v151 offset:53248
	v_lshl_add_u64 v[146:147], s[26:27], 0, v[130:131]
	s_mov_b32 m0, s28
	s_nop 0
	global_load_lds_dwordx4 v[146:147], off
	ds_read_b128 v[204:207], v151 offset:54272
	v_lshl_add_u64 v[146:147], s[26:27], 0, v[134:135]
	s_add_i32 m0, s28, 0x2000
	s_nop 0
	global_load_lds_dwordx4 v[146:147], off
	ds_read_b128 v[208:211], v151 offset:55296
	v_lshl_add_u64 v[146:147], v[218:219], 0, s[12:13]
	s_mov_b32 m0, s40
	s_nop 0
	global_load_lds_dwordx4 v[146:147], off
	ds_read_b128 v[212:215], v151 offset:56320
	v_lshl_add_u64 v[146:147], v[220:221], 0, s[12:13]
	s_mov_b32 m0, s41
	s_nop 0
	global_load_lds_dwordx4 v[146:147], off
	s_waitcnt vmcnt(8)
	s_waitcnt lgkmcnt(0)
	s_barrier
	s_waitcnt lgkmcnt(0)
	v_mfma_f32_16x16x32_bf16 v[60:63], v[152:155], v[184:187], v[60:63]
	v_mfma_f32_16x16x32_bf16 v[56:59], v[160:163], v[184:187], v[56:59]
	v_mfma_f32_16x16x32_bf16 v[52:55], v[152:155], v[192:195], v[52:55]
	v_mfma_f32_16x16x32_bf16 v[44:47], v[160:163], v[192:195], v[44:47]
	v_mfma_f32_16x16x32_bf16 v[36:39], v[152:155], v[200:203], v[36:39]
	v_mfma_f32_16x16x32_bf16 v[28:31], v[160:163], v[200:203], v[28:31]
	v_mfma_f32_16x16x32_bf16 v[20:23], v[152:155], v[208:211], v[20:23]
	v_mfma_f32_16x16x32_bf16 v[12:15], v[160:163], v[208:211], v[12:15]
	v_mfma_f32_16x16x32_bf16 v[60:63], v[156:159], v[188:191], v[60:63]
	v_mfma_f32_16x16x32_bf16 v[56:59], v[164:167], v[188:191], v[56:59]
	v_mfma_f32_16x16x32_bf16 v[52:55], v[156:159], v[196:199], v[52:55]
	v_mfma_f32_16x16x32_bf16 v[44:47], v[164:167], v[196:199], v[44:47]
	v_mfma_f32_16x16x32_bf16 v[36:39], v[156:159], v[204:207], v[36:39]
	v_mfma_f32_16x16x32_bf16 v[28:31], v[164:167], v[204:207], v[28:31]
	v_mfma_f32_16x16x32_bf16 v[20:23], v[156:159], v[212:215], v[20:23]
	v_mfma_f32_16x16x32_bf16 v[12:15], v[164:167], v[212:215], v[12:15]
	v_mfma_f32_16x16x32_bf16 v[48:51], v[168:171], v[184:187], v[48:51]
	v_mfma_f32_16x16x32_bf16 v[40:43], v[176:179], v[184:187], v[40:43]
	v_mfma_f32_16x16x32_bf16 v[32:35], v[168:171], v[192:195], v[32:35]
	v_mfma_f32_16x16x32_bf16 v[24:27], v[176:179], v[192:195], v[24:27]
	v_mfma_f32_16x16x32_bf16 v[16:19], v[168:171], v[200:203], v[16:19]
	v_mfma_f32_16x16x32_bf16 v[8:11], v[176:179], v[200:203], v[8:11]
	v_mfma_f32_16x16x32_bf16 v[4:7], v[168:171], v[208:211], v[4:7]
	v_mfma_f32_16x16x32_bf16 v[0:3], v[176:179], v[208:211], v[0:3]
	v_mfma_f32_16x16x32_bf16 v[48:51], v[172:175], v[188:191], v[48:51]
	v_mfma_f32_16x16x32_bf16 v[40:43], v[180:183], v[188:191], v[40:43]
	v_mfma_f32_16x16x32_bf16 v[32:35], v[172:175], v[196:199], v[32:35]
	v_mfma_f32_16x16x32_bf16 v[24:27], v[180:183], v[196:199], v[24:27]
	v_mfma_f32_16x16x32_bf16 v[16:19], v[172:175], v[204:207], v[16:19]
	v_mfma_f32_16x16x32_bf16 v[8:11], v[180:183], v[204:207], v[8:11]
	v_mfma_f32_16x16x32_bf16 v[4:7], v[172:175], v[212:215], v[4:7]
	v_mfma_f32_16x16x32_bf16 v[0:3], v[180:183], v[212:215], v[0:3]
	s_barrier
	s_add_i32 s57, s57, 2
	s_add_u32 s24, s24, 0x100
	s_addc_u32 s25, s25, 0
	s_add_u32 s55, s55, 0x100
	s_addc_u32 s56, s56, 0
	s_cmp_gt_u32 s57, 61
	s_cbranch_scc0 .LBB6_20
	s_mov_b64 vcc, s[0:1]
	s_cbranch_vccz .LBB6_23
	s_barrier

.LBB8_11:
	s_ashr_i32 s19, s18, 31
	v_cmp_lt_i64_e32 vcc, s[0:1], v[144:145]
	s_lshl_b64 s[0:1], s[18:19], 19
	s_add_u32 s20, s33, s0
	s_addc_u32 s21, s36, s1
	s_and_b64 s[0:1], vcc, exec
	s_cselect_b32 s5, s21, s29
	s_cselect_b32 s19, s20, s28
	s_ashr_i32 s11, s10, 31
	s_lshl_b64 s[0:1], s[10:11], 19
	s_add_u32 s22, s37, s0
	s_addc_u32 s23, s38, s1
	s_and_b64 s[0:1], vcc, exec
	s_cselect_b32 s11, s23, s27
	s_cselect_b32 s25, s22, s26
	s_add_u32 s34, s26, 0x100
	s_addc_u32 s35, s27, 0
	s_add_u32 s26, s28, 0x40080
	s_addc_u32 s27, s29, 0
	s_mov_b32 s65, -2
	ds_read_b128 v[148:151], v153
	ds_read_b128 v[156:159], v153 offset:1024
	ds_read_b128 v[160:163], v153 offset:2048
	ds_read_b128 v[164:167], v153 offset:3072
	ds_read_b128 v[168:171], v154
	ds_read_b128 v[172:175], v154 offset:1024
	ds_read_b128 v[176:179], v154 offset:2048
	ds_read_b128 v[180:183], v154 offset:3072
	s_add_u32 s28, s26, 0xfffc0080
	s_addc_u32 s29, s27, -1
	s_cmp_eq_u32 s65, 12
	s_cselect_b32 s31, s5, s29
	s_cselect_b32 s30, s19, s28
	s_cselect_b32 s29, s11, s35
	s_cselect_b32 s28, s25, s34
	v_lshl_add_u64 v[216:217], s[26:27], 0, v[142:143]
	s_add_i32 m0, s40, 0xc000
	s_nop 0
	global_load_lds_dwordx4 v[216:217], off
	ds_read_b128 v[184:187], v155
	ds_read_b128 v[188:191], v155 offset:1024
	ds_read_b128 v[192:195], v155 offset:2048
	ds_read_b128 v[196:199], v155 offset:3072
	ds_read_b128 v[200:203], v155 offset:4096
	ds_read_b128 v[204:207], v155 offset:5120
	ds_read_b128 v[208:211], v155 offset:6144
	ds_read_b128 v[212:215], v155 offset:7168
	v_lshl_add_u64 v[216:217], s[26:27], 0, v[140:141]
	s_add_i32 m0, s40, 0xe000
	s_nop 0
	global_load_lds_dwordx4 v[216:217], off
	s_waitcnt vmcnt(8)
	s_waitcnt lgkmcnt(0)
	s_barrier
	s_waitcnt lgkmcnt(0)
	v_mfma_f32_16x16x32_bf16 v[124:127], v[148:151], v[184:187], 0
	v_mfma_f32_16x16x32_bf16 v[120:123], v[160:163], v[184:187], 0
	v_mfma_f32_16x16x32_bf16 v[108:111], v[148:151], v[192:195], 0
	v_mfma_f32_16x16x32_bf16 v[104:107], v[160:163], v[192:195], 0
	v_mfma_f32_16x16x32_bf16 v[92:95], v[148:151], v[200:203], 0
	v_mfma_f32_16x16x32_bf16 v[88:91], v[160:163], v[200:203], 0
	v_mfma_f32_16x16x32_bf16 v[76:79], v[148:151], v[208:211], 0
	v_mfma_f32_16x16x32_bf16 v[72:75], v[160:163], v[208:211], 0
	v_mfma_f32_16x16x32_bf16 v[124:127], v[156:159], v[188:191], v[124:127]
	v_mfma_f32_16x16x32_bf16 v[120:123], v[164:167], v[188:191], v[120:123]
	v_mfma_f32_16x16x32_bf16 v[108:111], v[156:159], v[196:199], v[108:111]
	v_mfma_f32_16x16x32_bf16 v[104:107], v[164:167], v[196:199], v[104:107]
	v_mfma_f32_16x16x32_bf16 v[92:95], v[156:159], v[204:207], v[92:95]
	v_mfma_f32_16x16x32_bf16 v[88:91], v[164:167], v[204:207], v[88:91]
	v_mfma_f32_16x16x32_bf16 v[76:79], v[156:159], v[212:215], v[76:79]
	v_mfma_f32_16x16x32_bf16 v[72:75], v[164:167], v[212:215], v[72:75]
	v_mfma_f32_16x16x32_bf16 v[116:119], v[168:171], v[184:187], 0
	v_mfma_f32_16x16x32_bf16 v[112:115], v[176:179], v[184:187], 0
	v_mfma_f32_16x16x32_bf16 v[100:103], v[168:171], v[192:195], 0
	v_mfma_f32_16x16x32_bf16 v[96:99], v[176:179], v[192:195], 0
	v_mfma_f32_16x16x32_bf16 v[84:87], v[168:171], v[200:203], 0
	v_mfma_f32_16x16x32_bf16 v[80:83], v[176:179], v[200:203], 0
	v_mfma_f32_16x16x32_bf16 v[68:71], v[168:171], v[208:211], 0
	v_mfma_f32_16x16x32_bf16 v[64:67], v[176:179], v[208:211], 0
	v_mfma_f32_16x16x32_bf16 v[116:119], v[172:175], v[188:191], v[116:119]
	v_mfma_f32_16x16x32_bf16 v[112:115], v[180:183], v[188:191], v[112:115]
	v_mfma_f32_16x16x32_bf16 v[100:103], v[172:175], v[196:199], v[100:103]
	v_mfma_f32_16x16x32_bf16 v[96:99], v[180:183], v[196:199], v[96:99]
	v_mfma_f32_16x16x32_bf16 v[84:87], v[172:175], v[204:207], v[84:87]
	v_mfma_f32_16x16x32_bf16 v[80:83], v[180:183], v[204:207], v[80:83]
	v_mfma_f32_16x16x32_bf16 v[68:71], v[172:175], v[212:215], v[68:71]
	v_mfma_f32_16x16x32_bf16 v[64:67], v[180:183], v[212:215], v[64:67]
	s_barrier
	ds_read_b128 v[184:187], v155 offset:16384
	ds_read_b128 v[188:191], v155 offset:17408
	s_add_i32 s66, s52, s39
	v_lshl_add_u64 v[216:217], s[28:29], 0, v[130:131]
	s_mov_b32 m0, s66
	s_nop 0
	global_load_lds_dwordx4 v[216:217], off
	ds_read_b128 v[192:195], v155 offset:18432
	ds_read_b128 v[196:199], v155 offset:19456
	s_add_i32 m0, s66, 0x2000
	s_add_u32 s66, s28, 0x40000
	v_lshl_add_u64 v[218:219], s[28:29], 0, v[134:135]
	s_addc_u32 s67, s29, 0
	s_add_i32 s68, s53, s39
	global_load_lds_dwordx4 v[218:219], off
	ds_read_b128 v[200:203], v155 offset:20480
	v_lshl_add_u64 v[220:221], s[66:67], 0, v[130:131]
	s_mov_b32 m0, s68
	v_lshl_add_u64 v[222:223], s[30:31], 0, v[132:133]
	global_load_lds_dwordx4 v[220:221], off
	ds_read_b128 v[204:207], v155 offset:21504
	v_lshl_add_u64 v[220:221], s[66:67], 0, v[134:135]
	s_add_i32 m0, s68, 0x2000
	s_nop 0
	global_load_lds_dwordx4 v[220:221], off
	ds_read_b128 v[208:211], v155 offset:22528
	v_lshl_add_u64 v[220:221], s[30:31], 0, v[128:129]
	s_mov_b32 m0, s40
	s_nop 0
	global_load_lds_dwordx4 v[220:221], off
	ds_read_b128 v[212:215], v155 offset:23552
	s_mov_b32 m0, s41
	s_nop 0
	global_load_lds_dwordx4 v[222:223], off
	s_waitcnt vmcnt(8)
	s_waitcnt lgkmcnt(0)
	s_barrier
	s_waitcnt lgkmcnt(0)
	v_mfma_f32_16x16x32_bf16 v[60:63], v[148:151], v[184:187], 0
	v_mfma_f32_16x16x32_bf16 v[56:59], v[160:163], v[184:187], 0
	v_mfma_f32_16x16x32_bf16 v[44:47], v[148:151], v[192:195], 0
	v_mfma_f32_16x16x32_bf16 v[40:43], v[160:163], v[192:195], 0
	v_mfma_f32_16x16x32_bf16 v[28:31], v[148:151], v[200:203], 0
	v_mfma_f32_16x16x32_bf16 v[24:27], v[160:163], v[200:203], 0
	v_mfma_f32_16x16x32_bf16 v[12:15], v[148:151], v[208:211], 0
	v_mfma_f32_16x16x32_bf16 v[8:11], v[160:163], v[208:211], 0
	v_mfma_f32_16x16x32_bf16 v[60:63], v[156:159], v[188:191], v[60:63]
	v_mfma_f32_16x16x32_bf16 v[56:59], v[164:167], v[188:191], v[56:59]
	v_mfma_f32_16x16x32_bf16 v[44:47], v[156:159], v[196:199], v[44:47]
	v_mfma_f32_16x16x32_bf16 v[40:43], v[164:167], v[196:199], v[40:43]
	v_mfma_f32_16x16x32_bf16 v[28:31], v[156:159], v[204:207], v[28:31]
	v_mfma_f32_16x16x32_bf16 v[24:27], v[164:167], v[204:207], v[24:27]
	v_mfma_f32_16x16x32_bf16 v[12:15], v[156:159], v[212:215], v[12:15]
	v_mfma_f32_16x16x32_bf16 v[8:11], v[164:167], v[212:215], v[8:11]
	v_mfma_f32_16x16x32_bf16 v[52:55], v[168:171], v[184:187], 0
	v_mfma_f32_16x16x32_bf16 v[48:51], v[176:179], v[184:187], 0
	v_mfma_f32_16x16x32_bf16 v[36:39], v[168:171], v[192:195], 0
	v_mfma_f32_16x16x32_bf16 v[32:35], v[176:179], v[192:195], 0
	v_mfma_f32_16x16x32_bf16 v[20:23], v[168:171], v[200:203], 0
	v_mfma_f32_16x16x32_bf16 v[16:19], v[176:179], v[200:203], 0
	v_mfma_f32_16x16x32_bf16 v[4:7], v[168:171], v[208:211], 0
	v_mfma_f32_16x16x32_bf16 v[0:3], v[176:179], v[208:211], 0
	v_mfma_f32_16x16x32_bf16 v[52:55], v[172:175], v[188:191], v[52:55]
	v_mfma_f32_16x16x32_bf16 v[48:51], v[180:183], v[188:191], v[48:51]
	v_mfma_f32_16x16x32_bf16 v[36:39], v[172:175], v[196:199], v[36:39]
	v_mfma_f32_16x16x32_bf16 v[32:35], v[180:183], v[196:199], v[32:35]
	v_mfma_f32_16x16x32_bf16 v[20:23], v[172:175], v[204:207], v[20:23]
	v_mfma_f32_16x16x32_bf16 v[16:19], v[180:183], v[204:207], v[16:19]
	v_mfma_f32_16x16x32_bf16 v[4:7], v[172:175], v[212:215], v[4:7]
	v_mfma_f32_16x16x32_bf16 v[0:3], v[180:183], v[212:215], v[0:3]
	s_barrier
	s_add_i32 s67, 0, 0x1c000
	s_add_i32 s66, 0, 0x18000
	v_add_u32_e32 v164, s66, v152
	v_add_u32_e32 v180, s67, v152
	ds_read_b128 v[148:151], v164
	ds_read_b128 v[156:159], v164 offset:1024
	ds_read_b128 v[160:163], v164 offset:2048
	ds_read_b128 v[164:167], v164 offset:3072
	ds_read_b128 v[168:171], v180
	ds_read_b128 v[172:175], v180 offset:1024
	ds_read_b128 v[176:179], v180 offset:2048
	ds_read_b128 v[180:183], v180 offset:3072
	s_add_u32 s30, s30, 0x40000
	s_addc_u32 s31, s31, 0
	s_mov_b32 m0, s42
	v_lshl_add_u64 v[224:225], s[30:31], 0, v[128:129]
	global_load_lds_dwordx4 v[224:225], off
	ds_read_b128 v[184:187], v155 offset:32768
	ds_read_b128 v[188:191], v155 offset:33792
	ds_read_b128 v[192:195], v155 offset:34816
	ds_read_b128 v[196:199], v155 offset:35840
	ds_read_b128 v[200:203], v155 offset:36864
	ds_read_b128 v[204:207], v155 offset:37888
	ds_read_b128 v[208:211], v155 offset:38912
	ds_read_b128 v[212:215], v155 offset:39936
	v_lshl_add_u64 v[224:225], s[30:31], 0, v[132:133]
	s_mov_b32 m0, s43
	s_nop 0
	global_load_lds_dwordx4 v[224:225], off
	s_waitcnt vmcnt(8)
	s_waitcnt lgkmcnt(0)
	s_barrier
	s_waitcnt lgkmcnt(0)
	v_mfma_f32_16x16x32_bf16 v[124:127], v[148:151], v[184:187], v[124:127]
	v_mfma_f32_16x16x32_bf16 v[120:123], v[160:163], v[184:187], v[120:123]
	v_mfma_f32_16x16x32_bf16 v[108:111], v[148:151], v[192:195], v[108:111]
	v_mfma_f32_16x16x32_bf16 v[104:107], v[160:163], v[192:195], v[104:107]
	v_mfma_f32_16x16x32_bf16 v[92:95], v[148:151], v[200:203], v[92:95]
	v_mfma_f32_16x16x32_bf16 v[88:91], v[160:163], v[200:203], v[88:91]
	v_mfma_f32_16x16x32_bf16 v[76:79], v[148:151], v[208:211], v[76:79]
	v_mfma_f32_16x16x32_bf16 v[72:75], v[160:163], v[208:211], v[72:75]
	v_mfma_f32_16x16x32_bf16 v[124:127], v[156:159], v[188:191], v[124:127]
	v_mfma_f32_16x16x32_bf16 v[120:123], v[164:167], v[188:191], v[120:123]
	v_mfma_f32_16x16x32_bf16 v[108:111], v[156:159], v[196:199], v[108:111]
	v_mfma_f32_16x16x32_bf16 v[104:107], v[164:167], v[196:199], v[104:107]
	v_mfma_f32_16x16x32_bf16 v[92:95], v[156:159], v[204:207], v[92:95]
	v_mfma_f32_16x16x32_bf16 v[88:91], v[164:167], v[204:207], v[88:91]
	v_mfma_f32_16x16x32_bf16 v[76:79], v[156:159], v[212:215], v[76:79]
	v_mfma_f32_16x16x32_bf16 v[72:75], v[164:167], v[212:215], v[72:75]
	v_mfma_f32_16x16x32_bf16 v[116:119], v[168:171], v[184:187], v[116:119]
	v_mfma_f32_16x16x32_bf16 v[112:115], v[176:179], v[184:187], v[112:115]
	v_mfma_f32_16x16x32_bf16 v[100:103], v[168:171], v[192:195], v[100:103]
	v_mfma_f32_16x16x32_bf16 v[96:99], v[176:179], v[192:195], v[96:99]
	v_mfma_f32_16x16x32_bf16 v[84:87], v[168:171], v[200:203], v[84:87]
	v_mfma_f32_16x16x32_bf16 v[80:83], v[176:179], v[200:203], v[80:83]
	v_mfma_f32_16x16x32_bf16 v[68:71], v[168:171], v[208:211], v[68:71]
	v_mfma_f32_16x16x32_bf16 v[64:67], v[176:179], v[208:211], v[64:67]
	v_mfma_f32_16x16x32_bf16 v[116:119], v[172:175], v[188:191], v[116:119]
	v_mfma_f32_16x16x32_bf16 v[112:115], v[180:183], v[188:191], v[112:115]
	v_mfma_f32_16x16x32_bf16 v[100:103], v[172:175], v[196:199], v[100:103]
	v_mfma_f32_16x16x32_bf16 v[96:99], v[180:183], v[196:199], v[96:99]
	v_mfma_f32_16x16x32_bf16 v[84:87], v[172:175], v[204:207], v[84:87]
	v_mfma_f32_16x16x32_bf16 v[80:83], v[180:183], v[204:207], v[80:83]
	v_mfma_f32_16x16x32_bf16 v[68:71], v[172:175], v[212:215], v[68:71]
	v_mfma_f32_16x16x32_bf16 v[64:67], v[180:183], v[212:215], v[64:67]
	s_barrier
	ds_read_b128 v[184:187], v155 offset:49152
	ds_read_b128 v[188:191], v155 offset:50176
	s_add_i32 s30, s66, s39
	v_lshl_add_u64 v[216:217], v[216:217], 0, s[14:15]
	s_mov_b32 m0, s30
	s_nop 0
	global_load_lds_dwordx4 v[216:217], off
	ds_read_b128 v[192:195], v155 offset:51200
	ds_read_b128 v[196:199], v155 offset:52224
	s_add_i32 m0, s30, 0x2000
	s_add_u32 s28, s28, 0x40080
	v_lshl_add_u64 v[216:217], v[218:219], 0, s[14:15]
	s_addc_u32 s29, s29, 0
	s_add_i32 s30, s67, s39
	global_load_lds_dwordx4 v[216:217], off
	ds_read_b128 v[200:203], v155 offset:53248
	v_lshl_add_u64 v[216:217], s[28:29], 0, v[130:131]
	s_mov_b32 m0, s30
	s_nop 0
	global_load_lds_dwordx4 v[216:217], off
	ds_read_b128 v[204:207], v155 offset:54272
	v_lshl_add_u64 v[216:217], s[28:29], 0, v[134:135]
	s_add_i32 m0, s30, 0x2000
	s_nop 0
	global_load_lds_dwordx4 v[216:217], off
	ds_read_b128 v[208:211], v155 offset:55296
	v_lshl_add_u64 v[216:217], v[220:221], 0, s[14:15]
	s_mov_b32 m0, s45
	s_nop 0
	global_load_lds_dwordx4 v[216:217], off
	ds_read_b128 v[212:215], v155 offset:56320
	v_lshl_add_u64 v[216:217], v[222:223], 0, s[14:15]
	s_mov_b32 m0, s46
	s_nop 0
	global_load_lds_dwordx4 v[216:217], off
	s_waitcnt vmcnt(8)
	s_waitcnt lgkmcnt(0)
	s_barrier
	s_waitcnt lgkmcnt(0)
	v_mfma_f32_16x16x32_bf16 v[60:63], v[148:151], v[184:187], v[60:63]
	v_mfma_f32_16x16x32_bf16 v[56:59], v[160:163], v[184:187], v[56:59]
	v_mfma_f32_16x16x32_bf16 v[44:47], v[148:151], v[192:195], v[44:47]
	v_mfma_f32_16x16x32_bf16 v[40:43], v[160:163], v[192:195], v[40:43]
	v_mfma_f32_16x16x32_bf16 v[28:31], v[148:151], v[200:203], v[28:31]
	v_mfma_f32_16x16x32_bf16 v[24:27], v[160:163], v[200:203], v[24:27]
	v_mfma_f32_16x16x32_bf16 v[12:15], v[148:151], v[208:211], v[12:15]
	v_mfma_f32_16x16x32_bf16 v[8:11], v[160:163], v[208:211], v[8:11]
	v_mfma_f32_16x16x32_bf16 v[60:63], v[156:159], v[188:191], v[60:63]
	v_mfma_f32_16x16x32_bf16 v[56:59], v[164:167], v[188:191], v[56:59]
	v_mfma_f32_16x16x32_bf16 v[44:47], v[156:159], v[196:199], v[44:47]
	v_mfma_f32_16x16x32_bf16 v[40:43], v[164:167], v[196:199], v[40:43]
	v_mfma_f32_16x16x32_bf16 v[28:31], v[156:159], v[204:207], v[28:31]
	v_mfma_f32_16x16x32_bf16 v[24:27], v[164:167], v[204:207], v[24:27]
	v_mfma_f32_16x16x32_bf16 v[12:15], v[156:159], v[212:215], v[12:15]
	v_mfma_f32_16x16x32_bf16 v[8:11], v[164:167], v[212:215], v[8:11]
	v_mfma_f32_16x16x32_bf16 v[52:55], v[168:171], v[184:187], v[52:55]
	v_mfma_f32_16x16x32_bf16 v[48:51], v[176:179], v[184:187], v[48:51]
	v_mfma_f32_16x16x32_bf16 v[36:39], v[168:171], v[192:195], v[36:39]
	v_mfma_f32_16x16x32_bf16 v[32:35], v[176:179], v[192:195], v[32:35]
	v_mfma_f32_16x16x32_bf16 v[20:23], v[168:171], v[200:203], v[20:23]
	v_mfma_f32_16x16x32_bf16 v[16:19], v[176:179], v[200:203], v[16:19]
	v_mfma_f32_16x16x32_bf16 v[4:7], v[168:171], v[208:211], v[4:7]
	v_mfma_f32_16x16x32_bf16 v[0:3], v[176:179], v[208:211], v[0:3]
	v_mfma_f32_16x16x32_bf16 v[52:55], v[172:175], v[188:191], v[52:55]
	v_mfma_f32_16x16x32_bf16 v[48:51], v[180:183], v[188:191], v[48:51]
	v_mfma_f32_16x16x32_bf16 v[36:39], v[172:175], v[196:199], v[36:39]
	v_mfma_f32_16x16x32_bf16 v[32:35], v[180:183], v[196:199], v[32:35]
	v_mfma_f32_16x16x32_bf16 v[20:23], v[172:175], v[204:207], v[20:23]
	v_mfma_f32_16x16x32_bf16 v[16:19], v[180:183], v[204:207], v[16:19]
	v_mfma_f32_16x16x32_bf16 v[4:7], v[172:175], v[212:215], v[4:7]
	v_mfma_f32_16x16x32_bf16 v[0:3], v[180:183], v[212:215], v[0:3]
	s_barrier
	s_add_i32 s65, s65, 2
	s_add_u32 s34, s34, 0x100
	s_addc_u32 s35, s35, 0
	s_add_u32 s26, s26, 0x100
	s_addc_u32 s27, s27, 0
	s_cmp_lt_u32 s65, 14
.LBB8_12:
	ds_read_b128 v[148:151], v153
	ds_read_b128 v[156:159], v153 offset:1024
	ds_read_b128 v[160:163], v153 offset:2048
	ds_read_b128 v[164:167], v153 offset:3072
	ds_read_b128 v[168:171], v154
	ds_read_b128 v[172:175], v154 offset:1024
	ds_read_b128 v[176:179], v154 offset:2048
	ds_read_b128 v[180:183], v154 offset:3072
	s_add_u32 s28, s26, 0xfffc0080
	s_addc_u32 s29, s27, -1
	s_cmp_eq_u32 s65, 12
	s_cselect_b32 s31, s5, s29
	s_cselect_b32 s30, s19, s28
	s_cselect_b32 s29, s11, s35
	s_cselect_b32 s28, s25, s34
	v_lshl_add_u64 v[216:217], s[26:27], 0, v[142:143]
	s_add_i32 m0, s40, 0xc000
	s_nop 0
	global_load_lds_dwordx4 v[216:217], off
	ds_read_b128 v[184:187], v155
	ds_read_b128 v[188:191], v155 offset:1024
	ds_read_b128 v[192:195], v155 offset:2048
	ds_read_b128 v[196:199], v155 offset:3072
	ds_read_b128 v[200:203], v155 offset:4096
	ds_read_b128 v[204:207], v155 offset:5120
	ds_read_b128 v[208:211], v155 offset:6144
	ds_read_b128 v[212:215], v155 offset:7168
	v_lshl_add_u64 v[216:217], s[26:27], 0, v[140:141]
	s_add_i32 m0, s40, 0xe000
	s_nop 0
	global_load_lds_dwordx4 v[216:217], off
	s_waitcnt vmcnt(8)
	s_waitcnt lgkmcnt(0)
	s_barrier
	s_waitcnt lgkmcnt(0)
	v_mfma_f32_16x16x32_bf16 v[124:127], v[148:151], v[184:187], v[124:127]
	v_mfma_f32_16x16x32_bf16 v[120:123], v[160:163], v[184:187], v[120:123]
	v_mfma_f32_16x16x32_bf16 v[108:111], v[148:151], v[192:195], v[108:111]
	v_mfma_f32_16x16x32_bf16 v[104:107], v[160:163], v[192:195], v[104:107]
	v_mfma_f32_16x16x32_bf16 v[92:95], v[148:151], v[200:203], v[92:95]
	v_mfma_f32_16x16x32_bf16 v[88:91], v[160:163], v[200:203], v[88:91]
	v_mfma_f32_16x16x32_bf16 v[76:79], v[148:151], v[208:211], v[76:79]
	v_mfma_f32_16x16x32_bf16 v[72:75], v[160:163], v[208:211], v[72:75]
	v_mfma_f32_16x16x32_bf16 v[124:127], v[156:159], v[188:191], v[124:127]
	v_mfma_f32_16x16x32_bf16 v[120:123], v[164:167], v[188:191], v[120:123]
	v_mfma_f32_16x16x32_bf16 v[108:111], v[156:159], v[196:199], v[108:111]
	v_mfma_f32_16x16x32_bf16 v[104:107], v[164:167], v[196:199], v[104:107]
	v_mfma_f32_16x16x32_bf16 v[92:95], v[156:159], v[204:207], v[92:95]
	v_mfma_f32_16x16x32_bf16 v[88:91], v[164:167], v[204:207], v[88:91]
	v_mfma_f32_16x16x32_bf16 v[76:79], v[156:159], v[212:215], v[76:79]
	v_mfma_f32_16x16x32_bf16 v[72:75], v[164:167], v[212:215], v[72:75]
	v_mfma_f32_16x16x32_bf16 v[116:119], v[168:171], v[184:187], v[116:119]
	v_mfma_f32_16x16x32_bf16 v[112:115], v[176:179], v[184:187], v[112:115]
	v_mfma_f32_16x16x32_bf16 v[100:103], v[168:171], v[192:195], v[100:103]
	v_mfma_f32_16x16x32_bf16 v[96:99], v[176:179], v[192:195], v[96:99]
	v_mfma_f32_16x16x32_bf16 v[84:87], v[168:171], v[200:203], v[84:87]
	v_mfma_f32_16x16x32_bf16 v[80:83], v[176:179], v[200:203], v[80:83]
	v_mfma_f32_16x16x32_bf16 v[68:71], v[168:171], v[208:211], v[68:71]
	v_mfma_f32_16x16x32_bf16 v[64:67], v[176:179], v[208:211], v[64:67]
	v_mfma_f32_16x16x32_bf16 v[116:119], v[172:175], v[188:191], v[116:119]
	v_mfma_f32_16x16x32_bf16 v[112:115], v[180:183], v[188:191], v[112:115]
	v_mfma_f32_16x16x32_bf16 v[100:103], v[172:175], v[196:199], v[100:103]
	v_mfma_f32_16x16x32_bf16 v[96:99], v[180:183], v[196:199], v[96:99]
	v_mfma_f32_16x16x32_bf16 v[84:87], v[172:175], v[204:207], v[84:87]
	v_mfma_f32_16x16x32_bf16 v[80:83], v[180:183], v[204:207], v[80:83]
	v_mfma_f32_16x16x32_bf16 v[68:71], v[172:175], v[212:215], v[68:71]
	v_mfma_f32_16x16x32_bf16 v[64:67], v[180:183], v[212:215], v[64:67]
	s_barrier
	ds_read_b128 v[184:187], v155 offset:16384
	ds_read_b128 v[188:191], v155 offset:17408
	s_add_i32 s66, s52, s39
	v_lshl_add_u64 v[216:217], s[28:29], 0, v[130:131]
	s_mov_b32 m0, s66
	s_nop 0
	global_load_lds_dwordx4 v[216:217], off
	ds_read_b128 v[192:195], v155 offset:18432
	ds_read_b128 v[196:199], v155 offset:19456
	s_add_i32 m0, s66, 0x2000
	s_add_u32 s66, s28, 0x40000
	v_lshl_add_u64 v[218:219], s[28:29], 0, v[134:135]
	s_addc_u32 s67, s29, 0
	s_add_i32 s68, s53, s39
	global_load_lds_dwordx4 v[218:219], off
	ds_read_b128 v[200:203], v155 offset:20480
	v_lshl_add_u64 v[220:221], s[66:67], 0, v[130:131]
	s_mov_b32 m0, s68
	v_lshl_add_u64 v[222:223], s[30:31], 0, v[132:133]
	global_load_lds_dwordx4 v[220:221], off
	ds_read_b128 v[204:207], v155 offset:21504
	v_lshl_add_u64 v[220:221], s[66:67], 0, v[134:135]
	s_add_i32 m0, s68, 0x2000
	s_nop 0
	global_load_lds_dwordx4 v[220:221], off
	ds_read_b128 v[208:211], v155 offset:22528
	v_lshl_add_u64 v[220:221], s[30:31], 0, v[128:129]
	s_mov_b32 m0, s40
	s_nop 0
	global_load_lds_dwordx4 v[220:221], off
	ds_read_b128 v[212:215], v155 offset:23552
	s_mov_b32 m0, s41
	s_nop 0
	global_load_lds_dwordx4 v[222:223], off
	s_waitcnt vmcnt(8)
	s_waitcnt lgkmcnt(0)
	s_barrier
	s_waitcnt lgkmcnt(0)
	v_mfma_f32_16x16x32_bf16 v[60:63], v[148:151], v[184:187], v[60:63]
	v_mfma_f32_16x16x32_bf16 v[56:59], v[160:163], v[184:187], v[56:59]
	v_mfma_f32_16x16x32_bf16 v[44:47], v[148:151], v[192:195], v[44:47]
	v_mfma_f32_16x16x32_bf16 v[40:43], v[160:163], v[192:195], v[40:43]
	v_mfma_f32_16x16x32_bf16 v[28:31], v[148:151], v[200:203], v[28:31]
	v_mfma_f32_16x16x32_bf16 v[24:27], v[160:163], v[200:203], v[24:27]
	v_mfma_f32_16x16x32_bf16 v[12:15], v[148:151], v[208:211], v[12:15]
	v_mfma_f32_16x16x32_bf16 v[8:11], v[160:163], v[208:211], v[8:11]
	v_mfma_f32_16x16x32_bf16 v[60:63], v[156:159], v[188:191], v[60:63]
	v_mfma_f32_16x16x32_bf16 v[56:59], v[164:167], v[188:191], v[56:59]
	v_mfma_f32_16x16x32_bf16 v[44:47], v[156:159], v[196:199], v[44:47]
	v_mfma_f32_16x16x32_bf16 v[40:43], v[164:167], v[196:199], v[40:43]
	v_mfma_f32_16x16x32_bf16 v[28:31], v[156:159], v[204:207], v[28:31]
	v_mfma_f32_16x16x32_bf16 v[24:27], v[164:167], v[204:207], v[24:27]
	v_mfma_f32_16x16x32_bf16 v[12:15], v[156:159], v[212:215], v[12:15]
	v_mfma_f32_16x16x32_bf16 v[8:11], v[164:167], v[212:215], v[8:11]
	v_mfma_f32_16x16x32_bf16 v[52:55], v[168:171], v[184:187], v[52:55]
	v_mfma_f32_16x16x32_bf16 v[48:51], v[176:179], v[184:187], v[48:51]
	v_mfma_f32_16x16x32_bf16 v[36:39], v[168:171], v[192:195], v[36:39]
	v_mfma_f32_16x16x32_bf16 v[32:35], v[176:179], v[192:195], v[32:35]
	v_mfma_f32_16x16x32_bf16 v[20:23], v[168:171], v[200:203], v[20:23]
	v_mfma_f32_16x16x32_bf16 v[16:19], v[176:179], v[200:203], v[16:19]
	v_mfma_f32_16x16x32_bf16 v[4:7], v[168:171], v[208:211], v[4:7]
	v_mfma_f32_16x16x32_bf16 v[0:3], v[176:179], v[208:211], v[0:3]
	v_mfma_f32_16x16x32_bf16 v[52:55], v[172:175], v[188:191], v[52:55]
	v_mfma_f32_16x16x32_bf16 v[48:51], v[180:183], v[188:191], v[48:51]
	v_mfma_f32_16x16x32_bf16 v[36:39], v[172:175], v[196:199], v[36:39]
	v_mfma_f32_16x16x32_bf16 v[32:35], v[180:183], v[196:199], v[32:35]
	v_mfma_f32_16x16x32_bf16 v[20:23], v[172:175], v[204:207], v[20:23]
	v_mfma_f32_16x16x32_bf16 v[16:19], v[180:183], v[204:207], v[16:19]
	v_mfma_f32_16x16x32_bf16 v[4:7], v[172:175], v[212:215], v[4:7]
	v_mfma_f32_16x16x32_bf16 v[0:3], v[180:183], v[212:215], v[0:3]
	s_barrier
	s_add_i32 s67, 0, 0x1c000
	s_add_i32 s66, 0, 0x18000
	v_add_u32_e32 v164, s66, v152
	v_add_u32_e32 v180, s67, v152
	ds_read_b128 v[148:151], v164
	ds_read_b128 v[156:159], v164 offset:1024
	ds_read_b128 v[160:163], v164 offset:2048
	ds_read_b128 v[164:167], v164 offset:3072
	ds_read_b128 v[168:171], v180
	ds_read_b128 v[172:175], v180 offset:1024
	ds_read_b128 v[176:179], v180 offset:2048
	ds_read_b128 v[180:183], v180 offset:3072
	s_add_u32 s30, s30, 0x40000
	s_addc_u32 s31, s31, 0
	s_mov_b32 m0, s42
	v_lshl_add_u64 v[224:225], s[30:31], 0, v[128:129]
	global_load_lds_dwordx4 v[224:225], off
	ds_read_b128 v[184:187], v155 offset:32768
	ds_read_b128 v[188:191], v155 offset:33792
	ds_read_b128 v[192:195], v155 offset:34816
	ds_read_b128 v[196:199], v155 offset:35840
	ds_read_b128 v[200:203], v155 offset:36864
	ds_read_b128 v[204:207], v155 offset:37888
	ds_read_b128 v[208:211], v155 offset:38912
	ds_read_b128 v[212:215], v155 offset:39936
	v_lshl_add_u64 v[224:225], s[30:31], 0, v[132:133]
	s_mov_b32 m0, s43
	s_nop 0
	global_load_lds_dwordx4 v[224:225], off
	s_waitcnt vmcnt(8)
	s_waitcnt lgkmcnt(0)
	s_barrier
	s_waitcnt lgkmcnt(0)
	v_mfma_f32_16x16x32_bf16 v[124:127], v[148:151], v[184:187], v[124:127]
	v_mfma_f32_16x16x32_bf16 v[120:123], v[160:163], v[184:187], v[120:123]
	v_mfma_f32_16x16x32_bf16 v[108:111], v[148:151], v[192:195], v[108:111]
	v_mfma_f32_16x16x32_bf16 v[104:107], v[160:163], v[192:195], v[104:107]
	v_mfma_f32_16x16x32_bf16 v[92:95], v[148:151], v[200:203], v[92:95]
	v_mfma_f32_16x16x32_bf16 v[88:91], v[160:163], v[200:203], v[88:91]
	v_mfma_f32_16x16x32_bf16 v[76:79], v[148:151], v[208:211], v[76:79]
	v_mfma_f32_16x16x32_bf16 v[72:75], v[160:163], v[208:211], v[72:75]
	v_mfma_f32_16x16x32_bf16 v[124:127], v[156:159], v[188:191], v[124:127]
	v_mfma_f32_16x16x32_bf16 v[120:123], v[164:167], v[188:191], v[120:123]
	v_mfma_f32_16x16x32_bf16 v[108:111], v[156:159], v[196:199], v[108:111]
	v_mfma_f32_16x16x32_bf16 v[104:107], v[164:167], v[196:199], v[104:107]
	v_mfma_f32_16x16x32_bf16 v[92:95], v[156:159], v[204:207], v[92:95]
	v_mfma_f32_16x16x32_bf16 v[88:91], v[164:167], v[204:207], v[88:91]
	v_mfma_f32_16x16x32_bf16 v[76:79], v[156:159], v[212:215], v[76:79]
	v_mfma_f32_16x16x32_bf16 v[72:75], v[164:167], v[212:215], v[72:75]
	v_mfma_f32_16x16x32_bf16 v[116:119], v[168:171], v[184:187], v[116:119]
	v_mfma_f32_16x16x32_bf16 v[112:115], v[176:179], v[184:187], v[112:115]
	v_mfma_f32_16x16x32_bf16 v[100:103], v[168:171], v[192:195], v[100:103]
	v_mfma_f32_16x16x32_bf16 v[96:99], v[176:179], v[192:195], v[96:99]
	v_mfma_f32_16x16x32_bf16 v[84:87], v[168:171], v[200:203], v[84:87]
	v_mfma_f32_16x16x32_bf16 v[80:83], v[176:179], v[200:203], v[80:83]
	v_mfma_f32_16x16x32_bf16 v[68:71], v[168:171], v[208:211], v[68:71]
	v_mfma_f32_16x16x32_bf16 v[64:67], v[176:179], v[208:211], v[64:67]
	v_mfma_f32_16x16x32_bf16 v[116:119], v[172:175], v[188:191], v[116:119]
	v_mfma_f32_16x16x32_bf16 v[112:115], v[180:183], v[188:191], v[112:115]
	v_mfma_f32_16x16x32_bf16 v[100:103], v[172:175], v[196:199], v[100:103]
	v_mfma_f32_16x16x32_bf16 v[96:99], v[180:183], v[196:199], v[96:99]
	v_mfma_f32_16x16x32_bf16 v[84:87], v[172:175], v[204:207], v[84:87]
	v_mfma_f32_16x16x32_bf16 v[80:83], v[180:183], v[204:207], v[80:83]
	v_mfma_f32_16x16x32_bf16 v[68:71], v[172:175], v[212:215], v[68:71]
	v_mfma_f32_16x16x32_bf16 v[64:67], v[180:183], v[212:215], v[64:67]
	s_barrier
	ds_read_b128 v[184:187], v155 offset:49152
	ds_read_b128 v[188:191], v155 offset:50176
	s_add_i32 s30, s66, s39
	v_lshl_add_u64 v[216:217], v[216:217], 0, s[14:15]
	s_mov_b32 m0, s30
	s_nop 0
	global_load_lds_dwordx4 v[216:217], off
	ds_read_b128 v[192:195], v155 offset:51200
	ds_read_b128 v[196:199], v155 offset:52224
	s_add_i32 m0, s30, 0x2000
	s_add_u32 s28, s28, 0x40080
	v_lshl_add_u64 v[216:217], v[218:219], 0, s[14:15]
	s_addc_u32 s29, s29, 0
	s_add_i32 s30, s67, s39
	global_load_lds_dwordx4 v[216:217], off
	ds_read_b128 v[200:203], v155 offset:53248
	v_lshl_add_u64 v[216:217], s[28:29], 0, v[130:131]
	s_mov_b32 m0, s30
	s_nop 0
	global_load_lds_dwordx4 v[216:217], off
	ds_read_b128 v[204:207], v155 offset:54272
	v_lshl_add_u64 v[216:217], s[28:29], 0, v[134:135]
	s_add_i32 m0, s30, 0x2000
	s_nop 0
	global_load_lds_dwordx4 v[216:217], off
	ds_read_b128 v[208:211], v155 offset:55296
	v_lshl_add_u64 v[216:217], v[220:221], 0, s[14:15]
	s_mov_b32 m0, s45
	s_nop 0
	global_load_lds_dwordx4 v[216:217], off
	ds_read_b128 v[212:215], v155 offset:56320
	v_lshl_add_u64 v[216:217], v[222:223], 0, s[14:15]
	s_mov_b32 m0, s46
	s_nop 0
	global_load_lds_dwordx4 v[216:217], off
	s_waitcnt vmcnt(8)
	s_waitcnt lgkmcnt(0)
	s_barrier
	s_waitcnt lgkmcnt(0)
	v_mfma_f32_16x16x32_bf16 v[60:63], v[148:151], v[184:187], v[60:63]
	v_mfma_f32_16x16x32_bf16 v[56:59], v[160:163], v[184:187], v[56:59]
	v_mfma_f32_16x16x32_bf16 v[44:47], v[148:151], v[192:195], v[44:47]
	v_mfma_f32_16x16x32_bf16 v[40:43], v[160:163], v[192:195], v[40:43]
	v_mfma_f32_16x16x32_bf16 v[28:31], v[148:151], v[200:203], v[28:31]
	v_mfma_f32_16x16x32_bf16 v[24:27], v[160:163], v[200:203], v[24:27]
	v_mfma_f32_16x16x32_bf16 v[12:15], v[148:151], v[208:211], v[12:15]
	v_mfma_f32_16x16x32_bf16 v[8:11], v[160:163], v[208:211], v[8:11]
	v_mfma_f32_16x16x32_bf16 v[60:63], v[156:159], v[188:191], v[60:63]
	v_mfma_f32_16x16x32_bf16 v[56:59], v[164:167], v[188:191], v[56:59]
	v_mfma_f32_16x16x32_bf16 v[44:47], v[156:159], v[196:199], v[44:47]
	v_mfma_f32_16x16x32_bf16 v[40:43], v[164:167], v[196:199], v[40:43]
	v_mfma_f32_16x16x32_bf16 v[28:31], v[156:159], v[204:207], v[28:31]
	v_mfma_f32_16x16x32_bf16 v[24:27], v[164:167], v[204:207], v[24:27]
	v_mfma_f32_16x16x32_bf16 v[12:15], v[156:159], v[212:215], v[12:15]
	v_mfma_f32_16x16x32_bf16 v[8:11], v[164:167], v[212:215], v[8:11]
	v_mfma_f32_16x16x32_bf16 v[52:55], v[168:171], v[184:187], v[52:55]
	v_mfma_f32_16x16x32_bf16 v[48:51], v[176:179], v[184:187], v[48:51]
	v_mfma_f32_16x16x32_bf16 v[36:39], v[168:171], v[192:195], v[36:39]
	v_mfma_f32_16x16x32_bf16 v[32:35], v[176:179], v[192:195], v[32:35]
	v_mfma_f32_16x16x32_bf16 v[20:23], v[168:171], v[200:203], v[20:23]
	v_mfma_f32_16x16x32_bf16 v[16:19], v[176:179], v[200:203], v[16:19]
	v_mfma_f32_16x16x32_bf16 v[4:7], v[168:171], v[208:211], v[4:7]
	v_mfma_f32_16x16x32_bf16 v[0:3], v[176:179], v[208:211], v[0:3]
	v_mfma_f32_16x16x32_bf16 v[52:55], v[172:175], v[188:191], v[52:55]
	v_mfma_f32_16x16x32_bf16 v[48:51], v[180:183], v[188:191], v[48:51]
	v_mfma_f32_16x16x32_bf16 v[36:39], v[172:175], v[196:199], v[36:39]
	v_mfma_f32_16x16x32_bf16 v[32:35], v[180:183], v[196:199], v[32:35]
	v_mfma_f32_16x16x32_bf16 v[20:23], v[172:175], v[204:207], v[20:23]
	v_mfma_f32_16x16x32_bf16 v[16:19], v[180:183], v[204:207], v[16:19]
	v_mfma_f32_16x16x32_bf16 v[4:7], v[172:175], v[212:215], v[4:7]
	v_mfma_f32_16x16x32_bf16 v[0:3], v[180:183], v[212:215], v[0:3]
	s_barrier
	s_add_i32 s65, s65, 2
	s_add_u32 s34, s34, 0x100
	s_addc_u32 s35, s35, 0
	s_add_u32 s26, s26, 0x100
	s_addc_u32 s27, s27, 0
	s_cmp_lt_u32 s65, 14
	s_cbranch_scc1 .LBB8_12
	s_andn2_b64 vcc, exec, s[16:17]
	s_cbranch_vccnz .LBB8_15
	s_barrier

.LBB10_19:
	s_ashr_i32 s17, s16, 31
	v_cmp_lt_i64_e32 vcc, s[0:1], v[142:143]
	s_lshl_b64 s[0:1], s[16:17], 19
	s_add_u32 s18, s33, s0
	s_addc_u32 s19, s34, s1
	s_and_b64 s[0:1], vcc, exec
	s_cselect_b32 s17, s19, s27
	s_cselect_b32 s53, s18, s26
	s_ashr_i32 s15, s14, 31
	s_lshl_b64 s[0:1], s[14:15], 19
	s_add_u32 s20, s4, s0
	s_addc_u32 s21, s5, s1
	s_and_b64 s[0:1], vcc, exec
	s_cselect_b32 s15, s21, s25
	s_cselect_b32 s54, s20, s24
	s_add_u32 s55, s24, 0x100
	s_addc_u32 s56, s25, 0
	s_add_u32 s24, s26, 0x40080
	s_addc_u32 s25, s27, 0
	s_mov_b32 s57, -2
	ds_read_b128 v[152:155], v149
	ds_read_b128 v[156:159], v149 offset:1024
	ds_read_b128 v[160:163], v149 offset:2048
	ds_read_b128 v[164:167], v149 offset:3072
	ds_read_b128 v[168:171], v150
	ds_read_b128 v[172:175], v150 offset:1024
	ds_read_b128 v[176:179], v150 offset:2048
	ds_read_b128 v[180:183], v150 offset:3072
	s_add_u32 s26, s24, 0xfffc0080
	s_addc_u32 s27, s25, -1
	s_cmp_eq_u32 s57, 12
	s_cselect_b32 s29, s17, s27
	s_cselect_b32 s28, s53, s26
	s_cselect_b32 s27, s15, s56
	s_cselect_b32 s26, s54, s55
	v_lshl_add_u64 v[146:147], s[24:25], 0, v[140:141]
	s_add_i32 m0, s35, 0xc000
	s_nop 0
	global_load_lds_dwordx4 v[146:147], off
	ds_read_b128 v[184:187], v151
	ds_read_b128 v[188:191], v151 offset:1024
	ds_read_b128 v[192:195], v151 offset:2048
	ds_read_b128 v[196:199], v151 offset:3072
	ds_read_b128 v[200:203], v151 offset:4096
	ds_read_b128 v[204:207], v151 offset:5120
	ds_read_b128 v[208:211], v151 offset:6144
	ds_read_b128 v[212:215], v151 offset:7168
	v_lshl_add_u64 v[146:147], s[24:25], 0, v[138:139]
	s_add_i32 m0, s35, 0xe000
	s_nop 0
	global_load_lds_dwordx4 v[146:147], off
	s_waitcnt vmcnt(8)
	s_waitcnt lgkmcnt(0)
	s_barrier
	s_waitcnt lgkmcnt(0)
	v_mfma_f32_16x16x32_bf16 v[124:127], v[152:155], v[184:187], 0
	v_mfma_f32_16x16x32_bf16 v[120:123], v[160:163], v[184:187], 0
	v_mfma_f32_16x16x32_bf16 v[116:119], v[152:155], v[192:195], 0
	v_mfma_f32_16x16x32_bf16 v[108:111], v[160:163], v[192:195], 0
	v_mfma_f32_16x16x32_bf16 v[100:103], v[152:155], v[200:203], 0
	v_mfma_f32_16x16x32_bf16 v[92:95], v[160:163], v[200:203], 0
	v_mfma_f32_16x16x32_bf16 v[84:87], v[152:155], v[208:211], 0
	v_mfma_f32_16x16x32_bf16 v[76:79], v[160:163], v[208:211], 0
	v_mfma_f32_16x16x32_bf16 v[124:127], v[156:159], v[188:191], v[124:127]
	v_mfma_f32_16x16x32_bf16 v[120:123], v[164:167], v[188:191], v[120:123]
	v_mfma_f32_16x16x32_bf16 v[116:119], v[156:159], v[196:199], v[116:119]
	v_mfma_f32_16x16x32_bf16 v[108:111], v[164:167], v[196:199], v[108:111]
	v_mfma_f32_16x16x32_bf16 v[100:103], v[156:159], v[204:207], v[100:103]
	v_mfma_f32_16x16x32_bf16 v[92:95], v[164:167], v[204:207], v[92:95]
	v_mfma_f32_16x16x32_bf16 v[84:87], v[156:159], v[212:215], v[84:87]
	v_mfma_f32_16x16x32_bf16 v[76:79], v[164:167], v[212:215], v[76:79]
	v_mfma_f32_16x16x32_bf16 v[112:115], v[168:171], v[184:187], 0
	v_mfma_f32_16x16x32_bf16 v[104:107], v[176:179], v[184:187], 0
	v_mfma_f32_16x16x32_bf16 v[96:99], v[168:171], v[192:195], 0
	v_mfma_f32_16x16x32_bf16 v[88:91], v[176:179], v[192:195], 0
	v_mfma_f32_16x16x32_bf16 v[80:83], v[168:171], v[200:203], 0
	v_mfma_f32_16x16x32_bf16 v[72:75], v[176:179], v[200:203], 0
	v_mfma_f32_16x16x32_bf16 v[68:71], v[168:171], v[208:211], 0
	v_mfma_f32_16x16x32_bf16 v[64:67], v[176:179], v[208:211], 0
	v_mfma_f32_16x16x32_bf16 v[112:115], v[172:175], v[188:191], v[112:115]
	v_mfma_f32_16x16x32_bf16 v[104:107], v[180:183], v[188:191], v[104:107]
	v_mfma_f32_16x16x32_bf16 v[96:99], v[172:175], v[196:199], v[96:99]
	v_mfma_f32_16x16x32_bf16 v[88:91], v[180:183], v[196:199], v[88:91]
	v_mfma_f32_16x16x32_bf16 v[80:83], v[172:175], v[204:207], v[80:83]
	v_mfma_f32_16x16x32_bf16 v[72:75], v[180:183], v[204:207], v[72:75]
	v_mfma_f32_16x16x32_bf16 v[68:71], v[172:175], v[212:215], v[68:71]
	v_mfma_f32_16x16x32_bf16 v[64:67], v[180:183], v[212:215], v[64:67]
	s_barrier
	ds_read_b128 v[184:187], v151 offset:16384
	ds_read_b128 v[188:191], v151 offset:17408
	s_add_i32 s58, s46, s31
	v_lshl_add_u64 v[146:147], s[26:27], 0, v[130:131]
	s_mov_b32 m0, s58
	s_nop 0
	global_load_lds_dwordx4 v[146:147], off
	ds_read_b128 v[192:195], v151 offset:18432
	ds_read_b128 v[196:199], v151 offset:19456
	s_add_i32 m0, s58, 0x2000
	s_add_u32 s58, s26, 0x40000
	v_lshl_add_u64 v[216:217], s[26:27], 0, v[134:135]
	s_addc_u32 s59, s27, 0
	s_add_i32 s60, s47, s31
	global_load_lds_dwordx4 v[216:217], off
	ds_read_b128 v[200:203], v151 offset:20480
	v_lshl_add_u64 v[218:219], s[58:59], 0, v[130:131]
	s_mov_b32 m0, s60
	v_lshl_add_u64 v[220:221], s[28:29], 0, v[132:133]
	global_load_lds_dwordx4 v[218:219], off
	ds_read_b128 v[204:207], v151 offset:21504
	v_lshl_add_u64 v[218:219], s[58:59], 0, v[134:135]
	s_add_i32 m0, s60, 0x2000
	s_nop 0
	global_load_lds_dwordx4 v[218:219], off
	ds_read_b128 v[208:211], v151 offset:22528
	v_lshl_add_u64 v[218:219], s[28:29], 0, v[128:129]
	s_mov_b32 m0, s35
	s_nop 0
	global_load_lds_dwordx4 v[218:219], off
	ds_read_b128 v[212:215], v151 offset:23552
	s_mov_b32 m0, s36
	s_nop 0
	global_load_lds_dwordx4 v[220:221], off
	s_waitcnt vmcnt(8)
	s_waitcnt lgkmcnt(0)
	s_barrier
	s_waitcnt lgkmcnt(0)
	v_mfma_f32_16x16x32_bf16 v[60:63], v[152:155], v[184:187], 0
	v_mfma_f32_16x16x32_bf16 v[56:59], v[160:163], v[184:187], 0
	v_mfma_f32_16x16x32_bf16 v[52:55], v[152:155], v[192:195], 0
	v_mfma_f32_16x16x32_bf16 v[44:47], v[160:163], v[192:195], 0
	v_mfma_f32_16x16x32_bf16 v[36:39], v[152:155], v[200:203], 0
	v_mfma_f32_16x16x32_bf16 v[28:31], v[160:163], v[200:203], 0
	v_mfma_f32_16x16x32_bf16 v[20:23], v[152:155], v[208:211], 0
	v_mfma_f32_16x16x32_bf16 v[12:15], v[160:163], v[208:211], 0
	v_mfma_f32_16x16x32_bf16 v[60:63], v[156:159], v[188:191], v[60:63]
	v_mfma_f32_16x16x32_bf16 v[56:59], v[164:167], v[188:191], v[56:59]
	v_mfma_f32_16x16x32_bf16 v[52:55], v[156:159], v[196:199], v[52:55]
	v_mfma_f32_16x16x32_bf16 v[44:47], v[164:167], v[196:199], v[44:47]
	v_mfma_f32_16x16x32_bf16 v[36:39], v[156:159], v[204:207], v[36:39]
	v_mfma_f32_16x16x32_bf16 v[28:31], v[164:167], v[204:207], v[28:31]
	v_mfma_f32_16x16x32_bf16 v[20:23], v[156:159], v[212:215], v[20:23]
	v_mfma_f32_16x16x32_bf16 v[12:15], v[164:167], v[212:215], v[12:15]
	v_mfma_f32_16x16x32_bf16 v[48:51], v[168:171], v[184:187], 0
	v_mfma_f32_16x16x32_bf16 v[40:43], v[176:179], v[184:187], 0
	v_mfma_f32_16x16x32_bf16 v[32:35], v[168:171], v[192:195], 0
	v_mfma_f32_16x16x32_bf16 v[24:27], v[176:179], v[192:195], 0
	v_mfma_f32_16x16x32_bf16 v[16:19], v[168:171], v[200:203], 0
	v_mfma_f32_16x16x32_bf16 v[8:11], v[176:179], v[200:203], 0
	v_mfma_f32_16x16x32_bf16 v[4:7], v[168:171], v[208:211], 0
	v_mfma_f32_16x16x32_bf16 v[0:3], v[176:179], v[208:211], 0
	v_mfma_f32_16x16x32_bf16 v[48:51], v[172:175], v[188:191], v[48:51]
	v_mfma_f32_16x16x32_bf16 v[40:43], v[180:183], v[188:191], v[40:43]
	v_mfma_f32_16x16x32_bf16 v[32:35], v[172:175], v[196:199], v[32:35]
	v_mfma_f32_16x16x32_bf16 v[24:27], v[180:183], v[196:199], v[24:27]
	v_mfma_f32_16x16x32_bf16 v[16:19], v[172:175], v[204:207], v[16:19]
	v_mfma_f32_16x16x32_bf16 v[8:11], v[180:183], v[204:207], v[8:11]
	v_mfma_f32_16x16x32_bf16 v[4:7], v[172:175], v[212:215], v[4:7]
	v_mfma_f32_16x16x32_bf16 v[0:3], v[180:183], v[212:215], v[0:3]
	s_barrier
	s_add_i32 s59, 0, 0x1c000
	s_add_i32 s58, 0, 0x18000
	v_add_u32_e32 v164, s58, v148
	v_add_u32_e32 v180, s59, v148
	ds_read_b128 v[152:155], v164
	ds_read_b128 v[156:159], v164 offset:1024
	ds_read_b128 v[160:163], v164 offset:2048
	ds_read_b128 v[164:167], v164 offset:3072
	ds_read_b128 v[168:171], v180
	ds_read_b128 v[172:175], v180 offset:1024
	ds_read_b128 v[176:179], v180 offset:2048
	ds_read_b128 v[180:183], v180 offset:3072
	s_add_u32 s28, s28, 0x40000
	s_addc_u32 s29, s29, 0
	s_mov_b32 m0, s37
	v_lshl_add_u64 v[222:223], s[28:29], 0, v[128:129]
	global_load_lds_dwordx4 v[222:223], off
	ds_read_b128 v[184:187], v151 offset:32768
	ds_read_b128 v[188:191], v151 offset:33792
	ds_read_b128 v[192:195], v151 offset:34816
	ds_read_b128 v[196:199], v151 offset:35840
	ds_read_b128 v[200:203], v151 offset:36864
	ds_read_b128 v[204:207], v151 offset:37888
	ds_read_b128 v[208:211], v151 offset:38912
	ds_read_b128 v[212:215], v151 offset:39936
	v_lshl_add_u64 v[222:223], s[28:29], 0, v[132:133]
	s_mov_b32 m0, s38
	s_nop 0
	global_load_lds_dwordx4 v[222:223], off
	s_waitcnt vmcnt(8)
	s_waitcnt lgkmcnt(0)
	s_barrier
	s_waitcnt lgkmcnt(0)
	v_mfma_f32_16x16x32_bf16 v[124:127], v[152:155], v[184:187], v[124:127]
	v_mfma_f32_16x16x32_bf16 v[120:123], v[160:163], v[184:187], v[120:123]
	v_mfma_f32_16x16x32_bf16 v[116:119], v[152:155], v[192:195], v[116:119]
	v_mfma_f32_16x16x32_bf16 v[108:111], v[160:163], v[192:195], v[108:111]
	v_mfma_f32_16x16x32_bf16 v[100:103], v[152:155], v[200:203], v[100:103]
	v_mfma_f32_16x16x32_bf16 v[92:95], v[160:163], v[200:203], v[92:95]
	v_mfma_f32_16x16x32_bf16 v[84:87], v[152:155], v[208:211], v[84:87]
	v_mfma_f32_16x16x32_bf16 v[76:79], v[160:163], v[208:211], v[76:79]
	v_mfma_f32_16x16x32_bf16 v[124:127], v[156:159], v[188:191], v[124:127]
	v_mfma_f32_16x16x32_bf16 v[120:123], v[164:167], v[188:191], v[120:123]
	v_mfma_f32_16x16x32_bf16 v[116:119], v[156:159], v[196:199], v[116:119]
	v_mfma_f32_16x16x32_bf16 v[108:111], v[164:167], v[196:199], v[108:111]
	v_mfma_f32_16x16x32_bf16 v[100:103], v[156:159], v[204:207], v[100:103]
	v_mfma_f32_16x16x32_bf16 v[92:95], v[164:167], v[204:207], v[92:95]
	v_mfma_f32_16x16x32_bf16 v[84:87], v[156:159], v[212:215], v[84:87]
	v_mfma_f32_16x16x32_bf16 v[76:79], v[164:167], v[212:215], v[76:79]
	v_mfma_f32_16x16x32_bf16 v[112:115], v[168:171], v[184:187], v[112:115]
	v_mfma_f32_16x16x32_bf16 v[104:107], v[176:179], v[184:187], v[104:107]
	v_mfma_f32_16x16x32_bf16 v[96:99], v[168:171], v[192:195], v[96:99]
	v_mfma_f32_16x16x32_bf16 v[88:91], v[176:179], v[192:195], v[88:91]
	v_mfma_f32_16x16x32_bf16 v[80:83], v[168:171], v[200:203], v[80:83]
	v_mfma_f32_16x16x32_bf16 v[72:75], v[176:179], v[200:203], v[72:75]
	v_mfma_f32_16x16x32_bf16 v[68:71], v[168:171], v[208:211], v[68:71]
	v_mfma_f32_16x16x32_bf16 v[64:67], v[176:179], v[208:211], v[64:67]
	v_mfma_f32_16x16x32_bf16 v[112:115], v[172:175], v[188:191], v[112:115]
	v_mfma_f32_16x16x32_bf16 v[104:107], v[180:183], v[188:191], v[104:107]
	v_mfma_f32_16x16x32_bf16 v[96:99], v[172:175], v[196:199], v[96:99]
	v_mfma_f32_16x16x32_bf16 v[88:91], v[180:183], v[196:199], v[88:91]
	v_mfma_f32_16x16x32_bf16 v[80:83], v[172:175], v[204:207], v[80:83]
	v_mfma_f32_16x16x32_bf16 v[72:75], v[180:183], v[204:207], v[72:75]
	v_mfma_f32_16x16x32_bf16 v[68:71], v[172:175], v[212:215], v[68:71]
	v_mfma_f32_16x16x32_bf16 v[64:67], v[180:183], v[212:215], v[64:67]
	s_barrier
	ds_read_b128 v[184:187], v151 offset:49152
	ds_read_b128 v[188:191], v151 offset:50176
	s_add_i32 s28, s58, s31
	v_lshl_add_u64 v[146:147], v[146:147], 0, s[10:11]
	s_mov_b32 m0, s28
	s_nop 0
	global_load_lds_dwordx4 v[146:147], off
	ds_read_b128 v[192:195], v151 offset:51200
	ds_read_b128 v[196:199], v151 offset:52224
	s_add_i32 m0, s28, 0x2000
	s_add_u32 s26, s26, 0x40080
	v_lshl_add_u64 v[146:147], v[216:217], 0, s[10:11]
	s_addc_u32 s27, s27, 0
	s_add_i32 s28, s59, s31
	global_load_lds_dwordx4 v[146:147], off
	ds_read_b128 v[200:203], v151 offset:53248
	v_lshl_add_u64 v[146:147], s[26:27], 0, v[130:131]
	s_mov_b32 m0, s28
	s_nop 0
	global_load_lds_dwordx4 v[146:147], off
	ds_read_b128 v[204:207], v151 offset:54272
	v_lshl_add_u64 v[146:147], s[26:27], 0, v[134:135]
	s_add_i32 m0, s28, 0x2000
	s_nop 0
	global_load_lds_dwordx4 v[146:147], off
	ds_read_b128 v[208:211], v151 offset:55296
	v_lshl_add_u64 v[146:147], v[218:219], 0, s[10:11]
	s_mov_b32 m0, s41
	s_nop 0
	global_load_lds_dwordx4 v[146:147], off
	ds_read_b128 v[212:215], v151 offset:56320
	v_lshl_add_u64 v[146:147], v[220:221], 0, s[10:11]
	s_mov_b32 m0, s42
	s_nop 0
	global_load_lds_dwordx4 v[146:147], off
	s_waitcnt vmcnt(8)
	s_waitcnt lgkmcnt(0)
	s_barrier
	s_waitcnt lgkmcnt(0)
	v_mfma_f32_16x16x32_bf16 v[60:63], v[152:155], v[184:187], v[60:63]
	v_mfma_f32_16x16x32_bf16 v[56:59], v[160:163], v[184:187], v[56:59]
	v_mfma_f32_16x16x32_bf16 v[52:55], v[152:155], v[192:195], v[52:55]
	v_mfma_f32_16x16x32_bf16 v[44:47], v[160:163], v[192:195], v[44:47]
	v_mfma_f32_16x16x32_bf16 v[36:39], v[152:155], v[200:203], v[36:39]
	v_mfma_f32_16x16x32_bf16 v[28:31], v[160:163], v[200:203], v[28:31]
	v_mfma_f32_16x16x32_bf16 v[20:23], v[152:155], v[208:211], v[20:23]
	v_mfma_f32_16x16x32_bf16 v[12:15], v[160:163], v[208:211], v[12:15]
	v_mfma_f32_16x16x32_bf16 v[60:63], v[156:159], v[188:191], v[60:63]
	v_mfma_f32_16x16x32_bf16 v[56:59], v[164:167], v[188:191], v[56:59]
	v_mfma_f32_16x16x32_bf16 v[52:55], v[156:159], v[196:199], v[52:55]
	v_mfma_f32_16x16x32_bf16 v[44:47], v[164:167], v[196:199], v[44:47]
	v_mfma_f32_16x16x32_bf16 v[36:39], v[156:159], v[204:207], v[36:39]
	v_mfma_f32_16x16x32_bf16 v[28:31], v[164:167], v[204:207], v[28:31]
	v_mfma_f32_16x16x32_bf16 v[20:23], v[156:159], v[212:215], v[20:23]
	v_mfma_f32_16x16x32_bf16 v[12:15], v[164:167], v[212:215], v[12:15]
	v_mfma_f32_16x16x32_bf16 v[48:51], v[168:171], v[184:187], v[48:51]
	v_mfma_f32_16x16x32_bf16 v[40:43], v[176:179], v[184:187], v[40:43]
	v_mfma_f32_16x16x32_bf16 v[32:35], v[168:171], v[192:195], v[32:35]
	v_mfma_f32_16x16x32_bf16 v[24:27], v[176:179], v[192:195], v[24:27]
	v_mfma_f32_16x16x32_bf16 v[16:19], v[168:171], v[200:203], v[16:19]
	v_mfma_f32_16x16x32_bf16 v[8:11], v[176:179], v[200:203], v[8:11]
	v_mfma_f32_16x16x32_bf16 v[4:7], v[168:171], v[208:211], v[4:7]
	v_mfma_f32_16x16x32_bf16 v[0:3], v[176:179], v[208:211], v[0:3]
	v_mfma_f32_16x16x32_bf16 v[48:51], v[172:175], v[188:191], v[48:51]
	v_mfma_f32_16x16x32_bf16 v[40:43], v[180:183], v[188:191], v[40:43]
	v_mfma_f32_16x16x32_bf16 v[32:35], v[172:175], v[196:199], v[32:35]
	v_mfma_f32_16x16x32_bf16 v[24:27], v[180:183], v[196:199], v[24:27]
	v_mfma_f32_16x16x32_bf16 v[16:19], v[172:175], v[204:207], v[16:19]
	v_mfma_f32_16x16x32_bf16 v[8:11], v[180:183], v[204:207], v[8:11]
	v_mfma_f32_16x16x32_bf16 v[4:7], v[172:175], v[212:215], v[4:7]
	v_mfma_f32_16x16x32_bf16 v[0:3], v[180:183], v[212:215], v[0:3]
	s_barrier
	s_add_i32 s57, s57, 2
	s_add_u32 s55, s55, 0x100
	s_addc_u32 s56, s56, 0
	s_add_u32 s24, s24, 0x100
	s_addc_u32 s25, s25, 0
	s_cmp_lt_u32 s57, 14
.LBB10_20:
	ds_read_b128 v[152:155], v149
	ds_read_b128 v[156:159], v149 offset:1024
	ds_read_b128 v[160:163], v149 offset:2048
	ds_read_b128 v[164:167], v149 offset:3072
	ds_read_b128 v[168:171], v150
	ds_read_b128 v[172:175], v150 offset:1024
	ds_read_b128 v[176:179], v150 offset:2048
	ds_read_b128 v[180:183], v150 offset:3072
	s_add_u32 s26, s24, 0xfffc0080
	s_addc_u32 s27, s25, -1
	s_cmp_eq_u32 s57, 12
	s_cselect_b32 s29, s17, s27
	s_cselect_b32 s28, s53, s26
	s_cselect_b32 s27, s15, s56
	s_cselect_b32 s26, s54, s55
	v_lshl_add_u64 v[146:147], s[24:25], 0, v[140:141]
	s_add_i32 m0, s35, 0xc000
	s_nop 0
	global_load_lds_dwordx4 v[146:147], off
	ds_read_b128 v[184:187], v151
	ds_read_b128 v[188:191], v151 offset:1024
	ds_read_b128 v[192:195], v151 offset:2048
	ds_read_b128 v[196:199], v151 offset:3072
	ds_read_b128 v[200:203], v151 offset:4096
	ds_read_b128 v[204:207], v151 offset:5120
	ds_read_b128 v[208:211], v151 offset:6144
	ds_read_b128 v[212:215], v151 offset:7168
	v_lshl_add_u64 v[146:147], s[24:25], 0, v[138:139]
	s_add_i32 m0, s35, 0xe000
	s_nop 0
	global_load_lds_dwordx4 v[146:147], off
	s_waitcnt vmcnt(8)
	s_waitcnt lgkmcnt(0)
	s_barrier
	s_waitcnt lgkmcnt(0)
	v_mfma_f32_16x16x32_bf16 v[124:127], v[152:155], v[184:187], v[124:127]
	v_mfma_f32_16x16x32_bf16 v[120:123], v[160:163], v[184:187], v[120:123]
	v_mfma_f32_16x16x32_bf16 v[116:119], v[152:155], v[192:195], v[116:119]
	v_mfma_f32_16x16x32_bf16 v[108:111], v[160:163], v[192:195], v[108:111]
	v_mfma_f32_16x16x32_bf16 v[100:103], v[152:155], v[200:203], v[100:103]
	v_mfma_f32_16x16x32_bf16 v[92:95], v[160:163], v[200:203], v[92:95]
	v_mfma_f32_16x16x32_bf16 v[84:87], v[152:155], v[208:211], v[84:87]
	v_mfma_f32_16x16x32_bf16 v[76:79], v[160:163], v[208:211], v[76:79]
	v_mfma_f32_16x16x32_bf16 v[124:127], v[156:159], v[188:191], v[124:127]
	v_mfma_f32_16x16x32_bf16 v[120:123], v[164:167], v[188:191], v[120:123]
	v_mfma_f32_16x16x32_bf16 v[116:119], v[156:159], v[196:199], v[116:119]
	v_mfma_f32_16x16x32_bf16 v[108:111], v[164:167], v[196:199], v[108:111]
	v_mfma_f32_16x16x32_bf16 v[100:103], v[156:159], v[204:207], v[100:103]
	v_mfma_f32_16x16x32_bf16 v[92:95], v[164:167], v[204:207], v[92:95]
	v_mfma_f32_16x16x32_bf16 v[84:87], v[156:159], v[212:215], v[84:87]
	v_mfma_f32_16x16x32_bf16 v[76:79], v[164:167], v[212:215], v[76:79]
	v_mfma_f32_16x16x32_bf16 v[112:115], v[168:171], v[184:187], v[112:115]
	v_mfma_f32_16x16x32_bf16 v[104:107], v[176:179], v[184:187], v[104:107]
	v_mfma_f32_16x16x32_bf16 v[96:99], v[168:171], v[192:195], v[96:99]
	v_mfma_f32_16x16x32_bf16 v[88:91], v[176:179], v[192:195], v[88:91]
	v_mfma_f32_16x16x32_bf16 v[80:83], v[168:171], v[200:203], v[80:83]
	v_mfma_f32_16x16x32_bf16 v[72:75], v[176:179], v[200:203], v[72:75]
	v_mfma_f32_16x16x32_bf16 v[68:71], v[168:171], v[208:211], v[68:71]
	v_mfma_f32_16x16x32_bf16 v[64:67], v[176:179], v[208:211], v[64:67]
	v_mfma_f32_16x16x32_bf16 v[112:115], v[172:175], v[188:191], v[112:115]
	v_mfma_f32_16x16x32_bf16 v[104:107], v[180:183], v[188:191], v[104:107]
	v_mfma_f32_16x16x32_bf16 v[96:99], v[172:175], v[196:199], v[96:99]
	v_mfma_f32_16x16x32_bf16 v[88:91], v[180:183], v[196:199], v[88:91]
	v_mfma_f32_16x16x32_bf16 v[80:83], v[172:175], v[204:207], v[80:83]
	v_mfma_f32_16x16x32_bf16 v[72:75], v[180:183], v[204:207], v[72:75]
	v_mfma_f32_16x16x32_bf16 v[68:71], v[172:175], v[212:215], v[68:71]
	v_mfma_f32_16x16x32_bf16 v[64:67], v[180:183], v[212:215], v[64:67]
	s_barrier
	ds_read_b128 v[184:187], v151 offset:16384
	ds_read_b128 v[188:191], v151 offset:17408
	s_add_i32 s58, s46, s31
	v_lshl_add_u64 v[146:147], s[26:27], 0, v[130:131]
	s_mov_b32 m0, s58
	s_nop 0
	global_load_lds_dwordx4 v[146:147], off
	ds_read_b128 v[192:195], v151 offset:18432
	ds_read_b128 v[196:199], v151 offset:19456
	s_add_i32 m0, s58, 0x2000
	s_add_u32 s58, s26, 0x40000
	v_lshl_add_u64 v[216:217], s[26:27], 0, v[134:135]
	s_addc_u32 s59, s27, 0
	s_add_i32 s60, s47, s31
	global_load_lds_dwordx4 v[216:217], off
	ds_read_b128 v[200:203], v151 offset:20480
	v_lshl_add_u64 v[218:219], s[58:59], 0, v[130:131]
	s_mov_b32 m0, s60
	v_lshl_add_u64 v[220:221], s[28:29], 0, v[132:133]
	global_load_lds_dwordx4 v[218:219], off
	ds_read_b128 v[204:207], v151 offset:21504
	v_lshl_add_u64 v[218:219], s[58:59], 0, v[134:135]
	s_add_i32 m0, s60, 0x2000
	s_nop 0
	global_load_lds_dwordx4 v[218:219], off
	ds_read_b128 v[208:211], v151 offset:22528
	v_lshl_add_u64 v[218:219], s[28:29], 0, v[128:129]
	s_mov_b32 m0, s35
	s_nop 0
	global_load_lds_dwordx4 v[218:219], off
	ds_read_b128 v[212:215], v151 offset:23552
	s_mov_b32 m0, s36
	s_nop 0
	global_load_lds_dwordx4 v[220:221], off
	s_waitcnt vmcnt(8)
	s_waitcnt lgkmcnt(0)
	s_barrier
	s_waitcnt lgkmcnt(0)
	v_mfma_f32_16x16x32_bf16 v[60:63], v[152:155], v[184:187], v[60:63]
	v_mfma_f32_16x16x32_bf16 v[56:59], v[160:163], v[184:187], v[56:59]
	v_mfma_f32_16x16x32_bf16 v[52:55], v[152:155], v[192:195], v[52:55]
	v_mfma_f32_16x16x32_bf16 v[44:47], v[160:163], v[192:195], v[44:47]
	v_mfma_f32_16x16x32_bf16 v[36:39], v[152:155], v[200:203], v[36:39]
	v_mfma_f32_16x16x32_bf16 v[28:31], v[160:163], v[200:203], v[28:31]
	v_mfma_f32_16x16x32_bf16 v[20:23], v[152:155], v[208:211], v[20:23]
	v_mfma_f32_16x16x32_bf16 v[12:15], v[160:163], v[208:211], v[12:15]
	v_mfma_f32_16x16x32_bf16 v[60:63], v[156:159], v[188:191], v[60:63]
	v_mfma_f32_16x16x32_bf16 v[56:59], v[164:167], v[188:191], v[56:59]
	v_mfma_f32_16x16x32_bf16 v[52:55], v[156:159], v[196:199], v[52:55]
	v_mfma_f32_16x16x32_bf16 v[44:47], v[164:167], v[196:199], v[44:47]
	v_mfma_f32_16x16x32_bf16 v[36:39], v[156:159], v[204:207], v[36:39]
	v_mfma_f32_16x16x32_bf16 v[28:31], v[164:167], v[204:207], v[28:31]
	v_mfma_f32_16x16x32_bf16 v[20:23], v[156:159], v[212:215], v[20:23]
	v_mfma_f32_16x16x32_bf16 v[12:15], v[164:167], v[212:215], v[12:15]
	v_mfma_f32_16x16x32_bf16 v[48:51], v[168:171], v[184:187], v[48:51]
	v_mfma_f32_16x16x32_bf16 v[40:43], v[176:179], v[184:187], v[40:43]
	v_mfma_f32_16x16x32_bf16 v[32:35], v[168:171], v[192:195], v[32:35]
	v_mfma_f32_16x16x32_bf16 v[24:27], v[176:179], v[192:195], v[24:27]
	v_mfma_f32_16x16x32_bf16 v[16:19], v[168:171], v[200:203], v[16:19]
	v_mfma_f32_16x16x32_bf16 v[8:11], v[176:179], v[200:203], v[8:11]
	v_mfma_f32_16x16x32_bf16 v[4:7], v[168:171], v[208:211], v[4:7]
	v_mfma_f32_16x16x32_bf16 v[0:3], v[176:179], v[208:211], v[0:3]
	v_mfma_f32_16x16x32_bf16 v[48:51], v[172:175], v[188:191], v[48:51]
	v_mfma_f32_16x16x32_bf16 v[40:43], v[180:183], v[188:191], v[40:43]
	v_mfma_f32_16x16x32_bf16 v[32:35], v[172:175], v[196:199], v[32:35]
	v_mfma_f32_16x16x32_bf16 v[24:27], v[180:183], v[196:199], v[24:27]
	v_mfma_f32_16x16x32_bf16 v[16:19], v[172:175], v[204:207], v[16:19]
	v_mfma_f32_16x16x32_bf16 v[8:11], v[180:183], v[204:207], v[8:11]
	v_mfma_f32_16x16x32_bf16 v[4:7], v[172:175], v[212:215], v[4:7]
	v_mfma_f32_16x16x32_bf16 v[0:3], v[180:183], v[212:215], v[0:3]
	s_barrier
	s_add_i32 s59, 0, 0x1c000
	s_add_i32 s58, 0, 0x18000
	v_add_u32_e32 v164, s58, v148
	v_add_u32_e32 v180, s59, v148
	ds_read_b128 v[152:155], v164
	ds_read_b128 v[156:159], v164 offset:1024
	ds_read_b128 v[160:163], v164 offset:2048
	ds_read_b128 v[164:167], v164 offset:3072
	ds_read_b128 v[168:171], v180
	ds_read_b128 v[172:175], v180 offset:1024
	ds_read_b128 v[176:179], v180 offset:2048
	ds_read_b128 v[180:183], v180 offset:3072
	s_add_u32 s28, s28, 0x40000
	s_addc_u32 s29, s29, 0
	s_mov_b32 m0, s37
	v_lshl_add_u64 v[222:223], s[28:29], 0, v[128:129]
	global_load_lds_dwordx4 v[222:223], off
	ds_read_b128 v[184:187], v151 offset:32768
	ds_read_b128 v[188:191], v151 offset:33792
	ds_read_b128 v[192:195], v151 offset:34816
	ds_read_b128 v[196:199], v151 offset:35840
	ds_read_b128 v[200:203], v151 offset:36864
	ds_read_b128 v[204:207], v151 offset:37888
	ds_read_b128 v[208:211], v151 offset:38912
	ds_read_b128 v[212:215], v151 offset:39936
	v_lshl_add_u64 v[222:223], s[28:29], 0, v[132:133]
	s_mov_b32 m0, s38
	s_nop 0
	global_load_lds_dwordx4 v[222:223], off
	s_waitcnt vmcnt(8)
	s_waitcnt lgkmcnt(0)
	s_barrier
	s_waitcnt lgkmcnt(0)
	v_mfma_f32_16x16x32_bf16 v[124:127], v[152:155], v[184:187], v[124:127]
	v_mfma_f32_16x16x32_bf16 v[120:123], v[160:163], v[184:187], v[120:123]
	v_mfma_f32_16x16x32_bf16 v[116:119], v[152:155], v[192:195], v[116:119]
	v_mfma_f32_16x16x32_bf16 v[108:111], v[160:163], v[192:195], v[108:111]
	v_mfma_f32_16x16x32_bf16 v[100:103], v[152:155], v[200:203], v[100:103]
	v_mfma_f32_16x16x32_bf16 v[92:95], v[160:163], v[200:203], v[92:95]
	v_mfma_f32_16x16x32_bf16 v[84:87], v[152:155], v[208:211], v[84:87]
	v_mfma_f32_16x16x32_bf16 v[76:79], v[160:163], v[208:211], v[76:79]
	v_mfma_f32_16x16x32_bf16 v[124:127], v[156:159], v[188:191], v[124:127]
	v_mfma_f32_16x16x32_bf16 v[120:123], v[164:167], v[188:191], v[120:123]
	v_mfma_f32_16x16x32_bf16 v[116:119], v[156:159], v[196:199], v[116:119]
	v_mfma_f32_16x16x32_bf16 v[108:111], v[164:167], v[196:199], v[108:111]
	v_mfma_f32_16x16x32_bf16 v[100:103], v[156:159], v[204:207], v[100:103]
	v_mfma_f32_16x16x32_bf16 v[92:95], v[164:167], v[204:207], v[92:95]
	v_mfma_f32_16x16x32_bf16 v[84:87], v[156:159], v[212:215], v[84:87]
	v_mfma_f32_16x16x32_bf16 v[76:79], v[164:167], v[212:215], v[76:79]
	v_mfma_f32_16x16x32_bf16 v[112:115], v[168:171], v[184:187], v[112:115]
	v_mfma_f32_16x16x32_bf16 v[104:107], v[176:179], v[184:187], v[104:107]
	v_mfma_f32_16x16x32_bf16 v[96:99], v[168:171], v[192:195], v[96:99]
	v_mfma_f32_16x16x32_bf16 v[88:91], v[176:179], v[192:195], v[88:91]
	v_mfma_f32_16x16x32_bf16 v[80:83], v[168:171], v[200:203], v[80:83]
	v_mfma_f32_16x16x32_bf16 v[72:75], v[176:179], v[200:203], v[72:75]
	v_mfma_f32_16x16x32_bf16 v[68:71], v[168:171], v[208:211], v[68:71]
	v_mfma_f32_16x16x32_bf16 v[64:67], v[176:179], v[208:211], v[64:67]
	v_mfma_f32_16x16x32_bf16 v[112:115], v[172:175], v[188:191], v[112:115]
	v_mfma_f32_16x16x32_bf16 v[104:107], v[180:183], v[188:191], v[104:107]
	v_mfma_f32_16x16x32_bf16 v[96:99], v[172:175], v[196:199], v[96:99]
	v_mfma_f32_16x16x32_bf16 v[88:91], v[180:183], v[196:199], v[88:91]
	v_mfma_f32_16x16x32_bf16 v[80:83], v[172:175], v[204:207], v[80:83]
	v_mfma_f32_16x16x32_bf16 v[72:75], v[180:183], v[204:207], v[72:75]
	v_mfma_f32_16x16x32_bf16 v[68:71], v[172:175], v[212:215], v[68:71]
	v_mfma_f32_16x16x32_bf16 v[64:67], v[180:183], v[212:215], v[64:67]
	s_barrier
	ds_read_b128 v[184:187], v151 offset:49152
	ds_read_b128 v[188:191], v151 offset:50176
	s_add_i32 s28, s58, s31
	v_lshl_add_u64 v[146:147], v[146:147], 0, s[10:11]
	s_mov_b32 m0, s28
	s_nop 0
	global_load_lds_dwordx4 v[146:147], off
	ds_read_b128 v[192:195], v151 offset:51200
	ds_read_b128 v[196:199], v151 offset:52224
	s_add_i32 m0, s28, 0x2000
	s_add_u32 s26, s26, 0x40080
	v_lshl_add_u64 v[146:147], v[216:217], 0, s[10:11]
	s_addc_u32 s27, s27, 0
	s_add_i32 s28, s59, s31
	global_load_lds_dwordx4 v[146:147], off
	ds_read_b128 v[200:203], v151 offset:53248
	v_lshl_add_u64 v[146:147], s[26:27], 0, v[130:131]
	s_mov_b32 m0, s28
	s_nop 0
	global_load_lds_dwordx4 v[146:147], off
	ds_read_b128 v[204:207], v151 offset:54272
	v_lshl_add_u64 v[146:147], s[26:27], 0, v[134:135]
	s_add_i32 m0, s28, 0x2000
	s_nop 0
	global_load_lds_dwordx4 v[146:147], off
	ds_read_b128 v[208:211], v151 offset:55296
	v_lshl_add_u64 v[146:147], v[218:219], 0, s[10:11]
	s_mov_b32 m0, s41
	s_nop 0
	global_load_lds_dwordx4 v[146:147], off
	ds_read_b128 v[212:215], v151 offset:56320
	v_lshl_add_u64 v[146:147], v[220:221], 0, s[10:11]
	s_mov_b32 m0, s42
	s_nop 0
	global_load_lds_dwordx4 v[146:147], off
	s_waitcnt vmcnt(8)
	s_waitcnt lgkmcnt(0)
	s_barrier
	s_waitcnt lgkmcnt(0)
	v_mfma_f32_16x16x32_bf16 v[60:63], v[152:155], v[184:187], v[60:63]
	v_mfma_f32_16x16x32_bf16 v[56:59], v[160:163], v[184:187], v[56:59]
	v_mfma_f32_16x16x32_bf16 v[52:55], v[152:155], v[192:195], v[52:55]
	v_mfma_f32_16x16x32_bf16 v[44:47], v[160:163], v[192:195], v[44:47]
	v_mfma_f32_16x16x32_bf16 v[36:39], v[152:155], v[200:203], v[36:39]
	v_mfma_f32_16x16x32_bf16 v[28:31], v[160:163], v[200:203], v[28:31]
	v_mfma_f32_16x16x32_bf16 v[20:23], v[152:155], v[208:211], v[20:23]
	v_mfma_f32_16x16x32_bf16 v[12:15], v[160:163], v[208:211], v[12:15]
	v_mfma_f32_16x16x32_bf16 v[60:63], v[156:159], v[188:191], v[60:63]
	v_mfma_f32_16x16x32_bf16 v[56:59], v[164:167], v[188:191], v[56:59]
	v_mfma_f32_16x16x32_bf16 v[52:55], v[156:159], v[196:199], v[52:55]
	v_mfma_f32_16x16x32_bf16 v[44:47], v[164:167], v[196:199], v[44:47]
	v_mfma_f32_16x16x32_bf16 v[36:39], v[156:159], v[204:207], v[36:39]
	v_mfma_f32_16x16x32_bf16 v[28:31], v[164:167], v[204:207], v[28:31]
	v_mfma_f32_16x16x32_bf16 v[20:23], v[156:159], v[212:215], v[20:23]
	v_mfma_f32_16x16x32_bf16 v[12:15], v[164:167], v[212:215], v[12:15]
	v_mfma_f32_16x16x32_bf16 v[48:51], v[168:171], v[184:187], v[48:51]
	v_mfma_f32_16x16x32_bf16 v[40:43], v[176:179], v[184:187], v[40:43]
	v_mfma_f32_16x16x32_bf16 v[32:35], v[168:171], v[192:195], v[32:35]
	v_mfma_f32_16x16x32_bf16 v[24:27], v[176:179], v[192:195], v[24:27]
	v_mfma_f32_16x16x32_bf16 v[16:19], v[168:171], v[200:203], v[16:19]
	v_mfma_f32_16x16x32_bf16 v[8:11], v[176:179], v[200:203], v[8:11]
	v_mfma_f32_16x16x32_bf16 v[4:7], v[168:171], v[208:211], v[4:7]
	v_mfma_f32_16x16x32_bf16 v[0:3], v[176:179], v[208:211], v[0:3]
	v_mfma_f32_16x16x32_bf16 v[48:51], v[172:175], v[188:191], v[48:51]
	v_mfma_f32_16x16x32_bf16 v[40:43], v[180:183], v[188:191], v[40:43]
	v_mfma_f32_16x16x32_bf16 v[32:35], v[172:175], v[196:199], v[32:35]
	v_mfma_f32_16x16x32_bf16 v[24:27], v[180:183], v[196:199], v[24:27]
	v_mfma_f32_16x16x32_bf16 v[16:19], v[172:175], v[204:207], v[16:19]
	v_mfma_f32_16x16x32_bf16 v[8:11], v[180:183], v[204:207], v[8:11]
	v_mfma_f32_16x16x32_bf16 v[4:7], v[172:175], v[212:215], v[4:7]
	v_mfma_f32_16x16x32_bf16 v[0:3], v[180:183], v[212:215], v[0:3]
	s_barrier
	s_add_i32 s57, s57, 2
	s_add_u32 s55, s55, 0x100
	s_addc_u32 s56, s56, 0
	s_add_u32 s24, s24, 0x100
	s_addc_u32 s25, s25, 0
	s_cmp_lt_u32 s57, 14
	s_cbranch_scc1 .LBB10_20
	s_andn2_b64 vcc, exec, s[12:13]
	s_cbranch_vccnz .LBB10_23
	s_barrier

.LBB12_8:
	s_ashr_i32 s15, s14, 31
	v_cmp_lt_i64_e32 vcc, s[0:1], v[142:143]
	s_lshl_b64 s[0:1], s[14:15], 19
	s_add_u32 s16, s28, s0
	s_addc_u32 s17, s29, s1
	s_and_b64 s[0:1], vcc, exec
	s_cselect_b32 s15, s17, s25
	s_cselect_b32 s54, s16, s24
	s_ashr_i32 s13, s12, 31
	s_lshl_b64 s[0:1], s[12:13], 19
	s_add_u32 s18, s30, s0
	s_addc_u32 s19, s31, s1
	s_and_b64 s[0:1], vcc, exec
	s_cselect_b32 s13, s19, s23
	s_cselect_b32 s55, s18, s22
	s_add_u32 s56, s22, 0x100
	s_addc_u32 s57, s23, 0
	s_add_u32 s22, s24, 0x40080
	s_addc_u32 s23, s25, 0
	s_mov_b32 s58, -2
	ds_read_b128 v[152:155], v149
	ds_read_b128 v[156:159], v149 offset:1024
	ds_read_b128 v[160:163], v149 offset:2048
	ds_read_b128 v[164:167], v149 offset:3072
	ds_read_b128 v[168:171], v150
	ds_read_b128 v[172:175], v150 offset:1024
	ds_read_b128 v[176:179], v150 offset:2048
	ds_read_b128 v[180:183], v150 offset:3072
	s_add_u32 s24, s22, 0xfffc0080
	s_addc_u32 s25, s23, -1
	s_cmp_eq_u32 s58, 12
	s_cselect_b32 s27, s15, s25
	s_cselect_b32 s26, s54, s24
	s_cselect_b32 s25, s13, s57
	s_cselect_b32 s24, s55, s56
	v_lshl_add_u64 v[146:147], s[22:23], 0, v[140:141]
	s_add_i32 m0, s36, 0xc000
	s_nop 0
	global_load_lds_dwordx4 v[146:147], off
	ds_read_b128 v[184:187], v151
	ds_read_b128 v[188:191], v151 offset:1024
	ds_read_b128 v[192:195], v151 offset:2048
	ds_read_b128 v[196:199], v151 offset:3072
	ds_read_b128 v[200:203], v151 offset:4096
	ds_read_b128 v[204:207], v151 offset:5120
	ds_read_b128 v[208:211], v151 offset:6144
	ds_read_b128 v[212:215], v151 offset:7168
	v_lshl_add_u64 v[146:147], s[22:23], 0, v[138:139]
	s_add_i32 m0, s36, 0xe000
	s_nop 0
	global_load_lds_dwordx4 v[146:147], off
	s_waitcnt vmcnt(8)
	s_waitcnt lgkmcnt(0)
	s_barrier
	s_waitcnt lgkmcnt(0)
	v_mfma_f32_16x16x32_bf16 v[124:127], v[152:155], v[184:187], 0
	v_mfma_f32_16x16x32_bf16 v[120:123], v[160:163], v[184:187], 0
	v_mfma_f32_16x16x32_bf16 v[108:111], v[152:155], v[192:195], 0
	v_mfma_f32_16x16x32_bf16 v[104:107], v[160:163], v[192:195], 0
	v_mfma_f32_16x16x32_bf16 v[92:95], v[152:155], v[200:203], 0
	v_mfma_f32_16x16x32_bf16 v[88:91], v[160:163], v[200:203], 0
	v_mfma_f32_16x16x32_bf16 v[76:79], v[152:155], v[208:211], 0
	v_mfma_f32_16x16x32_bf16 v[72:75], v[160:163], v[208:211], 0
	v_mfma_f32_16x16x32_bf16 v[124:127], v[156:159], v[188:191], v[124:127]
	v_mfma_f32_16x16x32_bf16 v[120:123], v[164:167], v[188:191], v[120:123]
	v_mfma_f32_16x16x32_bf16 v[108:111], v[156:159], v[196:199], v[108:111]
	v_mfma_f32_16x16x32_bf16 v[104:107], v[164:167], v[196:199], v[104:107]
	v_mfma_f32_16x16x32_bf16 v[92:95], v[156:159], v[204:207], v[92:95]
	v_mfma_f32_16x16x32_bf16 v[88:91], v[164:167], v[204:207], v[88:91]
	v_mfma_f32_16x16x32_bf16 v[76:79], v[156:159], v[212:215], v[76:79]
	v_mfma_f32_16x16x32_bf16 v[72:75], v[164:167], v[212:215], v[72:75]
	v_mfma_f32_16x16x32_bf16 v[116:119], v[168:171], v[184:187], 0
	v_mfma_f32_16x16x32_bf16 v[112:115], v[176:179], v[184:187], 0
	v_mfma_f32_16x16x32_bf16 v[100:103], v[168:171], v[192:195], 0
	v_mfma_f32_16x16x32_bf16 v[96:99], v[176:179], v[192:195], 0
	v_mfma_f32_16x16x32_bf16 v[84:87], v[168:171], v[200:203], 0
	v_mfma_f32_16x16x32_bf16 v[80:83], v[176:179], v[200:203], 0
	v_mfma_f32_16x16x32_bf16 v[68:71], v[168:171], v[208:211], 0
	v_mfma_f32_16x16x32_bf16 v[64:67], v[176:179], v[208:211], 0
	v_mfma_f32_16x16x32_bf16 v[116:119], v[172:175], v[188:191], v[116:119]
	v_mfma_f32_16x16x32_bf16 v[112:115], v[180:183], v[188:191], v[112:115]
	v_mfma_f32_16x16x32_bf16 v[100:103], v[172:175], v[196:199], v[100:103]
	v_mfma_f32_16x16x32_bf16 v[96:99], v[180:183], v[196:199], v[96:99]
	v_mfma_f32_16x16x32_bf16 v[84:87], v[172:175], v[204:207], v[84:87]
	v_mfma_f32_16x16x32_bf16 v[80:83], v[180:183], v[204:207], v[80:83]
	v_mfma_f32_16x16x32_bf16 v[68:71], v[172:175], v[212:215], v[68:71]
	v_mfma_f32_16x16x32_bf16 v[64:67], v[180:183], v[212:215], v[64:67]
	s_barrier
	ds_read_b128 v[184:187], v151 offset:16384
	ds_read_b128 v[188:191], v151 offset:17408
	s_add_i32 s59, s44, s33
	v_lshl_add_u64 v[146:147], s[24:25], 0, v[132:133]
	s_mov_b32 m0, s59
	s_nop 0
	global_load_lds_dwordx4 v[146:147], off
	ds_read_b128 v[192:195], v151 offset:18432
	ds_read_b128 v[196:199], v151 offset:19456
	s_add_i32 m0, s59, 0x2000
	s_add_u32 s60, s24, 0x40000
	v_lshl_add_u64 v[216:217], s[24:25], 0, v[128:129]
	s_addc_u32 s61, s25, 0
	s_add_i32 s59, s45, s33
	global_load_lds_dwordx4 v[216:217], off
	ds_read_b128 v[200:203], v151 offset:20480
	v_lshl_add_u64 v[218:219], s[60:61], 0, v[132:133]
	s_mov_b32 m0, s59
	v_lshl_add_u64 v[220:221], s[26:27], 0, v[130:131]
	global_load_lds_dwordx4 v[218:219], off
	ds_read_b128 v[204:207], v151 offset:21504
	v_lshl_add_u64 v[218:219], s[60:61], 0, v[128:129]
	s_add_i32 m0, s59, 0x2000
	s_nop 0
	global_load_lds_dwordx4 v[218:219], off
	ds_read_b128 v[208:211], v151 offset:22528
	v_lshl_add_u64 v[218:219], s[26:27], 0, v[134:135]
	s_mov_b32 m0, s36
	s_nop 0
	global_load_lds_dwordx4 v[218:219], off
	ds_read_b128 v[212:215], v151 offset:23552
	s_mov_b32 m0, s37
	s_nop 0
	global_load_lds_dwordx4 v[220:221], off
	s_waitcnt vmcnt(8)
	s_waitcnt lgkmcnt(0)
	s_barrier
	s_waitcnt lgkmcnt(0)
	v_mfma_f32_16x16x32_bf16 v[60:63], v[152:155], v[184:187], 0
	v_mfma_f32_16x16x32_bf16 v[56:59], v[160:163], v[184:187], 0
	v_mfma_f32_16x16x32_bf16 v[44:47], v[152:155], v[192:195], 0
	v_mfma_f32_16x16x32_bf16 v[40:43], v[160:163], v[192:195], 0
	v_mfma_f32_16x16x32_bf16 v[28:31], v[152:155], v[200:203], 0
	v_mfma_f32_16x16x32_bf16 v[24:27], v[160:163], v[200:203], 0
	v_mfma_f32_16x16x32_bf16 v[12:15], v[152:155], v[208:211], 0
	v_mfma_f32_16x16x32_bf16 v[8:11], v[160:163], v[208:211], 0
	v_mfma_f32_16x16x32_bf16 v[60:63], v[156:159], v[188:191], v[60:63]
	v_mfma_f32_16x16x32_bf16 v[56:59], v[164:167], v[188:191], v[56:59]
	v_mfma_f32_16x16x32_bf16 v[44:47], v[156:159], v[196:199], v[44:47]
	v_mfma_f32_16x16x32_bf16 v[40:43], v[164:167], v[196:199], v[40:43]
	v_mfma_f32_16x16x32_bf16 v[28:31], v[156:159], v[204:207], v[28:31]
	v_mfma_f32_16x16x32_bf16 v[24:27], v[164:167], v[204:207], v[24:27]
	v_mfma_f32_16x16x32_bf16 v[12:15], v[156:159], v[212:215], v[12:15]
	v_mfma_f32_16x16x32_bf16 v[8:11], v[164:167], v[212:215], v[8:11]
	v_mfma_f32_16x16x32_bf16 v[52:55], v[168:171], v[184:187], 0
	v_mfma_f32_16x16x32_bf16 v[48:51], v[176:179], v[184:187], 0
	v_mfma_f32_16x16x32_bf16 v[36:39], v[168:171], v[192:195], 0
	v_mfma_f32_16x16x32_bf16 v[32:35], v[176:179], v[192:195], 0
	v_mfma_f32_16x16x32_bf16 v[20:23], v[168:171], v[200:203], 0
	v_mfma_f32_16x16x32_bf16 v[16:19], v[176:179], v[200:203], 0
	v_mfma_f32_16x16x32_bf16 v[4:7], v[168:171], v[208:211], 0
	v_mfma_f32_16x16x32_bf16 v[0:3], v[176:179], v[208:211], 0
	v_mfma_f32_16x16x32_bf16 v[52:55], v[172:175], v[188:191], v[52:55]
	v_mfma_f32_16x16x32_bf16 v[48:51], v[180:183], v[188:191], v[48:51]
	v_mfma_f32_16x16x32_bf16 v[36:39], v[172:175], v[196:199], v[36:39]
	v_mfma_f32_16x16x32_bf16 v[32:35], v[180:183], v[196:199], v[32:35]
	v_mfma_f32_16x16x32_bf16 v[20:23], v[172:175], v[204:207], v[20:23]
	v_mfma_f32_16x16x32_bf16 v[16:19], v[180:183], v[204:207], v[16:19]
	v_mfma_f32_16x16x32_bf16 v[4:7], v[172:175], v[212:215], v[4:7]
	v_mfma_f32_16x16x32_bf16 v[0:3], v[180:183], v[212:215], v[0:3]
	s_barrier
	s_add_i32 s60, 0, 0x1c000
	s_add_i32 s59, 0, 0x18000
	v_add_u32_e32 v164, s59, v148
	v_add_u32_e32 v180, s60, v148
	ds_read_b128 v[152:155], v164
	ds_read_b128 v[156:159], v164 offset:1024
	ds_read_b128 v[160:163], v164 offset:2048
	ds_read_b128 v[164:167], v164 offset:3072
	ds_read_b128 v[168:171], v180
	ds_read_b128 v[172:175], v180 offset:1024
	ds_read_b128 v[176:179], v180 offset:2048
	ds_read_b128 v[180:183], v180 offset:3072
	s_add_u32 s26, s26, 0x40000
	s_addc_u32 s27, s27, 0
	s_mov_b32 m0, s38
	v_lshl_add_u64 v[222:223], s[26:27], 0, v[134:135]
	global_load_lds_dwordx4 v[222:223], off
	ds_read_b128 v[184:187], v151 offset:32768
	ds_read_b128 v[188:191], v151 offset:33792
	ds_read_b128 v[192:195], v151 offset:34816
	ds_read_b128 v[196:199], v151 offset:35840
	ds_read_b128 v[200:203], v151 offset:36864
	ds_read_b128 v[204:207], v151 offset:37888
	ds_read_b128 v[208:211], v151 offset:38912
	ds_read_b128 v[212:215], v151 offset:39936
	v_lshl_add_u64 v[222:223], s[26:27], 0, v[130:131]
	s_mov_b32 m0, s39
	s_nop 0
	global_load_lds_dwordx4 v[222:223], off
	s_waitcnt vmcnt(8)
	s_waitcnt lgkmcnt(0)
	s_barrier
	s_waitcnt lgkmcnt(0)
	v_mfma_f32_16x16x32_bf16 v[124:127], v[152:155], v[184:187], v[124:127]
	v_mfma_f32_16x16x32_bf16 v[120:123], v[160:163], v[184:187], v[120:123]
	v_mfma_f32_16x16x32_bf16 v[108:111], v[152:155], v[192:195], v[108:111]
	v_mfma_f32_16x16x32_bf16 v[104:107], v[160:163], v[192:195], v[104:107]
	v_mfma_f32_16x16x32_bf16 v[92:95], v[152:155], v[200:203], v[92:95]
	v_mfma_f32_16x16x32_bf16 v[88:91], v[160:163], v[200:203], v[88:91]
	v_mfma_f32_16x16x32_bf16 v[76:79], v[152:155], v[208:211], v[76:79]
	v_mfma_f32_16x16x32_bf16 v[72:75], v[160:163], v[208:211], v[72:75]
	v_mfma_f32_16x16x32_bf16 v[124:127], v[156:159], v[188:191], v[124:127]
	v_mfma_f32_16x16x32_bf16 v[120:123], v[164:167], v[188:191], v[120:123]
	v_mfma_f32_16x16x32_bf16 v[108:111], v[156:159], v[196:199], v[108:111]
	v_mfma_f32_16x16x32_bf16 v[104:107], v[164:167], v[196:199], v[104:107]
	v_mfma_f32_16x16x32_bf16 v[92:95], v[156:159], v[204:207], v[92:95]
	v_mfma_f32_16x16x32_bf16 v[88:91], v[164:167], v[204:207], v[88:91]
	v_mfma_f32_16x16x32_bf16 v[76:79], v[156:159], v[212:215], v[76:79]
	v_mfma_f32_16x16x32_bf16 v[72:75], v[164:167], v[212:215], v[72:75]
	v_mfma_f32_16x16x32_bf16 v[116:119], v[168:171], v[184:187], v[116:119]
	v_mfma_f32_16x16x32_bf16 v[112:115], v[176:179], v[184:187], v[112:115]
	v_mfma_f32_16x16x32_bf16 v[100:103], v[168:171], v[192:195], v[100:103]
	v_mfma_f32_16x16x32_bf16 v[96:99], v[176:179], v[192:195], v[96:99]
	v_mfma_f32_16x16x32_bf16 v[84:87], v[168:171], v[200:203], v[84:87]
	v_mfma_f32_16x16x32_bf16 v[80:83], v[176:179], v[200:203], v[80:83]
	v_mfma_f32_16x16x32_bf16 v[68:71], v[168:171], v[208:211], v[68:71]
	v_mfma_f32_16x16x32_bf16 v[64:67], v[176:179], v[208:211], v[64:67]
	v_mfma_f32_16x16x32_bf16 v[116:119], v[172:175], v[188:191], v[116:119]
	v_mfma_f32_16x16x32_bf16 v[112:115], v[180:183], v[188:191], v[112:115]
	v_mfma_f32_16x16x32_bf16 v[100:103], v[172:175], v[196:199], v[100:103]
	v_mfma_f32_16x16x32_bf16 v[96:99], v[180:183], v[196:199], v[96:99]
	v_mfma_f32_16x16x32_bf16 v[84:87], v[172:175], v[204:207], v[84:87]
	v_mfma_f32_16x16x32_bf16 v[80:83], v[180:183], v[204:207], v[80:83]
	v_mfma_f32_16x16x32_bf16 v[68:71], v[172:175], v[212:215], v[68:71]
	v_mfma_f32_16x16x32_bf16 v[64:67], v[180:183], v[212:215], v[64:67]
	s_barrier
	ds_read_b128 v[184:187], v151 offset:49152
	ds_read_b128 v[188:191], v151 offset:50176
	s_add_i32 s26, s59, s33
	v_lshl_add_u64 v[146:147], v[146:147], 0, s[8:9]
	s_mov_b32 m0, s26
	s_nop 0
	global_load_lds_dwordx4 v[146:147], off
	ds_read_b128 v[192:195], v151 offset:51200
	ds_read_b128 v[196:199], v151 offset:52224
	s_add_i32 m0, s26, 0x2000
	s_add_u32 s24, s24, 0x40080
	v_lshl_add_u64 v[146:147], v[216:217], 0, s[8:9]
	s_addc_u32 s25, s25, 0
	s_add_i32 s26, s60, s33
	global_load_lds_dwordx4 v[146:147], off
	ds_read_b128 v[200:203], v151 offset:53248
	v_lshl_add_u64 v[146:147], s[24:25], 0, v[132:133]
	s_mov_b32 m0, s26
	s_nop 0
	global_load_lds_dwordx4 v[146:147], off
	ds_read_b128 v[204:207], v151 offset:54272
	v_lshl_add_u64 v[146:147], s[24:25], 0, v[128:129]
	s_add_i32 m0, s26, 0x2000
	s_nop 0
	global_load_lds_dwordx4 v[146:147], off
	ds_read_b128 v[208:211], v151 offset:55296
	v_lshl_add_u64 v[146:147], v[218:219], 0, s[8:9]
	s_mov_b32 m0, s41
	s_nop 0
	global_load_lds_dwordx4 v[146:147], off
	ds_read_b128 v[212:215], v151 offset:56320
	v_lshl_add_u64 v[146:147], v[220:221], 0, s[8:9]
	s_mov_b32 m0, s42
	s_nop 0
	global_load_lds_dwordx4 v[146:147], off
	s_waitcnt vmcnt(8)
	s_waitcnt lgkmcnt(0)
	s_barrier
	s_waitcnt lgkmcnt(0)
	v_mfma_f32_16x16x32_bf16 v[60:63], v[152:155], v[184:187], v[60:63]
	v_mfma_f32_16x16x32_bf16 v[56:59], v[160:163], v[184:187], v[56:59]
	v_mfma_f32_16x16x32_bf16 v[44:47], v[152:155], v[192:195], v[44:47]
	v_mfma_f32_16x16x32_bf16 v[40:43], v[160:163], v[192:195], v[40:43]
	v_mfma_f32_16x16x32_bf16 v[28:31], v[152:155], v[200:203], v[28:31]
	v_mfma_f32_16x16x32_bf16 v[24:27], v[160:163], v[200:203], v[24:27]
	v_mfma_f32_16x16x32_bf16 v[12:15], v[152:155], v[208:211], v[12:15]
	v_mfma_f32_16x16x32_bf16 v[8:11], v[160:163], v[208:211], v[8:11]
	v_mfma_f32_16x16x32_bf16 v[60:63], v[156:159], v[188:191], v[60:63]
	v_mfma_f32_16x16x32_bf16 v[56:59], v[164:167], v[188:191], v[56:59]
	v_mfma_f32_16x16x32_bf16 v[44:47], v[156:159], v[196:199], v[44:47]
	v_mfma_f32_16x16x32_bf16 v[40:43], v[164:167], v[196:199], v[40:43]
	v_mfma_f32_16x16x32_bf16 v[28:31], v[156:159], v[204:207], v[28:31]
	v_mfma_f32_16x16x32_bf16 v[24:27], v[164:167], v[204:207], v[24:27]
	v_mfma_f32_16x16x32_bf16 v[12:15], v[156:159], v[212:215], v[12:15]
	v_mfma_f32_16x16x32_bf16 v[8:11], v[164:167], v[212:215], v[8:11]
	v_mfma_f32_16x16x32_bf16 v[52:55], v[168:171], v[184:187], v[52:55]
	v_mfma_f32_16x16x32_bf16 v[48:51], v[176:179], v[184:187], v[48:51]
	v_mfma_f32_16x16x32_bf16 v[36:39], v[168:171], v[192:195], v[36:39]
	v_mfma_f32_16x16x32_bf16 v[32:35], v[176:179], v[192:195], v[32:35]
	v_mfma_f32_16x16x32_bf16 v[20:23], v[168:171], v[200:203], v[20:23]
	v_mfma_f32_16x16x32_bf16 v[16:19], v[176:179], v[200:203], v[16:19]
	v_mfma_f32_16x16x32_bf16 v[4:7], v[168:171], v[208:211], v[4:7]
	v_mfma_f32_16x16x32_bf16 v[0:3], v[176:179], v[208:211], v[0:3]
	v_mfma_f32_16x16x32_bf16 v[52:55], v[172:175], v[188:191], v[52:55]
	v_mfma_f32_16x16x32_bf16 v[48:51], v[180:183], v[188:191], v[48:51]
	v_mfma_f32_16x16x32_bf16 v[36:39], v[172:175], v[196:199], v[36:39]
	v_mfma_f32_16x16x32_bf16 v[32:35], v[180:183], v[196:199], v[32:35]
	v_mfma_f32_16x16x32_bf16 v[20:23], v[172:175], v[204:207], v[20:23]
	v_mfma_f32_16x16x32_bf16 v[16:19], v[180:183], v[204:207], v[16:19]
	v_mfma_f32_16x16x32_bf16 v[4:7], v[172:175], v[212:215], v[4:7]
	v_mfma_f32_16x16x32_bf16 v[0:3], v[180:183], v[212:215], v[0:3]
	s_barrier
	s_add_i32 s58, s58, 2
	s_add_u32 s56, s56, 0x100
	s_addc_u32 s57, s57, 0
	s_add_u32 s22, s22, 0x100
	s_addc_u32 s23, s23, 0
	s_cmp_lt_u32 s58, 14
.LBB12_9:
	ds_read_b128 v[152:155], v149
	ds_read_b128 v[156:159], v149 offset:1024
	ds_read_b128 v[160:163], v149 offset:2048
	ds_read_b128 v[164:167], v149 offset:3072
	ds_read_b128 v[168:171], v150
	ds_read_b128 v[172:175], v150 offset:1024
	ds_read_b128 v[176:179], v150 offset:2048
	ds_read_b128 v[180:183], v150 offset:3072
	s_add_u32 s24, s22, 0xfffc0080
	s_addc_u32 s25, s23, -1
	s_cmp_eq_u32 s58, 12
	s_cselect_b32 s27, s15, s25
	s_cselect_b32 s26, s54, s24
	s_cselect_b32 s25, s13, s57
	s_cselect_b32 s24, s55, s56
	v_lshl_add_u64 v[146:147], s[22:23], 0, v[140:141]
	s_add_i32 m0, s36, 0xc000
	s_nop 0
	global_load_lds_dwordx4 v[146:147], off
	ds_read_b128 v[184:187], v151
	ds_read_b128 v[188:191], v151 offset:1024
	ds_read_b128 v[192:195], v151 offset:2048
	ds_read_b128 v[196:199], v151 offset:3072
	ds_read_b128 v[200:203], v151 offset:4096
	ds_read_b128 v[204:207], v151 offset:5120
	ds_read_b128 v[208:211], v151 offset:6144
	ds_read_b128 v[212:215], v151 offset:7168
	v_lshl_add_u64 v[146:147], s[22:23], 0, v[138:139]
	s_add_i32 m0, s36, 0xe000
	s_nop 0
	global_load_lds_dwordx4 v[146:147], off
	s_waitcnt vmcnt(8)
	s_waitcnt lgkmcnt(0)
	s_barrier
	s_waitcnt lgkmcnt(0)
	v_mfma_f32_16x16x32_bf16 v[124:127], v[152:155], v[184:187], v[124:127]
	v_mfma_f32_16x16x32_bf16 v[120:123], v[160:163], v[184:187], v[120:123]
	v_mfma_f32_16x16x32_bf16 v[108:111], v[152:155], v[192:195], v[108:111]
	v_mfma_f32_16x16x32_bf16 v[104:107], v[160:163], v[192:195], v[104:107]
	v_mfma_f32_16x16x32_bf16 v[92:95], v[152:155], v[200:203], v[92:95]
	v_mfma_f32_16x16x32_bf16 v[88:91], v[160:163], v[200:203], v[88:91]
	v_mfma_f32_16x16x32_bf16 v[76:79], v[152:155], v[208:211], v[76:79]
	v_mfma_f32_16x16x32_bf16 v[72:75], v[160:163], v[208:211], v[72:75]
	v_mfma_f32_16x16x32_bf16 v[124:127], v[156:159], v[188:191], v[124:127]
	v_mfma_f32_16x16x32_bf16 v[120:123], v[164:167], v[188:191], v[120:123]
	v_mfma_f32_16x16x32_bf16 v[108:111], v[156:159], v[196:199], v[108:111]
	v_mfma_f32_16x16x32_bf16 v[104:107], v[164:167], v[196:199], v[104:107]
	v_mfma_f32_16x16x32_bf16 v[92:95], v[156:159], v[204:207], v[92:95]
	v_mfma_f32_16x16x32_bf16 v[88:91], v[164:167], v[204:207], v[88:91]
	v_mfma_f32_16x16x32_bf16 v[76:79], v[156:159], v[212:215], v[76:79]
	v_mfma_f32_16x16x32_bf16 v[72:75], v[164:167], v[212:215], v[72:75]
	v_mfma_f32_16x16x32_bf16 v[116:119], v[168:171], v[184:187], v[116:119]
	v_mfma_f32_16x16x32_bf16 v[112:115], v[176:179], v[184:187], v[112:115]
	v_mfma_f32_16x16x32_bf16 v[100:103], v[168:171], v[192:195], v[100:103]
	v_mfma_f32_16x16x32_bf16 v[96:99], v[176:179], v[192:195], v[96:99]
	v_mfma_f32_16x16x32_bf16 v[84:87], v[168:171], v[200:203], v[84:87]
	v_mfma_f32_16x16x32_bf16 v[80:83], v[176:179], v[200:203], v[80:83]
	v_mfma_f32_16x16x32_bf16 v[68:71], v[168:171], v[208:211], v[68:71]
	v_mfma_f32_16x16x32_bf16 v[64:67], v[176:179], v[208:211], v[64:67]
	v_mfma_f32_16x16x32_bf16 v[116:119], v[172:175], v[188:191], v[116:119]
	v_mfma_f32_16x16x32_bf16 v[112:115], v[180:183], v[188:191], v[112:115]
	v_mfma_f32_16x16x32_bf16 v[100:103], v[172:175], v[196:199], v[100:103]
	v_mfma_f32_16x16x32_bf16 v[96:99], v[180:183], v[196:199], v[96:99]
	v_mfma_f32_16x16x32_bf16 v[84:87], v[172:175], v[204:207], v[84:87]
	v_mfma_f32_16x16x32_bf16 v[80:83], v[180:183], v[204:207], v[80:83]
	v_mfma_f32_16x16x32_bf16 v[68:71], v[172:175], v[212:215], v[68:71]
	v_mfma_f32_16x16x32_bf16 v[64:67], v[180:183], v[212:215], v[64:67]
	s_barrier
	ds_read_b128 v[184:187], v151 offset:16384
	ds_read_b128 v[188:191], v151 offset:17408
	s_add_i32 s59, s44, s33
	v_lshl_add_u64 v[146:147], s[24:25], 0, v[132:133]
	s_mov_b32 m0, s59
	s_nop 0
	global_load_lds_dwordx4 v[146:147], off
	ds_read_b128 v[192:195], v151 offset:18432
	ds_read_b128 v[196:199], v151 offset:19456
	s_add_i32 m0, s59, 0x2000
	s_add_u32 s60, s24, 0x40000
	v_lshl_add_u64 v[216:217], s[24:25], 0, v[128:129]
	s_addc_u32 s61, s25, 0
	s_add_i32 s59, s45, s33
	global_load_lds_dwordx4 v[216:217], off
	ds_read_b128 v[200:203], v151 offset:20480
	v_lshl_add_u64 v[218:219], s[60:61], 0, v[132:133]
	s_mov_b32 m0, s59
	v_lshl_add_u64 v[220:221], s[26:27], 0, v[130:131]
	global_load_lds_dwordx4 v[218:219], off
	ds_read_b128 v[204:207], v151 offset:21504
	v_lshl_add_u64 v[218:219], s[60:61], 0, v[128:129]
	s_add_i32 m0, s59, 0x2000
	s_nop 0
	global_load_lds_dwordx4 v[218:219], off
	ds_read_b128 v[208:211], v151 offset:22528
	v_lshl_add_u64 v[218:219], s[26:27], 0, v[134:135]
	s_mov_b32 m0, s36
	s_nop 0
	global_load_lds_dwordx4 v[218:219], off
	ds_read_b128 v[212:215], v151 offset:23552
	s_mov_b32 m0, s37
	s_nop 0
	global_load_lds_dwordx4 v[220:221], off
	s_waitcnt vmcnt(8)
	s_waitcnt lgkmcnt(0)
	s_barrier
	s_waitcnt lgkmcnt(0)
	v_mfma_f32_16x16x32_bf16 v[60:63], v[152:155], v[184:187], v[60:63]
	v_mfma_f32_16x16x32_bf16 v[56:59], v[160:163], v[184:187], v[56:59]
	v_mfma_f32_16x16x32_bf16 v[44:47], v[152:155], v[192:195], v[44:47]
	v_mfma_f32_16x16x32_bf16 v[40:43], v[160:163], v[192:195], v[40:43]
	v_mfma_f32_16x16x32_bf16 v[28:31], v[152:155], v[200:203], v[28:31]
	v_mfma_f32_16x16x32_bf16 v[24:27], v[160:163], v[200:203], v[24:27]
	v_mfma_f32_16x16x32_bf16 v[12:15], v[152:155], v[208:211], v[12:15]
	v_mfma_f32_16x16x32_bf16 v[8:11], v[160:163], v[208:211], v[8:11]
	v_mfma_f32_16x16x32_bf16 v[60:63], v[156:159], v[188:191], v[60:63]
	v_mfma_f32_16x16x32_bf16 v[56:59], v[164:167], v[188:191], v[56:59]
	v_mfma_f32_16x16x32_bf16 v[44:47], v[156:159], v[196:199], v[44:47]
	v_mfma_f32_16x16x32_bf16 v[40:43], v[164:167], v[196:199], v[40:43]
	v_mfma_f32_16x16x32_bf16 v[28:31], v[156:159], v[204:207], v[28:31]
	v_mfma_f32_16x16x32_bf16 v[24:27], v[164:167], v[204:207], v[24:27]
	v_mfma_f32_16x16x32_bf16 v[12:15], v[156:159], v[212:215], v[12:15]
	v_mfma_f32_16x16x32_bf16 v[8:11], v[164:167], v[212:215], v[8:11]
	v_mfma_f32_16x16x32_bf16 v[52:55], v[168:171], v[184:187], v[52:55]
	v_mfma_f32_16x16x32_bf16 v[48:51], v[176:179], v[184:187], v[48:51]
	v_mfma_f32_16x16x32_bf16 v[36:39], v[168:171], v[192:195], v[36:39]
	v_mfma_f32_16x16x32_bf16 v[32:35], v[176:179], v[192:195], v[32:35]
	v_mfma_f32_16x16x32_bf16 v[20:23], v[168:171], v[200:203], v[20:23]
	v_mfma_f32_16x16x32_bf16 v[16:19], v[176:179], v[200:203], v[16:19]
	v_mfma_f32_16x16x32_bf16 v[4:7], v[168:171], v[208:211], v[4:7]
	v_mfma_f32_16x16x32_bf16 v[0:3], v[176:179], v[208:211], v[0:3]
	v_mfma_f32_16x16x32_bf16 v[52:55], v[172:175], v[188:191], v[52:55]
	v_mfma_f32_16x16x32_bf16 v[48:51], v[180:183], v[188:191], v[48:51]
	v_mfma_f32_16x16x32_bf16 v[36:39], v[172:175], v[196:199], v[36:39]
	v_mfma_f32_16x16x32_bf16 v[32:35], v[180:183], v[196:199], v[32:35]
	v_mfma_f32_16x16x32_bf16 v[20:23], v[172:175], v[204:207], v[20:23]
	v_mfma_f32_16x16x32_bf16 v[16:19], v[180:183], v[204:207], v[16:19]
	v_mfma_f32_16x16x32_bf16 v[4:7], v[172:175], v[212:215], v[4:7]
	v_mfma_f32_16x16x32_bf16 v[0:3], v[180:183], v[212:215], v[0:3]
	s_barrier
	s_add_i32 s60, 0, 0x1c000
	s_add_i32 s59, 0, 0x18000
	v_add_u32_e32 v164, s59, v148
	v_add_u32_e32 v180, s60, v148
	ds_read_b128 v[152:155], v164
	ds_read_b128 v[156:159], v164 offset:1024
	ds_read_b128 v[160:163], v164 offset:2048
	ds_read_b128 v[164:167], v164 offset:3072
	ds_read_b128 v[168:171], v180
	ds_read_b128 v[172:175], v180 offset:1024
	ds_read_b128 v[176:179], v180 offset:2048
	ds_read_b128 v[180:183], v180 offset:3072
	s_add_u32 s26, s26, 0x40000
	s_addc_u32 s27, s27, 0
	s_mov_b32 m0, s38
	v_lshl_add_u64 v[222:223], s[26:27], 0, v[134:135]
	global_load_lds_dwordx4 v[222:223], off
	ds_read_b128 v[184:187], v151 offset:32768
	ds_read_b128 v[188:191], v151 offset:33792
	ds_read_b128 v[192:195], v151 offset:34816
	ds_read_b128 v[196:199], v151 offset:35840
	ds_read_b128 v[200:203], v151 offset:36864
	ds_read_b128 v[204:207], v151 offset:37888
	ds_read_b128 v[208:211], v151 offset:38912
	ds_read_b128 v[212:215], v151 offset:39936
	v_lshl_add_u64 v[222:223], s[26:27], 0, v[130:131]
	s_mov_b32 m0, s39
	s_nop 0
	global_load_lds_dwordx4 v[222:223], off
	s_waitcnt vmcnt(8)
	s_waitcnt lgkmcnt(0)
	s_barrier
	s_waitcnt lgkmcnt(0)
	v_mfma_f32_16x16x32_bf16 v[124:127], v[152:155], v[184:187], v[124:127]
	v_mfma_f32_16x16x32_bf16 v[120:123], v[160:163], v[184:187], v[120:123]
	v_mfma_f32_16x16x32_bf16 v[108:111], v[152:155], v[192:195], v[108:111]
	v_mfma_f32_16x16x32_bf16 v[104:107], v[160:163], v[192:195], v[104:107]
	v_mfma_f32_16x16x32_bf16 v[92:95], v[152:155], v[200:203], v[92:95]
	v_mfma_f32_16x16x32_bf16 v[88:91], v[160:163], v[200:203], v[88:91]
	v_mfma_f32_16x16x32_bf16 v[76:79], v[152:155], v[208:211], v[76:79]
	v_mfma_f32_16x16x32_bf16 v[72:75], v[160:163], v[208:211], v[72:75]
	v_mfma_f32_16x16x32_bf16 v[124:127], v[156:159], v[188:191], v[124:127]
	v_mfma_f32_16x16x32_bf16 v[120:123], v[164:167], v[188:191], v[120:123]
	v_mfma_f32_16x16x32_bf16 v[108:111], v[156:159], v[196:199], v[108:111]
	v_mfma_f32_16x16x32_bf16 v[104:107], v[164:167], v[196:199], v[104:107]
	v_mfma_f32_16x16x32_bf16 v[92:95], v[156:159], v[204:207], v[92:95]
	v_mfma_f32_16x16x32_bf16 v[88:91], v[164:167], v[204:207], v[88:91]
	v_mfma_f32_16x16x32_bf16 v[76:79], v[156:159], v[212:215], v[76:79]
	v_mfma_f32_16x16x32_bf16 v[72:75], v[164:167], v[212:215], v[72:75]
	v_mfma_f32_16x16x32_bf16 v[116:119], v[168:171], v[184:187], v[116:119]
	v_mfma_f32_16x16x32_bf16 v[112:115], v[176:179], v[184:187], v[112:115]
	v_mfma_f32_16x16x32_bf16 v[100:103], v[168:171], v[192:195], v[100:103]
	v_mfma_f32_16x16x32_bf16 v[96:99], v[176:179], v[192:195], v[96:99]
	v_mfma_f32_16x16x32_bf16 v[84:87], v[168:171], v[200:203], v[84:87]
	v_mfma_f32_16x16x32_bf16 v[80:83], v[176:179], v[200:203], v[80:83]
	v_mfma_f32_16x16x32_bf16 v[68:71], v[168:171], v[208:211], v[68:71]
	v_mfma_f32_16x16x32_bf16 v[64:67], v[176:179], v[208:211], v[64:67]
	v_mfma_f32_16x16x32_bf16 v[116:119], v[172:175], v[188:191], v[116:119]
	v_mfma_f32_16x16x32_bf16 v[112:115], v[180:183], v[188:191], v[112:115]
	v_mfma_f32_16x16x32_bf16 v[100:103], v[172:175], v[196:199], v[100:103]
	v_mfma_f32_16x16x32_bf16 v[96:99], v[180:183], v[196:199], v[96:99]
	v_mfma_f32_16x16x32_bf16 v[84:87], v[172:175], v[204:207], v[84:87]
	v_mfma_f32_16x16x32_bf16 v[80:83], v[180:183], v[204:207], v[80:83]
	v_mfma_f32_16x16x32_bf16 v[68:71], v[172:175], v[212:215], v[68:71]
	v_mfma_f32_16x16x32_bf16 v[64:67], v[180:183], v[212:215], v[64:67]
	s_barrier
	ds_read_b128 v[184:187], v151 offset:49152
	ds_read_b128 v[188:191], v151 offset:50176
	s_add_i32 s26, s59, s33
	v_lshl_add_u64 v[146:147], v[146:147], 0, s[8:9]
	s_mov_b32 m0, s26
	s_nop 0
	global_load_lds_dwordx4 v[146:147], off
	ds_read_b128 v[192:195], v151 offset:51200
	ds_read_b128 v[196:199], v151 offset:52224
	s_add_i32 m0, s26, 0x2000
	s_add_u32 s24, s24, 0x40080
	v_lshl_add_u64 v[146:147], v[216:217], 0, s[8:9]
	s_addc_u32 s25, s25, 0
	s_add_i32 s26, s60, s33
	global_load_lds_dwordx4 v[146:147], off
	ds_read_b128 v[200:203], v151 offset:53248
	v_lshl_add_u64 v[146:147], s[24:25], 0, v[132:133]
	s_mov_b32 m0, s26
	s_nop 0
	global_load_lds_dwordx4 v[146:147], off
	ds_read_b128 v[204:207], v151 offset:54272
	v_lshl_add_u64 v[146:147], s[24:25], 0, v[128:129]
	s_add_i32 m0, s26, 0x2000
	s_nop 0
	global_load_lds_dwordx4 v[146:147], off
	ds_read_b128 v[208:211], v151 offset:55296
	v_lshl_add_u64 v[146:147], v[218:219], 0, s[8:9]
	s_mov_b32 m0, s41
	s_nop 0
	global_load_lds_dwordx4 v[146:147], off
	ds_read_b128 v[212:215], v151 offset:56320
	v_lshl_add_u64 v[146:147], v[220:221], 0, s[8:9]
	s_mov_b32 m0, s42
	s_nop 0
	global_load_lds_dwordx4 v[146:147], off
	s_waitcnt vmcnt(8)
	s_waitcnt lgkmcnt(0)
	s_barrier
	s_waitcnt lgkmcnt(0)
	v_mfma_f32_16x16x32_bf16 v[60:63], v[152:155], v[184:187], v[60:63]
	v_mfma_f32_16x16x32_bf16 v[56:59], v[160:163], v[184:187], v[56:59]
	v_mfma_f32_16x16x32_bf16 v[44:47], v[152:155], v[192:195], v[44:47]
	v_mfma_f32_16x16x32_bf16 v[40:43], v[160:163], v[192:195], v[40:43]
	v_mfma_f32_16x16x32_bf16 v[28:31], v[152:155], v[200:203], v[28:31]
	v_mfma_f32_16x16x32_bf16 v[24:27], v[160:163], v[200:203], v[24:27]
	v_mfma_f32_16x16x32_bf16 v[12:15], v[152:155], v[208:211], v[12:15]
	v_mfma_f32_16x16x32_bf16 v[8:11], v[160:163], v[208:211], v[8:11]
	v_mfma_f32_16x16x32_bf16 v[60:63], v[156:159], v[188:191], v[60:63]
	v_mfma_f32_16x16x32_bf16 v[56:59], v[164:167], v[188:191], v[56:59]
	v_mfma_f32_16x16x32_bf16 v[44:47], v[156:159], v[196:199], v[44:47]
	v_mfma_f32_16x16x32_bf16 v[40:43], v[164:167], v[196:199], v[40:43]
	v_mfma_f32_16x16x32_bf16 v[28:31], v[156:159], v[204:207], v[28:31]
	v_mfma_f32_16x16x32_bf16 v[24:27], v[164:167], v[204:207], v[24:27]
	v_mfma_f32_16x16x32_bf16 v[12:15], v[156:159], v[212:215], v[12:15]
	v_mfma_f32_16x16x32_bf16 v[8:11], v[164:167], v[212:215], v[8:11]
	v_mfma_f32_16x16x32_bf16 v[52:55], v[168:171], v[184:187], v[52:55]
	v_mfma_f32_16x16x32_bf16 v[48:51], v[176:179], v[184:187], v[48:51]
	v_mfma_f32_16x16x32_bf16 v[36:39], v[168:171], v[192:195], v[36:39]
	v_mfma_f32_16x16x32_bf16 v[32:35], v[176:179], v[192:195], v[32:35]
	v_mfma_f32_16x16x32_bf16 v[20:23], v[168:171], v[200:203], v[20:23]
	v_mfma_f32_16x16x32_bf16 v[16:19], v[176:179], v[200:203], v[16:19]
	v_mfma_f32_16x16x32_bf16 v[4:7], v[168:171], v[208:211], v[4:7]
	v_mfma_f32_16x16x32_bf16 v[0:3], v[176:179], v[208:211], v[0:3]
	v_mfma_f32_16x16x32_bf16 v[52:55], v[172:175], v[188:191], v[52:55]
	v_mfma_f32_16x16x32_bf16 v[48:51], v[180:183], v[188:191], v[48:51]
	v_mfma_f32_16x16x32_bf16 v[36:39], v[172:175], v[196:199], v[36:39]
	v_mfma_f32_16x16x32_bf16 v[32:35], v[180:183], v[196:199], v[32:35]
	v_mfma_f32_16x16x32_bf16 v[20:23], v[172:175], v[204:207], v[20:23]
	v_mfma_f32_16x16x32_bf16 v[16:19], v[180:183], v[204:207], v[16:19]
	v_mfma_f32_16x16x32_bf16 v[4:7], v[172:175], v[212:215], v[4:7]
	v_mfma_f32_16x16x32_bf16 v[0:3], v[180:183], v[212:215], v[0:3]
	s_barrier
	s_add_i32 s58, s58, 2
	s_add_u32 s56, s56, 0x100
	s_addc_u32 s57, s57, 0
	s_add_u32 s22, s22, 0x100
	s_addc_u32 s23, s23, 0
	s_cmp_lt_u32 s58, 14
	s_cbranch_scc1 .LBB12_9
	s_andn2_b64 vcc, exec, s[10:11]
	s_cbranch_vccnz .LBB12_12
	s_barrier

.LBB13_19:
	s_ashr_i32 s17, s16, 31
	v_cmp_lt_i64_e32 vcc, s[0:1], v[142:143]
	s_lshl_b64 s[0:1], s[16:17], 21
	s_add_u32 s18, s33, s0
	s_addc_u32 s19, s34, s1
	s_and_b64 s[0:1], vcc, exec
	s_cselect_b32 s17, s19, s27
	s_cselect_b32 s53, s18, s26
	s_ashr_i32 s15, s14, 31
	s_lshl_b64 s[0:1], s[14:15], 21
	s_add_u32 s20, s4, s0
	s_addc_u32 s21, s5, s1
	s_and_b64 s[0:1], vcc, exec
	s_cselect_b32 s15, s21, s25
	s_cselect_b32 s54, s20, s24
	s_add_u32 s55, s24, 0x100
	s_addc_u32 s56, s25, 0
	s_add_u32 s24, s26, 0x100080
	s_addc_u32 s25, s27, 0
	s_mov_b32 s57, -2
	ds_read_b128 v[152:155], v149
	ds_read_b128 v[156:159], v149 offset:1024
	ds_read_b128 v[160:163], v149 offset:2048
	ds_read_b128 v[164:167], v149 offset:3072
	ds_read_b128 v[168:171], v150
	ds_read_b128 v[172:175], v150 offset:1024
	ds_read_b128 v[176:179], v150 offset:2048
	ds_read_b128 v[180:183], v150 offset:3072
	s_add_u32 s26, s24, 0xfff00080
	s_addc_u32 s27, s25, -1
	s_cmp_eq_u32 s57, 60
	s_cselect_b32 s29, s17, s27
	s_cselect_b32 s28, s53, s26
	s_cselect_b32 s27, s15, s56
	s_cselect_b32 s26, s54, s55
	v_lshl_add_u64 v[146:147], s[24:25], 0, v[140:141]
	s_add_i32 m0, s35, 0xc000
	s_nop 0
	global_load_lds_dwordx4 v[146:147], off
	ds_read_b128 v[184:187], v151
	ds_read_b128 v[188:191], v151 offset:1024
	ds_read_b128 v[192:195], v151 offset:2048
	ds_read_b128 v[196:199], v151 offset:3072
	ds_read_b128 v[200:203], v151 offset:4096
	ds_read_b128 v[204:207], v151 offset:5120
	ds_read_b128 v[208:211], v151 offset:6144
	ds_read_b128 v[212:215], v151 offset:7168
	v_lshl_add_u64 v[146:147], s[24:25], 0, v[138:139]
	s_add_i32 m0, s35, 0xe000
	s_nop 0
	global_load_lds_dwordx4 v[146:147], off
	s_waitcnt vmcnt(8)
	s_waitcnt lgkmcnt(0)
	s_barrier
	s_waitcnt lgkmcnt(0)
	v_mfma_f32_16x16x32_bf16 v[124:127], v[152:155], v[184:187], 0
	v_mfma_f32_16x16x32_bf16 v[120:123], v[160:163], v[184:187], 0
	v_mfma_f32_16x16x32_bf16 v[116:119], v[152:155], v[192:195], 0
	v_mfma_f32_16x16x32_bf16 v[108:111], v[160:163], v[192:195], 0
	v_mfma_f32_16x16x32_bf16 v[100:103], v[152:155], v[200:203], 0
	v_mfma_f32_16x16x32_bf16 v[92:95], v[160:163], v[200:203], 0
	v_mfma_f32_16x16x32_bf16 v[84:87], v[152:155], v[208:211], 0
	v_mfma_f32_16x16x32_bf16 v[76:79], v[160:163], v[208:211], 0
	v_mfma_f32_16x16x32_bf16 v[124:127], v[156:159], v[188:191], v[124:127]
	v_mfma_f32_16x16x32_bf16 v[120:123], v[164:167], v[188:191], v[120:123]
	v_mfma_f32_16x16x32_bf16 v[116:119], v[156:159], v[196:199], v[116:119]
	v_mfma_f32_16x16x32_bf16 v[108:111], v[164:167], v[196:199], v[108:111]
	v_mfma_f32_16x16x32_bf16 v[100:103], v[156:159], v[204:207], v[100:103]
	v_mfma_f32_16x16x32_bf16 v[92:95], v[164:167], v[204:207], v[92:95]
	v_mfma_f32_16x16x32_bf16 v[84:87], v[156:159], v[212:215], v[84:87]
	v_mfma_f32_16x16x32_bf16 v[76:79], v[164:167], v[212:215], v[76:79]
	v_mfma_f32_16x16x32_bf16 v[112:115], v[168:171], v[184:187], 0
	v_mfma_f32_16x16x32_bf16 v[104:107], v[176:179], v[184:187], 0
	v_mfma_f32_16x16x32_bf16 v[96:99], v[168:171], v[192:195], 0
	v_mfma_f32_16x16x32_bf16 v[88:91], v[176:179], v[192:195], 0
	v_mfma_f32_16x16x32_bf16 v[80:83], v[168:171], v[200:203], 0
	v_mfma_f32_16x16x32_bf16 v[72:75], v[176:179], v[200:203], 0
	v_mfma_f32_16x16x32_bf16 v[68:71], v[168:171], v[208:211], 0
	v_mfma_f32_16x16x32_bf16 v[64:67], v[176:179], v[208:211], 0
	v_mfma_f32_16x16x32_bf16 v[112:115], v[172:175], v[188:191], v[112:115]
	v_mfma_f32_16x16x32_bf16 v[104:107], v[180:183], v[188:191], v[104:107]
	v_mfma_f32_16x16x32_bf16 v[96:99], v[172:175], v[196:199], v[96:99]
	v_mfma_f32_16x16x32_bf16 v[88:91], v[180:183], v[196:199], v[88:91]
	v_mfma_f32_16x16x32_bf16 v[80:83], v[172:175], v[204:207], v[80:83]
	v_mfma_f32_16x16x32_bf16 v[72:75], v[180:183], v[204:207], v[72:75]
	v_mfma_f32_16x16x32_bf16 v[68:71], v[172:175], v[212:215], v[68:71]
	v_mfma_f32_16x16x32_bf16 v[64:67], v[180:183], v[212:215], v[64:67]
	s_barrier
	ds_read_b128 v[184:187], v151 offset:16384
	ds_read_b128 v[188:191], v151 offset:17408
	s_add_i32 s58, s46, s31
	v_lshl_add_u64 v[146:147], s[26:27], 0, v[130:131]
	s_mov_b32 m0, s58
	s_nop 0
	global_load_lds_dwordx4 v[146:147], off
	ds_read_b128 v[192:195], v151 offset:18432
	ds_read_b128 v[196:199], v151 offset:19456
	s_add_i32 m0, s58, 0x2000
	s_add_u32 s58, s26, 0x100000
	v_lshl_add_u64 v[216:217], s[26:27], 0, v[134:135]
	s_addc_u32 s59, s27, 0
	s_add_i32 s60, s47, s31
	global_load_lds_dwordx4 v[216:217], off
	ds_read_b128 v[200:203], v151 offset:20480
	v_lshl_add_u64 v[218:219], s[58:59], 0, v[130:131]
	s_mov_b32 m0, s60
	v_lshl_add_u64 v[220:221], s[28:29], 0, v[132:133]
	global_load_lds_dwordx4 v[218:219], off
	ds_read_b128 v[204:207], v151 offset:21504
	v_lshl_add_u64 v[218:219], s[58:59], 0, v[134:135]
	s_add_i32 m0, s60, 0x2000
	s_nop 0
	global_load_lds_dwordx4 v[218:219], off
	ds_read_b128 v[208:211], v151 offset:22528
	v_lshl_add_u64 v[218:219], s[28:29], 0, v[128:129]
	s_mov_b32 m0, s35
	s_nop 0
	global_load_lds_dwordx4 v[218:219], off
	ds_read_b128 v[212:215], v151 offset:23552
	s_mov_b32 m0, s36
	s_nop 0
	global_load_lds_dwordx4 v[220:221], off
	s_waitcnt vmcnt(8)
	s_waitcnt lgkmcnt(0)
	s_barrier
	s_waitcnt lgkmcnt(0)
	v_mfma_f32_16x16x32_bf16 v[60:63], v[152:155], v[184:187], 0
	v_mfma_f32_16x16x32_bf16 v[56:59], v[160:163], v[184:187], 0
	v_mfma_f32_16x16x32_bf16 v[52:55], v[152:155], v[192:195], 0
	v_mfma_f32_16x16x32_bf16 v[44:47], v[160:163], v[192:195], 0
	v_mfma_f32_16x16x32_bf16 v[36:39], v[152:155], v[200:203], 0
	v_mfma_f32_16x16x32_bf16 v[28:31], v[160:163], v[200:203], 0
	v_mfma_f32_16x16x32_bf16 v[20:23], v[152:155], v[208:211], 0
	v_mfma_f32_16x16x32_bf16 v[12:15], v[160:163], v[208:211], 0
	v_mfma_f32_16x16x32_bf16 v[60:63], v[156:159], v[188:191], v[60:63]
	v_mfma_f32_16x16x32_bf16 v[56:59], v[164:167], v[188:191], v[56:59]
	v_mfma_f32_16x16x32_bf16 v[52:55], v[156:159], v[196:199], v[52:55]
	v_mfma_f32_16x16x32_bf16 v[44:47], v[164:167], v[196:199], v[44:47]
	v_mfma_f32_16x16x32_bf16 v[36:39], v[156:159], v[204:207], v[36:39]
	v_mfma_f32_16x16x32_bf16 v[28:31], v[164:167], v[204:207], v[28:31]
	v_mfma_f32_16x16x32_bf16 v[20:23], v[156:159], v[212:215], v[20:23]
	v_mfma_f32_16x16x32_bf16 v[12:15], v[164:167], v[212:215], v[12:15]
	v_mfma_f32_16x16x32_bf16 v[48:51], v[168:171], v[184:187], 0
	v_mfma_f32_16x16x32_bf16 v[40:43], v[176:179], v[184:187], 0
	v_mfma_f32_16x16x32_bf16 v[32:35], v[168:171], v[192:195], 0
	v_mfma_f32_16x16x32_bf16 v[24:27], v[176:179], v[192:195], 0
	v_mfma_f32_16x16x32_bf16 v[16:19], v[168:171], v[200:203], 0
	v_mfma_f32_16x16x32_bf16 v[8:11], v[176:179], v[200:203], 0
	v_mfma_f32_16x16x32_bf16 v[4:7], v[168:171], v[208:211], 0
	v_mfma_f32_16x16x32_bf16 v[0:3], v[176:179], v[208:211], 0
	v_mfma_f32_16x16x32_bf16 v[48:51], v[172:175], v[188:191], v[48:51]
	v_mfma_f32_16x16x32_bf16 v[40:43], v[180:183], v[188:191], v[40:43]
	v_mfma_f32_16x16x32_bf16 v[32:35], v[172:175], v[196:199], v[32:35]
	v_mfma_f32_16x16x32_bf16 v[24:27], v[180:183], v[196:199], v[24:27]
	v_mfma_f32_16x16x32_bf16 v[16:19], v[172:175], v[204:207], v[16:19]
	v_mfma_f32_16x16x32_bf16 v[8:11], v[180:183], v[204:207], v[8:11]
	v_mfma_f32_16x16x32_bf16 v[4:7], v[172:175], v[212:215], v[4:7]
	v_mfma_f32_16x16x32_bf16 v[0:3], v[180:183], v[212:215], v[0:3]
	s_barrier
	s_add_i32 s59, 0, 0x1c000
	s_add_i32 s58, 0, 0x18000
	v_add_u32_e32 v164, s58, v148
	v_add_u32_e32 v180, s59, v148
	ds_read_b128 v[152:155], v164
	ds_read_b128 v[156:159], v164 offset:1024
	ds_read_b128 v[160:163], v164 offset:2048
	ds_read_b128 v[164:167], v164 offset:3072
	ds_read_b128 v[168:171], v180
	ds_read_b128 v[172:175], v180 offset:1024
	ds_read_b128 v[176:179], v180 offset:2048
	ds_read_b128 v[180:183], v180 offset:3072
	s_add_u32 s28, s28, 0x100000
	s_addc_u32 s29, s29, 0
	s_mov_b32 m0, s37
	v_lshl_add_u64 v[222:223], s[28:29], 0, v[128:129]
	global_load_lds_dwordx4 v[222:223], off
	ds_read_b128 v[184:187], v151 offset:32768
	ds_read_b128 v[188:191], v151 offset:33792
	ds_read_b128 v[192:195], v151 offset:34816
	ds_read_b128 v[196:199], v151 offset:35840
	ds_read_b128 v[200:203], v151 offset:36864
	ds_read_b128 v[204:207], v151 offset:37888
	ds_read_b128 v[208:211], v151 offset:38912
	ds_read_b128 v[212:215], v151 offset:39936
	v_lshl_add_u64 v[222:223], s[28:29], 0, v[132:133]
	s_mov_b32 m0, s38
	s_nop 0
	global_load_lds_dwordx4 v[222:223], off
	s_waitcnt vmcnt(8)
	s_waitcnt lgkmcnt(0)
	s_barrier
	s_waitcnt lgkmcnt(0)
	v_mfma_f32_16x16x32_bf16 v[124:127], v[152:155], v[184:187], v[124:127]
	v_mfma_f32_16x16x32_bf16 v[120:123], v[160:163], v[184:187], v[120:123]
	v_mfma_f32_16x16x32_bf16 v[116:119], v[152:155], v[192:195], v[116:119]
	v_mfma_f32_16x16x32_bf16 v[108:111], v[160:163], v[192:195], v[108:111]
	v_mfma_f32_16x16x32_bf16 v[100:103], v[152:155], v[200:203], v[100:103]
	v_mfma_f32_16x16x32_bf16 v[92:95], v[160:163], v[200:203], v[92:95]
	v_mfma_f32_16x16x32_bf16 v[84:87], v[152:155], v[208:211], v[84:87]
	v_mfma_f32_16x16x32_bf16 v[76:79], v[160:163], v[208:211], v[76:79]
	v_mfma_f32_16x16x32_bf16 v[124:127], v[156:159], v[188:191], v[124:127]
	v_mfma_f32_16x16x32_bf16 v[120:123], v[164:167], v[188:191], v[120:123]
	v_mfma_f32_16x16x32_bf16 v[116:119], v[156:159], v[196:199], v[116:119]
	v_mfma_f32_16x16x32_bf16 v[108:111], v[164:167], v[196:199], v[108:111]
	v_mfma_f32_16x16x32_bf16 v[100:103], v[156:159], v[204:207], v[100:103]
	v_mfma_f32_16x16x32_bf16 v[92:95], v[164:167], v[204:207], v[92:95]
	v_mfma_f32_16x16x32_bf16 v[84:87], v[156:159], v[212:215], v[84:87]
	v_mfma_f32_16x16x32_bf16 v[76:79], v[164:167], v[212:215], v[76:79]
	v_mfma_f32_16x16x32_bf16 v[112:115], v[168:171], v[184:187], v[112:115]
	v_mfma_f32_16x16x32_bf16 v[104:107], v[176:179], v[184:187], v[104:107]
	v_mfma_f32_16x16x32_bf16 v[96:99], v[168:171], v[192:195], v[96:99]
	v_mfma_f32_16x16x32_bf16 v[88:91], v[176:179], v[192:195], v[88:91]
	v_mfma_f32_16x16x32_bf16 v[80:83], v[168:171], v[200:203], v[80:83]
	v_mfma_f32_16x16x32_bf16 v[72:75], v[176:179], v[200:203], v[72:75]
	v_mfma_f32_16x16x32_bf16 v[68:71], v[168:171], v[208:211], v[68:71]
	v_mfma_f32_16x16x32_bf16 v[64:67], v[176:179], v[208:211], v[64:67]
	v_mfma_f32_16x16x32_bf16 v[112:115], v[172:175], v[188:191], v[112:115]
	v_mfma_f32_16x16x32_bf16 v[104:107], v[180:183], v[188:191], v[104:107]
	v_mfma_f32_16x16x32_bf16 v[96:99], v[172:175], v[196:199], v[96:99]
	v_mfma_f32_16x16x32_bf16 v[88:91], v[180:183], v[196:199], v[88:91]
	v_mfma_f32_16x16x32_bf16 v[80:83], v[172:175], v[204:207], v[80:83]
	v_mfma_f32_16x16x32_bf16 v[72:75], v[180:183], v[204:207], v[72:75]
	v_mfma_f32_16x16x32_bf16 v[68:71], v[172:175], v[212:215], v[68:71]
	v_mfma_f32_16x16x32_bf16 v[64:67], v[180:183], v[212:215], v[64:67]
	s_barrier
	ds_read_b128 v[184:187], v151 offset:49152
	ds_read_b128 v[188:191], v151 offset:50176
	s_add_i32 s28, s58, s31
	v_lshl_add_u64 v[146:147], v[146:147], 0, s[10:11]
	s_mov_b32 m0, s28
	s_nop 0
	global_load_lds_dwordx4 v[146:147], off
	ds_read_b128 v[192:195], v151 offset:51200
	ds_read_b128 v[196:199], v151 offset:52224
	s_add_i32 m0, s28, 0x2000
	s_add_u32 s26, s26, 0x100080
	v_lshl_add_u64 v[146:147], v[216:217], 0, s[10:11]
	s_addc_u32 s27, s27, 0
	s_add_i32 s28, s59, s31
	global_load_lds_dwordx4 v[146:147], off
	ds_read_b128 v[200:203], v151 offset:53248
	v_lshl_add_u64 v[146:147], s[26:27], 0, v[130:131]
	s_mov_b32 m0, s28
	s_nop 0
	global_load_lds_dwordx4 v[146:147], off
	ds_read_b128 v[204:207], v151 offset:54272
	v_lshl_add_u64 v[146:147], s[26:27], 0, v[134:135]
	s_add_i32 m0, s28, 0x2000
	s_nop 0
	global_load_lds_dwordx4 v[146:147], off
	ds_read_b128 v[208:211], v151 offset:55296
	v_lshl_add_u64 v[146:147], v[218:219], 0, s[10:11]
	s_mov_b32 m0, s41
	s_nop 0
	global_load_lds_dwordx4 v[146:147], off
	ds_read_b128 v[212:215], v151 offset:56320
	v_lshl_add_u64 v[146:147], v[220:221], 0, s[10:11]
	s_mov_b32 m0, s42
	s_nop 0
	global_load_lds_dwordx4 v[146:147], off
	s_waitcnt vmcnt(8)
	s_waitcnt lgkmcnt(0)
	s_barrier
	s_waitcnt lgkmcnt(0)
	v_mfma_f32_16x16x32_bf16 v[60:63], v[152:155], v[184:187], v[60:63]
	v_mfma_f32_16x16x32_bf16 v[56:59], v[160:163], v[184:187], v[56:59]
	v_mfma_f32_16x16x32_bf16 v[52:55], v[152:155], v[192:195], v[52:55]
	v_mfma_f32_16x16x32_bf16 v[44:47], v[160:163], v[192:195], v[44:47]
	v_mfma_f32_16x16x32_bf16 v[36:39], v[152:155], v[200:203], v[36:39]
	v_mfma_f32_16x16x32_bf16 v[28:31], v[160:163], v[200:203], v[28:31]
	v_mfma_f32_16x16x32_bf16 v[20:23], v[152:155], v[208:211], v[20:23]
	v_mfma_f32_16x16x32_bf16 v[12:15], v[160:163], v[208:211], v[12:15]
	v_mfma_f32_16x16x32_bf16 v[60:63], v[156:159], v[188:191], v[60:63]
	v_mfma_f32_16x16x32_bf16 v[56:59], v[164:167], v[188:191], v[56:59]
	v_mfma_f32_16x16x32_bf16 v[52:55], v[156:159], v[196:199], v[52:55]
	v_mfma_f32_16x16x32_bf16 v[44:47], v[164:167], v[196:199], v[44:47]
	v_mfma_f32_16x16x32_bf16 v[36:39], v[156:159], v[204:207], v[36:39]
	v_mfma_f32_16x16x32_bf16 v[28:31], v[164:167], v[204:207], v[28:31]
	v_mfma_f32_16x16x32_bf16 v[20:23], v[156:159], v[212:215], v[20:23]
	v_mfma_f32_16x16x32_bf16 v[12:15], v[164:167], v[212:215], v[12:15]
	v_mfma_f32_16x16x32_bf16 v[48:51], v[168:171], v[184:187], v[48:51]
	v_mfma_f32_16x16x32_bf16 v[40:43], v[176:179], v[184:187], v[40:43]
	v_mfma_f32_16x16x32_bf16 v[32:35], v[168:171], v[192:195], v[32:35]
	v_mfma_f32_16x16x32_bf16 v[24:27], v[176:179], v[192:195], v[24:27]
	v_mfma_f32_16x16x32_bf16 v[16:19], v[168:171], v[200:203], v[16:19]
	v_mfma_f32_16x16x32_bf16 v[8:11], v[176:179], v[200:203], v[8:11]
	v_mfma_f32_16x16x32_bf16 v[4:7], v[168:171], v[208:211], v[4:7]
	v_mfma_f32_16x16x32_bf16 v[0:3], v[176:179], v[208:211], v[0:3]
	v_mfma_f32_16x16x32_bf16 v[48:51], v[172:175], v[188:191], v[48:51]
	v_mfma_f32_16x16x32_bf16 v[40:43], v[180:183], v[188:191], v[40:43]
	v_mfma_f32_16x16x32_bf16 v[32:35], v[172:175], v[196:199], v[32:35]
	v_mfma_f32_16x16x32_bf16 v[24:27], v[180:183], v[196:199], v[24:27]
	v_mfma_f32_16x16x32_bf16 v[16:19], v[172:175], v[204:207], v[16:19]
	v_mfma_f32_16x16x32_bf16 v[8:11], v[180:183], v[204:207], v[8:11]
	v_mfma_f32_16x16x32_bf16 v[4:7], v[172:175], v[212:215], v[4:7]
	v_mfma_f32_16x16x32_bf16 v[0:3], v[180:183], v[212:215], v[0:3]
	s_barrier
	s_add_i32 s57, s57, 2
	s_add_u32 s55, s55, 0x100
	s_addc_u32 s56, s56, 0
	s_add_u32 s24, s24, 0x100
	s_addc_u32 s25, s25, 0
	s_cmp_lt_u32 s57, 62
.LBB13_20:
	ds_read_b128 v[152:155], v149
	ds_read_b128 v[156:159], v149 offset:1024
	ds_read_b128 v[160:163], v149 offset:2048
	ds_read_b128 v[164:167], v149 offset:3072
	ds_read_b128 v[168:171], v150
	ds_read_b128 v[172:175], v150 offset:1024
	ds_read_b128 v[176:179], v150 offset:2048
	ds_read_b128 v[180:183], v150 offset:3072
	s_add_u32 s26, s24, 0xfff00080
	s_addc_u32 s27, s25, -1
	s_cmp_eq_u32 s57, 60
	s_cselect_b32 s29, s17, s27
	s_cselect_b32 s28, s53, s26
	s_cselect_b32 s27, s15, s56
	s_cselect_b32 s26, s54, s55
	v_lshl_add_u64 v[146:147], s[24:25], 0, v[140:141]
	s_add_i32 m0, s35, 0xc000
	s_nop 0
	global_load_lds_dwordx4 v[146:147], off
	ds_read_b128 v[184:187], v151
	ds_read_b128 v[188:191], v151 offset:1024
	ds_read_b128 v[192:195], v151 offset:2048
	ds_read_b128 v[196:199], v151 offset:3072
	ds_read_b128 v[200:203], v151 offset:4096
	ds_read_b128 v[204:207], v151 offset:5120
	ds_read_b128 v[208:211], v151 offset:6144
	ds_read_b128 v[212:215], v151 offset:7168
	v_lshl_add_u64 v[146:147], s[24:25], 0, v[138:139]
	s_add_i32 m0, s35, 0xe000
	s_nop 0
	global_load_lds_dwordx4 v[146:147], off
	s_waitcnt vmcnt(8)
	s_waitcnt lgkmcnt(0)
	s_barrier
	s_waitcnt lgkmcnt(0)
	v_mfma_f32_16x16x32_bf16 v[124:127], v[152:155], v[184:187], v[124:127]
	v_mfma_f32_16x16x32_bf16 v[120:123], v[160:163], v[184:187], v[120:123]
	v_mfma_f32_16x16x32_bf16 v[116:119], v[152:155], v[192:195], v[116:119]
	v_mfma_f32_16x16x32_bf16 v[108:111], v[160:163], v[192:195], v[108:111]
	v_mfma_f32_16x16x32_bf16 v[100:103], v[152:155], v[200:203], v[100:103]
	v_mfma_f32_16x16x32_bf16 v[92:95], v[160:163], v[200:203], v[92:95]
	v_mfma_f32_16x16x32_bf16 v[84:87], v[152:155], v[208:211], v[84:87]
	v_mfma_f32_16x16x32_bf16 v[76:79], v[160:163], v[208:211], v[76:79]
	v_mfma_f32_16x16x32_bf16 v[124:127], v[156:159], v[188:191], v[124:127]
	v_mfma_f32_16x16x32_bf16 v[120:123], v[164:167], v[188:191], v[120:123]
	v_mfma_f32_16x16x32_bf16 v[116:119], v[156:159], v[196:199], v[116:119]
	v_mfma_f32_16x16x32_bf16 v[108:111], v[164:167], v[196:199], v[108:111]
	v_mfma_f32_16x16x32_bf16 v[100:103], v[156:159], v[204:207], v[100:103]
	v_mfma_f32_16x16x32_bf16 v[92:95], v[164:167], v[204:207], v[92:95]
	v_mfma_f32_16x16x32_bf16 v[84:87], v[156:159], v[212:215], v[84:87]
	v_mfma_f32_16x16x32_bf16 v[76:79], v[164:167], v[212:215], v[76:79]
	v_mfma_f32_16x16x32_bf16 v[112:115], v[168:171], v[184:187], v[112:115]
	v_mfma_f32_16x16x32_bf16 v[104:107], v[176:179], v[184:187], v[104:107]
	v_mfma_f32_16x16x32_bf16 v[96:99], v[168:171], v[192:195], v[96:99]
	v_mfma_f32_16x16x32_bf16 v[88:91], v[176:179], v[192:195], v[88:91]
	v_mfma_f32_16x16x32_bf16 v[80:83], v[168:171], v[200:203], v[80:83]
	v_mfma_f32_16x16x32_bf16 v[72:75], v[176:179], v[200:203], v[72:75]
	v_mfma_f32_16x16x32_bf16 v[68:71], v[168:171], v[208:211], v[68:71]
	v_mfma_f32_16x16x32_bf16 v[64:67], v[176:179], v[208:211], v[64:67]
	v_mfma_f32_16x16x32_bf16 v[112:115], v[172:175], v[188:191], v[112:115]
	v_mfma_f32_16x16x32_bf16 v[104:107], v[180:183], v[188:191], v[104:107]
	v_mfma_f32_16x16x32_bf16 v[96:99], v[172:175], v[196:199], v[96:99]
	v_mfma_f32_16x16x32_bf16 v[88:91], v[180:183], v[196:199], v[88:91]
	v_mfma_f32_16x16x32_bf16 v[80:83], v[172:175], v[204:207], v[80:83]
	v_mfma_f32_16x16x32_bf16 v[72:75], v[180:183], v[204:207], v[72:75]
	v_mfma_f32_16x16x32_bf16 v[68:71], v[172:175], v[212:215], v[68:71]
	v_mfma_f32_16x16x32_bf16 v[64:67], v[180:183], v[212:215], v[64:67]
	s_barrier
	ds_read_b128 v[184:187], v151 offset:16384
	ds_read_b128 v[188:191], v151 offset:17408
	s_add_i32 s58, s46, s31
	v_lshl_add_u64 v[146:147], s[26:27], 0, v[130:131]
	s_mov_b32 m0, s58
	s_nop 0
	global_load_lds_dwordx4 v[146:147], off
	ds_read_b128 v[192:195], v151 offset:18432
	ds_read_b128 v[196:199], v151 offset:19456
	s_add_i32 m0, s58, 0x2000
	s_add_u32 s58, s26, 0x100000
	v_lshl_add_u64 v[216:217], s[26:27], 0, v[134:135]
	s_addc_u32 s59, s27, 0
	s_add_i32 s60, s47, s31
	global_load_lds_dwordx4 v[216:217], off
	ds_read_b128 v[200:203], v151 offset:20480
	v_lshl_add_u64 v[218:219], s[58:59], 0, v[130:131]
	s_mov_b32 m0, s60
	v_lshl_add_u64 v[220:221], s[28:29], 0, v[132:133]
	global_load_lds_dwordx4 v[218:219], off
	ds_read_b128 v[204:207], v151 offset:21504
	v_lshl_add_u64 v[218:219], s[58:59], 0, v[134:135]
	s_add_i32 m0, s60, 0x2000
	s_nop 0
	global_load_lds_dwordx4 v[218:219], off
	ds_read_b128 v[208:211], v151 offset:22528
	v_lshl_add_u64 v[218:219], s[28:29], 0, v[128:129]
	s_mov_b32 m0, s35
	s_nop 0
	global_load_lds_dwordx4 v[218:219], off
	ds_read_b128 v[212:215], v151 offset:23552
	s_mov_b32 m0, s36
	s_nop 0
	global_load_lds_dwordx4 v[220:221], off
	s_waitcnt vmcnt(8)
	s_waitcnt lgkmcnt(0)
	s_barrier
	s_waitcnt lgkmcnt(0)
	v_mfma_f32_16x16x32_bf16 v[60:63], v[152:155], v[184:187], v[60:63]
	v_mfma_f32_16x16x32_bf16 v[56:59], v[160:163], v[184:187], v[56:59]
	v_mfma_f32_16x16x32_bf16 v[52:55], v[152:155], v[192:195], v[52:55]
	v_mfma_f32_16x16x32_bf16 v[44:47], v[160:163], v[192:195], v[44:47]
	v_mfma_f32_16x16x32_bf16 v[36:39], v[152:155], v[200:203], v[36:39]
	v_mfma_f32_16x16x32_bf16 v[28:31], v[160:163], v[200:203], v[28:31]
	v_mfma_f32_16x16x32_bf16 v[20:23], v[152:155], v[208:211], v[20:23]
	v_mfma_f32_16x16x32_bf16 v[12:15], v[160:163], v[208:211], v[12:15]
	v_mfma_f32_16x16x32_bf16 v[60:63], v[156:159], v[188:191], v[60:63]
	v_mfma_f32_16x16x32_bf16 v[56:59], v[164:167], v[188:191], v[56:59]
	v_mfma_f32_16x16x32_bf16 v[52:55], v[156:159], v[196:199], v[52:55]
	v_mfma_f32_16x16x32_bf16 v[44:47], v[164:167], v[196:199], v[44:47]
	v_mfma_f32_16x16x32_bf16 v[36:39], v[156:159], v[204:207], v[36:39]
	v_mfma_f32_16x16x32_bf16 v[28:31], v[164:167], v[204:207], v[28:31]
	v_mfma_f32_16x16x32_bf16 v[20:23], v[156:159], v[212:215], v[20:23]
	v_mfma_f32_16x16x32_bf16 v[12:15], v[164:167], v[212:215], v[12:15]
	v_mfma_f32_16x16x32_bf16 v[48:51], v[168:171], v[184:187], v[48:51]
	v_mfma_f32_16x16x32_bf16 v[40:43], v[176:179], v[184:187], v[40:43]
	v_mfma_f32_16x16x32_bf16 v[32:35], v[168:171], v[192:195], v[32:35]
	v_mfma_f32_16x16x32_bf16 v[24:27], v[176:179], v[192:195], v[24:27]
	v_mfma_f32_16x16x32_bf16 v[16:19], v[168:171], v[200:203], v[16:19]
	v_mfma_f32_16x16x32_bf16 v[8:11], v[176:179], v[200:203], v[8:11]
	v_mfma_f32_16x16x32_bf16 v[4:7], v[168:171], v[208:211], v[4:7]
	v_mfma_f32_16x16x32_bf16 v[0:3], v[176:179], v[208:211], v[0:3]
	v_mfma_f32_16x16x32_bf16 v[48:51], v[172:175], v[188:191], v[48:51]
	v_mfma_f32_16x16x32_bf16 v[40:43], v[180:183], v[188:191], v[40:43]
	v_mfma_f32_16x16x32_bf16 v[32:35], v[172:175], v[196:199], v[32:35]
	v_mfma_f32_16x16x32_bf16 v[24:27], v[180:183], v[196:199], v[24:27]
	v_mfma_f32_16x16x32_bf16 v[16:19], v[172:175], v[204:207], v[16:19]
	v_mfma_f32_16x16x32_bf16 v[8:11], v[180:183], v[204:207], v[8:11]
	v_mfma_f32_16x16x32_bf16 v[4:7], v[172:175], v[212:215], v[4:7]
	v_mfma_f32_16x16x32_bf16 v[0:3], v[180:183], v[212:215], v[0:3]
	s_barrier
	s_add_i32 s59, 0, 0x1c000
	s_add_i32 s58, 0, 0x18000
	v_add_u32_e32 v164, s58, v148
	v_add_u32_e32 v180, s59, v148
	ds_read_b128 v[152:155], v164
	ds_read_b128 v[156:159], v164 offset:1024
	ds_read_b128 v[160:163], v164 offset:2048
	ds_read_b128 v[164:167], v164 offset:3072
	ds_read_b128 v[168:171], v180
	ds_read_b128 v[172:175], v180 offset:1024
	ds_read_b128 v[176:179], v180 offset:2048
	ds_read_b128 v[180:183], v180 offset:3072
	s_add_u32 s28, s28, 0x100000
	s_addc_u32 s29, s29, 0
	s_mov_b32 m0, s37
	v_lshl_add_u64 v[222:223], s[28:29], 0, v[128:129]
	global_load_lds_dwordx4 v[222:223], off
	ds_read_b128 v[184:187], v151 offset:32768
	ds_read_b128 v[188:191], v151 offset:33792
	ds_read_b128 v[192:195], v151 offset:34816
	ds_read_b128 v[196:199], v151 offset:35840
	ds_read_b128 v[200:203], v151 offset:36864
	ds_read_b128 v[204:207], v151 offset:37888
	ds_read_b128 v[208:211], v151 offset:38912
	ds_read_b128 v[212:215], v151 offset:39936
	v_lshl_add_u64 v[222:223], s[28:29], 0, v[132:133]
	s_mov_b32 m0, s38
	s_nop 0
	global_load_lds_dwordx4 v[222:223], off
	s_waitcnt vmcnt(8)
	s_waitcnt lgkmcnt(0)
	s_barrier
	s_waitcnt lgkmcnt(0)
	v_mfma_f32_16x16x32_bf16 v[124:127], v[152:155], v[184:187], v[124:127]
	v_mfma_f32_16x16x32_bf16 v[120:123], v[160:163], v[184:187], v[120:123]
	v_mfma_f32_16x16x32_bf16 v[116:119], v[152:155], v[192:195], v[116:119]
	v_mfma_f32_16x16x32_bf16 v[108:111], v[160:163], v[192:195], v[108:111]
	v_mfma_f32_16x16x32_bf16 v[100:103], v[152:155], v[200:203], v[100:103]
	v_mfma_f32_16x16x32_bf16 v[92:95], v[160:163], v[200:203], v[92:95]
	v_mfma_f32_16x16x32_bf16 v[84:87], v[152:155], v[208:211], v[84:87]
	v_mfma_f32_16x16x32_bf16 v[76:79], v[160:163], v[208:211], v[76:79]
	v_mfma_f32_16x16x32_bf16 v[124:127], v[156:159], v[188:191], v[124:127]
	v_mfma_f32_16x16x32_bf16 v[120:123], v[164:167], v[188:191], v[120:123]
	v_mfma_f32_16x16x32_bf16 v[116:119], v[156:159], v[196:199], v[116:119]
	v_mfma_f32_16x16x32_bf16 v[108:111], v[164:167], v[196:199], v[108:111]
	v_mfma_f32_16x16x32_bf16 v[100:103], v[156:159], v[204:207], v[100:103]
	v_mfma_f32_16x16x32_bf16 v[92:95], v[164:167], v[204:207], v[92:95]
	v_mfma_f32_16x16x32_bf16 v[84:87], v[156:159], v[212:215], v[84:87]
	v_mfma_f32_16x16x32_bf16 v[76:79], v[164:167], v[212:215], v[76:79]
	v_mfma_f32_16x16x32_bf16 v[112:115], v[168:171], v[184:187], v[112:115]
	v_mfma_f32_16x16x32_bf16 v[104:107], v[176:179], v[184:187], v[104:107]
	v_mfma_f32_16x16x32_bf16 v[96:99], v[168:171], v[192:195], v[96:99]
	v_mfma_f32_16x16x32_bf16 v[88:91], v[176:179], v[192:195], v[88:91]
	v_mfma_f32_16x16x32_bf16 v[80:83], v[168:171], v[200:203], v[80:83]
	v_mfma_f32_16x16x32_bf16 v[72:75], v[176:179], v[200:203], v[72:75]
	v_mfma_f32_16x16x32_bf16 v[68:71], v[168:171], v[208:211], v[68:71]
	v_mfma_f32_16x16x32_bf16 v[64:67], v[176:179], v[208:211], v[64:67]
	v_mfma_f32_16x16x32_bf16 v[112:115], v[172:175], v[188:191], v[112:115]
	v_mfma_f32_16x16x32_bf16 v[104:107], v[180:183], v[188:191], v[104:107]
	v_mfma_f32_16x16x32_bf16 v[96:99], v[172:175], v[196:199], v[96:99]
	v_mfma_f32_16x16x32_bf16 v[88:91], v[180:183], v[196:199], v[88:91]
	v_mfma_f32_16x16x32_bf16 v[80:83], v[172:175], v[204:207], v[80:83]
	v_mfma_f32_16x16x32_bf16 v[72:75], v[180:183], v[204:207], v[72:75]
	v_mfma_f32_16x16x32_bf16 v[68:71], v[172:175], v[212:215], v[68:71]
	v_mfma_f32_16x16x32_bf16 v[64:67], v[180:183], v[212:215], v[64:67]
	s_barrier
	ds_read_b128 v[184:187], v151 offset:49152
	ds_read_b128 v[188:191], v151 offset:50176
	s_add_i32 s28, s58, s31
	v_lshl_add_u64 v[146:147], v[146:147], 0, s[10:11]
	s_mov_b32 m0, s28
	s_nop 0
	global_load_lds_dwordx4 v[146:147], off
	ds_read_b128 v[192:195], v151 offset:51200
	ds_read_b128 v[196:199], v151 offset:52224
	s_add_i32 m0, s28, 0x2000
	s_add_u32 s26, s26, 0x100080
	v_lshl_add_u64 v[146:147], v[216:217], 0, s[10:11]
	s_addc_u32 s27, s27, 0
	s_add_i32 s28, s59, s31
	global_load_lds_dwordx4 v[146:147], off
	ds_read_b128 v[200:203], v151 offset:53248
	v_lshl_add_u64 v[146:147], s[26:27], 0, v[130:131]
	s_mov_b32 m0, s28
	s_nop 0
	global_load_lds_dwordx4 v[146:147], off
	ds_read_b128 v[204:207], v151 offset:54272
	v_lshl_add_u64 v[146:147], s[26:27], 0, v[134:135]
	s_add_i32 m0, s28, 0x2000
	s_nop 0
	global_load_lds_dwordx4 v[146:147], off
	ds_read_b128 v[208:211], v151 offset:55296
	v_lshl_add_u64 v[146:147], v[218:219], 0, s[10:11]
	s_mov_b32 m0, s41
	s_nop 0
	global_load_lds_dwordx4 v[146:147], off
	ds_read_b128 v[212:215], v151 offset:56320
	v_lshl_add_u64 v[146:147], v[220:221], 0, s[10:11]
	s_mov_b32 m0, s42
	s_nop 0
	global_load_lds_dwordx4 v[146:147], off
	s_waitcnt vmcnt(8)
	s_waitcnt lgkmcnt(0)
	s_barrier
	s_waitcnt lgkmcnt(0)
	v_mfma_f32_16x16x32_bf16 v[60:63], v[152:155], v[184:187], v[60:63]
	v_mfma_f32_16x16x32_bf16 v[56:59], v[160:163], v[184:187], v[56:59]
	v_mfma_f32_16x16x32_bf16 v[52:55], v[152:155], v[192:195], v[52:55]
	v_mfma_f32_16x16x32_bf16 v[44:47], v[160:163], v[192:195], v[44:47]
	v_mfma_f32_16x16x32_bf16 v[36:39], v[152:155], v[200:203], v[36:39]
	v_mfma_f32_16x16x32_bf16 v[28:31], v[160:163], v[200:203], v[28:31]
	v_mfma_f32_16x16x32_bf16 v[20:23], v[152:155], v[208:211], v[20:23]
	v_mfma_f32_16x16x32_bf16 v[12:15], v[160:163], v[208:211], v[12:15]
	v_mfma_f32_16x16x32_bf16 v[60:63], v[156:159], v[188:191], v[60:63]
	v_mfma_f32_16x16x32_bf16 v[56:59], v[164:167], v[188:191], v[56:59]
	v_mfma_f32_16x16x32_bf16 v[52:55], v[156:159], v[196:199], v[52:55]
	v_mfma_f32_16x16x32_bf16 v[44:47], v[164:167], v[196:199], v[44:47]
	v_mfma_f32_16x16x32_bf16 v[36:39], v[156:159], v[204:207], v[36:39]
	v_mfma_f32_16x16x32_bf16 v[28:31], v[164:167], v[204:207], v[28:31]
	v_mfma_f32_16x16x32_bf16 v[20:23], v[156:159], v[212:215], v[20:23]
	v_mfma_f32_16x16x32_bf16 v[12:15], v[164:167], v[212:215], v[12:15]
	v_mfma_f32_16x16x32_bf16 v[48:51], v[168:171], v[184:187], v[48:51]
	v_mfma_f32_16x16x32_bf16 v[40:43], v[176:179], v[184:187], v[40:43]
	v_mfma_f32_16x16x32_bf16 v[32:35], v[168:171], v[192:195], v[32:35]
	v_mfma_f32_16x16x32_bf16 v[24:27], v[176:179], v[192:195], v[24:27]
	v_mfma_f32_16x16x32_bf16 v[16:19], v[168:171], v[200:203], v[16:19]
	v_mfma_f32_16x16x32_bf16 v[8:11], v[176:179], v[200:203], v[8:11]
	v_mfma_f32_16x16x32_bf16 v[4:7], v[168:171], v[208:211], v[4:7]
	v_mfma_f32_16x16x32_bf16 v[0:3], v[176:179], v[208:211], v[0:3]
	v_mfma_f32_16x16x32_bf16 v[48:51], v[172:175], v[188:191], v[48:51]
	v_mfma_f32_16x16x32_bf16 v[40:43], v[180:183], v[188:191], v[40:43]
	v_mfma_f32_16x16x32_bf16 v[32:35], v[172:175], v[196:199], v[32:35]
	v_mfma_f32_16x16x32_bf16 v[24:27], v[180:183], v[196:199], v[24:27]
	v_mfma_f32_16x16x32_bf16 v[16:19], v[172:175], v[204:207], v[16:19]
	v_mfma_f32_16x16x32_bf16 v[8:11], v[180:183], v[204:207], v[8:11]
	v_mfma_f32_16x16x32_bf16 v[4:7], v[172:175], v[212:215], v[4:7]
	v_mfma_f32_16x16x32_bf16 v[0:3], v[180:183], v[212:215], v[0:3]
	s_barrier
	s_add_i32 s57, s57, 2
	s_add_u32 s55, s55, 0x100
	s_addc_u32 s56, s56, 0
	s_add_u32 s24, s24, 0x100
	s_addc_u32 s25, s25, 0
	s_cmp_lt_u32 s57, 62
	s_cbranch_scc1 .LBB13_20
	s_andn2_b64 vcc, exec, s[12:13]
	s_cbranch_vccnz .LBB13_23
	s_barrier
